# GEMM mainloops: one static s_setprio 1 for the younger wave half at phase entry, per-segment toggles removed (strategy 4)
# speedup vs baseline: 1.0018x; 1.0018x over previous
.Lpost_getpc1:
	s_add_u32 s98, s98, (.LBB0_1550-.Lpost_getpc1)&4294967295
	s_addc_u32 s99, s99, (.LBB0_1550-.Lpost_getpc1)>>32
	s_setpc_b64 s[98:99]
	s_nop 0
	s_nop 0
	s_nop 0
	s_nop 0
	s_nop 0
	s_nop 0
	s_nop 0
	s_nop 0
	s_nop 0
	s_nop 0
	s_nop 0
	s_nop 0
.LBB0_14:
	v_readfirstlane_b32 s0, v0
	s_bitcmp1_b32 s0, 8
	s_cbranch_scc0 .Lhalf_skip
	s_setprio 1

.LBB0_212:
	s_add_u32 s46, s44, 0xfff80080
	s_addc_u32 s47, s45, -1
	s_add_i32 s74, 0, 0x10000
	s_cmp_eq_u32 s63, 28
	s_cselect_b32 s57, s13, s47
	s_cselect_b32 s56, s49, s46
	v_add_u32_e32 v2, s74, v167
	s_cselect_b32 s47, s39, s62
	s_cselect_b32 s46, s58, s59
	s_add_i32 s76, 0, 0x14000
	ds_read_b128 v[132:135], v2
	ds_read_b128 v[136:139], v2 offset:1024
	ds_read_b128 v[140:143], v2 offset:2048
	ds_read_b128 v[144:147], v2 offset:3072
	v_add_u32_e32 v2, s76, v167
	ds_read_b128 v[160:163], v2
	ds_read_b128 v[170:173], v2 offset:1024
	ds_read_b128 v[174:177], v2 offset:2048
	ds_read_b128 v[178:181], v2 offset:3072
	v_lshl_add_u64 v[164:165], s[44:45], 0, v[156:157]
	s_add_i32 m0, s15, 0xc000
	ds_read_b128 v[182:185], v168
	ds_read_b128 v[186:189], v168 offset:1024
	ds_read_b128 v[190:193], v168 offset:2048
	ds_read_b128 v[194:197], v168 offset:3072
	ds_read_b128 v[212:215], v168 offset:4096
	ds_read_b128 v[216:219], v168 offset:5120
	ds_read_b128 v[220:223], v168 offset:6144
	ds_read_b128 v[224:227], v168 offset:7168
	global_load_lds_dwordx4 v[164:165], off
	v_lshl_add_u64 v[164:165], s[44:45], 0, v[158:159]
	s_add_i32 m0, s15, 0xe000
	s_nop 0
	global_load_lds_dwordx4 v[164:165], off
	s_waitcnt vmcnt(8)
	s_waitcnt lgkmcnt(0)
	s_barrier
	s_nop 0
	s_waitcnt lgkmcnt(0)
	v_mfma_f32_16x16x32_bf16 v[128:131], v[132:135], v[182:185], v[128:131]
	v_mfma_f32_16x16x32_bf16 v[124:127], v[140:143], v[182:185], v[124:127]
	v_mfma_f32_16x16x32_bf16 v[120:123], v[132:135], v[190:193], v[120:123]
	v_mfma_f32_16x16x32_bf16 v[116:119], v[140:143], v[190:193], v[116:119]
	v_mfma_f32_16x16x32_bf16 v[108:111], v[132:135], v[212:215], v[108:111]
	v_mfma_f32_16x16x32_bf16 v[100:103], v[140:143], v[212:215], v[100:103]
	v_mfma_f32_16x16x32_bf16 v[92:95], v[132:135], v[220:223], v[92:95]
	v_mfma_f32_16x16x32_bf16 v[84:87], v[140:143], v[220:223], v[84:87]
	v_mfma_f32_16x16x32_bf16 v[128:131], v[136:139], v[186:189], v[128:131]
	v_mfma_f32_16x16x32_bf16 v[124:127], v[144:147], v[186:189], v[124:127]
	v_mfma_f32_16x16x32_bf16 v[120:123], v[136:139], v[194:197], v[120:123]
	v_mfma_f32_16x16x32_bf16 v[116:119], v[144:147], v[194:197], v[116:119]
	v_mfma_f32_16x16x32_bf16 v[108:111], v[136:139], v[216:219], v[108:111]
	v_mfma_f32_16x16x32_bf16 v[100:103], v[144:147], v[216:219], v[100:103]
	v_mfma_f32_16x16x32_bf16 v[92:95], v[136:139], v[224:227], v[92:95]
	v_mfma_f32_16x16x32_bf16 v[84:87], v[144:147], v[224:227], v[84:87]
	s_nop 0
	s_nop 0
	v_mfma_f32_16x16x32_bf16 v[112:115], v[160:163], v[182:185], v[112:115]
	v_mfma_f32_16x16x32_bf16 v[104:107], v[174:177], v[182:185], v[104:107]
	v_mfma_f32_16x16x32_bf16 v[96:99], v[160:163], v[190:193], v[96:99]
	v_mfma_f32_16x16x32_bf16 v[88:91], v[174:177], v[190:193], v[88:91]
	v_mfma_f32_16x16x32_bf16 v[80:83], v[160:163], v[212:215], v[80:83]
	v_mfma_f32_16x16x32_bf16 v[76:79], v[174:177], v[212:215], v[76:79]
	v_mfma_f32_16x16x32_bf16 v[72:75], v[160:163], v[220:223], v[72:75]
	v_mfma_f32_16x16x32_bf16 v[68:71], v[174:177], v[220:223], v[68:71]
	v_mfma_f32_16x16x32_bf16 v[112:115], v[170:173], v[186:189], v[112:115]
	v_mfma_f32_16x16x32_bf16 v[104:107], v[178:181], v[186:189], v[104:107]
	v_mfma_f32_16x16x32_bf16 v[96:99], v[170:173], v[194:197], v[96:99]
	v_mfma_f32_16x16x32_bf16 v[88:91], v[178:181], v[194:197], v[88:91]
	v_mfma_f32_16x16x32_bf16 v[80:83], v[170:173], v[216:219], v[80:83]
	v_mfma_f32_16x16x32_bf16 v[76:79], v[178:181], v[216:219], v[76:79]
	v_mfma_f32_16x16x32_bf16 v[72:75], v[170:173], v[224:227], v[72:75]
	v_mfma_f32_16x16x32_bf16 v[68:71], v[178:181], v[224:227], v[68:71]
	s_nop 0
	s_barrier
	s_add_i32 s74, s74, s40
	v_lshl_add_u64 v[164:165], s[46:47], 0, v[150:151]
	s_mov_b32 m0, s74
	ds_read_b128 v[182:185], v168 offset:16384
	ds_read_b128 v[186:189], v168 offset:17408
	ds_read_b128 v[190:193], v168 offset:18432
	ds_read_b128 v[194:197], v168 offset:19456
	ds_read_b128 v[212:215], v168 offset:20480
	ds_read_b128 v[216:219], v168 offset:21504
	ds_read_b128 v[220:223], v168 offset:22528
	ds_read_b128 v[224:227], v168 offset:23552
	global_load_lds_dwordx4 v[164:165], off
	s_add_i32 m0, s74, 0x2000
	s_add_u32 s74, s46, 0x80000
	v_lshl_add_u64 v[198:199], s[46:47], 0, v[154:155]
	s_addc_u32 s75, s47, 0
	s_add_i32 s76, s76, s40
	global_load_lds_dwordx4 v[198:199], off
	v_lshl_add_u64 v[204:205], s[74:75], 0, v[150:151]
	s_mov_b32 m0, s76
	v_lshl_add_u64 v[206:207], s[56:57], 0, v[152:153]
	global_load_lds_dwordx4 v[204:205], off
	v_lshl_add_u64 v[204:205], s[74:75], 0, v[154:155]
	s_add_i32 m0, s76, 0x2000
	s_nop 0
	global_load_lds_dwordx4 v[204:205], off
	v_lshl_add_u64 v[204:205], s[56:57], 0, v[148:149]
	s_mov_b32 m0, s15
	s_nop 0
	global_load_lds_dwordx4 v[204:205], off
	s_mov_b32 m0, s41
	s_nop 0
	global_load_lds_dwordx4 v[206:207], off
	s_waitcnt vmcnt(8)
	s_waitcnt lgkmcnt(0)
	s_barrier
	s_nop 0
	s_waitcnt lgkmcnt(0)
	v_mfma_f32_16x16x32_bf16 v[64:67], v[132:135], v[182:185], v[64:67]
	v_mfma_f32_16x16x32_bf16 v[60:63], v[140:143], v[182:185], v[60:63]
	v_mfma_f32_16x16x32_bf16 v[56:59], v[132:135], v[190:193], v[56:59]
	v_mfma_f32_16x16x32_bf16 v[52:55], v[140:143], v[190:193], v[52:55]
	v_mfma_f32_16x16x32_bf16 v[44:47], v[132:135], v[212:215], v[44:47]
	v_mfma_f32_16x16x32_bf16 v[36:39], v[140:143], v[212:215], v[36:39]
	v_mfma_f32_16x16x32_bf16 v[28:31], v[132:135], v[220:223], v[28:31]
	v_mfma_f32_16x16x32_bf16 v[20:23], v[140:143], v[220:223], v[20:23]
	v_mfma_f32_16x16x32_bf16 v[64:67], v[136:139], v[186:189], v[64:67]
	v_mfma_f32_16x16x32_bf16 v[60:63], v[144:147], v[186:189], v[60:63]
	v_mfma_f32_16x16x32_bf16 v[56:59], v[136:139], v[194:197], v[56:59]
	v_mfma_f32_16x16x32_bf16 v[52:55], v[144:147], v[194:197], v[52:55]
	v_mfma_f32_16x16x32_bf16 v[44:47], v[136:139], v[216:219], v[44:47]
	v_mfma_f32_16x16x32_bf16 v[36:39], v[144:147], v[216:219], v[36:39]
	v_mfma_f32_16x16x32_bf16 v[28:31], v[136:139], v[224:227], v[28:31]
	v_mfma_f32_16x16x32_bf16 v[20:23], v[144:147], v[224:227], v[20:23]
	s_nop 0
	s_nop 0
	v_mfma_f32_16x16x32_bf16 v[48:51], v[160:163], v[182:185], v[48:51]
	v_mfma_f32_16x16x32_bf16 v[40:43], v[174:177], v[182:185], v[40:43]
	v_mfma_f32_16x16x32_bf16 v[32:35], v[160:163], v[190:193], v[32:35]
	v_mfma_f32_16x16x32_bf16 v[24:27], v[174:177], v[190:193], v[24:27]
	v_mfma_f32_16x16x32_bf16 v[16:19], v[160:163], v[212:215], v[16:19]
	v_mfma_f32_16x16x32_bf16 v[12:15], v[174:177], v[212:215], v[12:15]
	v_mfma_f32_16x16x32_bf16 v[8:11], v[160:163], v[220:223], v[8:11]
	v_mfma_f32_16x16x32_bf16 v[4:7], v[174:177], v[220:223], v[4:7]
	v_mfma_f32_16x16x32_bf16 v[48:51], v[170:173], v[186:189], v[48:51]
	v_mfma_f32_16x16x32_bf16 v[40:43], v[178:181], v[186:189], v[40:43]
	v_mfma_f32_16x16x32_bf16 v[32:35], v[170:173], v[194:197], v[32:35]
	v_mfma_f32_16x16x32_bf16 v[24:27], v[178:181], v[194:197], v[24:27]
	v_mfma_f32_16x16x32_bf16 v[16:19], v[170:173], v[216:219], v[16:19]
	v_mfma_f32_16x16x32_bf16 v[12:15], v[178:181], v[216:219], v[12:15]
	v_mfma_f32_16x16x32_bf16 v[8:11], v[170:173], v[224:227], v[8:11]
	v_mfma_f32_16x16x32_bf16 v[4:7], v[178:181], v[224:227], v[4:7]
	s_nop 0
	s_barrier
	s_add_i32 s74, 0, 0x18000
	v_add_u32_e32 v2, s74, v167
	s_add_i32 s75, 0, 0x1c000
	ds_read_b128 v[132:135], v2
	ds_read_b128 v[136:139], v2 offset:1024
	ds_read_b128 v[140:143], v2 offset:2048
	ds_read_b128 v[144:147], v2 offset:3072
	v_add_u32_e32 v2, s75, v167
	ds_read_b128 v[160:163], v2
	ds_read_b128 v[170:173], v2 offset:1024
	ds_read_b128 v[174:177], v2 offset:2048
	ds_read_b128 v[178:181], v2 offset:3072
	s_add_u32 s56, s56, 0x80000
	s_addc_u32 s57, s57, 0
	s_mov_b32 m0, s64
	v_lshl_add_u64 v[228:229], s[56:57], 0, v[148:149]
	ds_read_b128 v[182:185], v168 offset:32768
	ds_read_b128 v[186:189], v168 offset:33792
	ds_read_b128 v[190:193], v168 offset:34816
	ds_read_b128 v[194:197], v168 offset:35840
	ds_read_b128 v[212:215], v168 offset:36864
	ds_read_b128 v[216:219], v168 offset:37888
	ds_read_b128 v[220:223], v168 offset:38912
	ds_read_b128 v[224:227], v168 offset:39936
	global_load_lds_dwordx4 v[228:229], off
	v_lshl_add_u64 v[228:229], s[56:57], 0, v[152:153]
	s_mov_b32 m0, s65
	s_nop 0
	global_load_lds_dwordx4 v[228:229], off
	s_waitcnt vmcnt(8)
	s_waitcnt lgkmcnt(0)
	s_barrier
	s_nop 0
	s_waitcnt lgkmcnt(0)
	v_mfma_f32_16x16x32_bf16 v[128:131], v[132:135], v[182:185], v[128:131]
	v_mfma_f32_16x16x32_bf16 v[124:127], v[140:143], v[182:185], v[124:127]
	v_mfma_f32_16x16x32_bf16 v[120:123], v[132:135], v[190:193], v[120:123]
	v_mfma_f32_16x16x32_bf16 v[116:119], v[140:143], v[190:193], v[116:119]
	v_mfma_f32_16x16x32_bf16 v[108:111], v[132:135], v[212:215], v[108:111]
	v_mfma_f32_16x16x32_bf16 v[100:103], v[140:143], v[212:215], v[100:103]
	v_mfma_f32_16x16x32_bf16 v[92:95], v[132:135], v[220:223], v[92:95]
	v_mfma_f32_16x16x32_bf16 v[84:87], v[140:143], v[220:223], v[84:87]
	v_mfma_f32_16x16x32_bf16 v[128:131], v[136:139], v[186:189], v[128:131]
	v_mfma_f32_16x16x32_bf16 v[124:127], v[144:147], v[186:189], v[124:127]
	v_mfma_f32_16x16x32_bf16 v[120:123], v[136:139], v[194:197], v[120:123]
	v_mfma_f32_16x16x32_bf16 v[116:119], v[144:147], v[194:197], v[116:119]
	v_mfma_f32_16x16x32_bf16 v[108:111], v[136:139], v[216:219], v[108:111]
	v_mfma_f32_16x16x32_bf16 v[100:103], v[144:147], v[216:219], v[100:103]
	v_mfma_f32_16x16x32_bf16 v[92:95], v[136:139], v[224:227], v[92:95]
	v_mfma_f32_16x16x32_bf16 v[84:87], v[144:147], v[224:227], v[84:87]
	s_nop 0
	s_nop 0
	v_mfma_f32_16x16x32_bf16 v[112:115], v[160:163], v[182:185], v[112:115]
	v_mfma_f32_16x16x32_bf16 v[104:107], v[174:177], v[182:185], v[104:107]
	v_mfma_f32_16x16x32_bf16 v[96:99], v[160:163], v[190:193], v[96:99]
	v_mfma_f32_16x16x32_bf16 v[88:91], v[174:177], v[190:193], v[88:91]
	v_mfma_f32_16x16x32_bf16 v[80:83], v[160:163], v[212:215], v[80:83]
	v_mfma_f32_16x16x32_bf16 v[76:79], v[174:177], v[212:215], v[76:79]
	v_mfma_f32_16x16x32_bf16 v[72:75], v[160:163], v[220:223], v[72:75]
	v_mfma_f32_16x16x32_bf16 v[68:71], v[174:177], v[220:223], v[68:71]
	v_mfma_f32_16x16x32_bf16 v[112:115], v[170:173], v[186:189], v[112:115]
	v_mfma_f32_16x16x32_bf16 v[104:107], v[178:181], v[186:189], v[104:107]
	v_mfma_f32_16x16x32_bf16 v[96:99], v[170:173], v[194:197], v[96:99]
	v_mfma_f32_16x16x32_bf16 v[88:91], v[178:181], v[194:197], v[88:91]
	v_mfma_f32_16x16x32_bf16 v[80:83], v[170:173], v[216:219], v[80:83]
	v_mfma_f32_16x16x32_bf16 v[76:79], v[178:181], v[216:219], v[76:79]
	v_mfma_f32_16x16x32_bf16 v[72:75], v[170:173], v[224:227], v[72:75]
	v_mfma_f32_16x16x32_bf16 v[68:71], v[178:181], v[224:227], v[68:71]
	s_nop 0
	s_barrier
	s_add_i32 s56, s74, s40
	v_lshl_add_u64 v[164:165], v[164:165], 0, s[94:95]
	s_mov_b32 m0, s56
	ds_read_b128 v[182:185], v168 offset:49152
	ds_read_b128 v[186:189], v168 offset:50176
	ds_read_b128 v[190:193], v168 offset:51200
	ds_read_b128 v[194:197], v168 offset:52224
	ds_read_b128 v[212:215], v168 offset:53248
	ds_read_b128 v[216:219], v168 offset:54272
	ds_read_b128 v[220:223], v168 offset:55296
	ds_read_b128 v[224:227], v168 offset:56320
	global_load_lds_dwordx4 v[164:165], off
	s_add_i32 m0, s56, 0x2000
	s_add_u32 s46, s46, 0x80080
	v_lshl_add_u64 v[164:165], v[198:199], 0, s[94:95]
	s_addc_u32 s47, s47, 0
	s_add_i32 s56, s75, s40
	global_load_lds_dwordx4 v[164:165], off
	v_lshl_add_u64 v[164:165], s[46:47], 0, v[150:151]
	s_mov_b32 m0, s56
	s_nop 0
	global_load_lds_dwordx4 v[164:165], off
	v_lshl_add_u64 v[164:165], s[46:47], 0, v[154:155]
	s_add_i32 m0, s56, 0x2000
	s_nop 0
	global_load_lds_dwordx4 v[164:165], off
	v_lshl_add_u64 v[164:165], v[204:205], 0, s[94:95]
	s_mov_b32 m0, s68
	s_nop 0
	global_load_lds_dwordx4 v[164:165], off
	v_lshl_add_u64 v[164:165], v[206:207], 0, s[94:95]
	s_mov_b32 m0, s69
	s_nop 0
	global_load_lds_dwordx4 v[164:165], off
	s_waitcnt vmcnt(8)
	s_waitcnt lgkmcnt(0)
	s_barrier
	s_nop 0
	s_waitcnt lgkmcnt(0)
	v_mfma_f32_16x16x32_bf16 v[64:67], v[132:135], v[182:185], v[64:67]
	v_mfma_f32_16x16x32_bf16 v[60:63], v[140:143], v[182:185], v[60:63]
	v_mfma_f32_16x16x32_bf16 v[56:59], v[132:135], v[190:193], v[56:59]
	v_mfma_f32_16x16x32_bf16 v[52:55], v[140:143], v[190:193], v[52:55]
	v_mfma_f32_16x16x32_bf16 v[44:47], v[132:135], v[212:215], v[44:47]
	v_mfma_f32_16x16x32_bf16 v[36:39], v[140:143], v[212:215], v[36:39]
	v_mfma_f32_16x16x32_bf16 v[28:31], v[132:135], v[220:223], v[28:31]
	v_mfma_f32_16x16x32_bf16 v[20:23], v[140:143], v[220:223], v[20:23]
	v_mfma_f32_16x16x32_bf16 v[64:67], v[136:139], v[186:189], v[64:67]
	v_mfma_f32_16x16x32_bf16 v[60:63], v[144:147], v[186:189], v[60:63]
	v_mfma_f32_16x16x32_bf16 v[56:59], v[136:139], v[194:197], v[56:59]
	v_mfma_f32_16x16x32_bf16 v[52:55], v[144:147], v[194:197], v[52:55]
	v_mfma_f32_16x16x32_bf16 v[44:47], v[136:139], v[216:219], v[44:47]
	v_mfma_f32_16x16x32_bf16 v[36:39], v[144:147], v[216:219], v[36:39]
	v_mfma_f32_16x16x32_bf16 v[28:31], v[136:139], v[224:227], v[28:31]
	v_mfma_f32_16x16x32_bf16 v[20:23], v[144:147], v[224:227], v[20:23]
	s_nop 0
	s_nop 0
	v_mfma_f32_16x16x32_bf16 v[48:51], v[160:163], v[182:185], v[48:51]
	v_mfma_f32_16x16x32_bf16 v[40:43], v[174:177], v[182:185], v[40:43]
	v_mfma_f32_16x16x32_bf16 v[32:35], v[160:163], v[190:193], v[32:35]
	v_mfma_f32_16x16x32_bf16 v[24:27], v[174:177], v[190:193], v[24:27]
	v_mfma_f32_16x16x32_bf16 v[16:19], v[160:163], v[212:215], v[16:19]
	v_mfma_f32_16x16x32_bf16 v[12:15], v[174:177], v[212:215], v[12:15]
	v_mfma_f32_16x16x32_bf16 v[8:11], v[160:163], v[220:223], v[8:11]
	v_mfma_f32_16x16x32_bf16 v[4:7], v[174:177], v[220:223], v[4:7]
	v_mfma_f32_16x16x32_bf16 v[48:51], v[170:173], v[186:189], v[48:51]
	v_mfma_f32_16x16x32_bf16 v[40:43], v[178:181], v[186:189], v[40:43]
	v_mfma_f32_16x16x32_bf16 v[32:35], v[170:173], v[194:197], v[32:35]
	v_mfma_f32_16x16x32_bf16 v[24:27], v[178:181], v[194:197], v[24:27]
	v_mfma_f32_16x16x32_bf16 v[16:19], v[170:173], v[216:219], v[16:19]
	v_mfma_f32_16x16x32_bf16 v[12:15], v[178:181], v[216:219], v[12:15]
	v_mfma_f32_16x16x32_bf16 v[8:11], v[170:173], v[224:227], v[8:11]
	v_mfma_f32_16x16x32_bf16 v[4:7], v[178:181], v[224:227], v[4:7]
	s_nop 0
	s_barrier
	s_add_i32 s63, s63, 2
	s_add_u32 s44, s44, 0x100
	s_addc_u32 s45, s45, 0
	s_add_u32 s59, s59, 0x100
	s_addc_u32 s62, s62, 0
	s_cmp_gt_u32 s63, 29
	s_cbranch_scc0 .LBB0_212
	s_and_b64 vcc, exec, s[18:19]
	s_cbranch_vccz .LBB0_215
	s_barrier

.LBB0_316:
	s_add_u32 s34, s30, 0xfff80080
	s_addc_u32 s35, s31, -1
	s_add_i32 s55, 0, 0x10000
	s_cmp_eq_u32 s54, 28
	s_cselect_b32 s37, s23, s35
	s_cselect_b32 s36, s48, s34
	v_add_u32_e32 v2, s55, v144
	s_cselect_b32 s35, s21, s53
	s_cselect_b32 s34, s49, s52
	s_add_i32 s58, 0, 0x14000
	ds_read_b128 v[146:149], v2
	ds_read_b128 v[150:153], v2 offset:1024
	ds_read_b128 v[154:157], v2 offset:2048
	ds_read_b128 v[158:161], v2 offset:3072
	v_add_u32_e32 v2, s58, v144
	ds_read_b128 v[162:165], v2
	ds_read_b128 v[168:171], v2 offset:1024
	ds_read_b128 v[172:175], v2 offset:2048
	ds_read_b128 v[176:179], v2 offset:3072
	v_lshl_add_u64 v[204:205], s[30:31], 0, v[140:141]
	s_add_i32 m0, s40, 0xc000
	ds_read_b128 v[180:183], v145
	ds_read_b128 v[184:187], v145 offset:1024
	ds_read_b128 v[188:191], v145 offset:2048
	ds_read_b128 v[192:195], v145 offset:3072
	ds_read_b128 v[196:199], v145 offset:4096
	ds_read_b128 v[212:215], v145 offset:5120
	ds_read_b128 v[216:219], v145 offset:6144
	ds_read_b128 v[220:223], v145 offset:7168
	global_load_lds_dwordx4 v[204:205], off
	v_lshl_add_u64 v[204:205], s[30:31], 0, v[142:143]
	s_add_i32 m0, s40, 0xe000
	s_nop 0
	global_load_lds_dwordx4 v[204:205], off
	s_waitcnt vmcnt(8)
	s_waitcnt lgkmcnt(0)
	s_barrier
	s_nop 0
	s_waitcnt lgkmcnt(0)
	v_mfma_f32_16x16x32_bf16 v[128:131], v[146:149], v[180:183], v[128:131]
	v_mfma_f32_16x16x32_bf16 v[124:127], v[154:157], v[180:183], v[124:127]
	v_mfma_f32_16x16x32_bf16 v[120:123], v[146:149], v[188:191], v[120:123]
	v_mfma_f32_16x16x32_bf16 v[116:119], v[154:157], v[188:191], v[116:119]
	v_mfma_f32_16x16x32_bf16 v[104:107], v[146:149], v[196:199], v[104:107]
	v_mfma_f32_16x16x32_bf16 v[100:103], v[154:157], v[196:199], v[100:103]
	v_mfma_f32_16x16x32_bf16 v[88:91], v[146:149], v[216:219], v[88:91]
	v_mfma_f32_16x16x32_bf16 v[84:87], v[154:157], v[216:219], v[84:87]
	v_mfma_f32_16x16x32_bf16 v[128:131], v[150:153], v[184:187], v[128:131]
	v_mfma_f32_16x16x32_bf16 v[124:127], v[158:161], v[184:187], v[124:127]
	v_mfma_f32_16x16x32_bf16 v[120:123], v[150:153], v[192:195], v[120:123]
	v_mfma_f32_16x16x32_bf16 v[116:119], v[158:161], v[192:195], v[116:119]
	v_mfma_f32_16x16x32_bf16 v[104:107], v[150:153], v[212:215], v[104:107]
	v_mfma_f32_16x16x32_bf16 v[100:103], v[158:161], v[212:215], v[100:103]
	v_mfma_f32_16x16x32_bf16 v[88:91], v[150:153], v[220:223], v[88:91]
	v_mfma_f32_16x16x32_bf16 v[84:87], v[158:161], v[220:223], v[84:87]
	s_nop 0
	s_nop 0
	v_mfma_f32_16x16x32_bf16 v[112:115], v[162:165], v[180:183], v[112:115]
	v_mfma_f32_16x16x32_bf16 v[108:111], v[172:175], v[180:183], v[108:111]
	v_mfma_f32_16x16x32_bf16 v[96:99], v[162:165], v[188:191], v[96:99]
	v_mfma_f32_16x16x32_bf16 v[92:95], v[172:175], v[188:191], v[92:95]
	v_mfma_f32_16x16x32_bf16 v[80:83], v[162:165], v[196:199], v[80:83]
	v_mfma_f32_16x16x32_bf16 v[76:79], v[172:175], v[196:199], v[76:79]
	v_mfma_f32_16x16x32_bf16 v[72:75], v[162:165], v[216:219], v[72:75]
	v_mfma_f32_16x16x32_bf16 v[68:71], v[172:175], v[216:219], v[68:71]
	v_mfma_f32_16x16x32_bf16 v[112:115], v[168:171], v[184:187], v[112:115]
	v_mfma_f32_16x16x32_bf16 v[108:111], v[176:179], v[184:187], v[108:111]
	v_mfma_f32_16x16x32_bf16 v[96:99], v[168:171], v[192:195], v[96:99]
	v_mfma_f32_16x16x32_bf16 v[92:95], v[176:179], v[192:195], v[92:95]
	v_mfma_f32_16x16x32_bf16 v[80:83], v[168:171], v[212:215], v[80:83]
	v_mfma_f32_16x16x32_bf16 v[76:79], v[176:179], v[212:215], v[76:79]
	v_mfma_f32_16x16x32_bf16 v[72:75], v[168:171], v[220:223], v[72:75]
	v_mfma_f32_16x16x32_bf16 v[68:71], v[176:179], v[220:223], v[68:71]
	s_nop 0
	s_barrier
	s_add_i32 s55, s55, s38
	v_lshl_add_u64 v[204:205], s[34:35], 0, v[136:137]
	s_mov_b32 m0, s55
	ds_read_b128 v[180:183], v145 offset:16384
	ds_read_b128 v[184:187], v145 offset:17408
	ds_read_b128 v[188:191], v145 offset:18432
	ds_read_b128 v[192:195], v145 offset:19456
	ds_read_b128 v[196:199], v145 offset:20480
	ds_read_b128 v[212:215], v145 offset:21504
	ds_read_b128 v[216:219], v145 offset:22528
	ds_read_b128 v[220:223], v145 offset:23552
	global_load_lds_dwordx4 v[204:205], off
	s_add_i32 m0, s55, 0x2000
	s_add_u32 s56, s34, 0x80000
	v_lshl_add_u64 v[206:207], s[34:35], 0, v[132:133]
	s_addc_u32 s57, s35, 0
	s_add_i32 s55, s58, s38
	global_load_lds_dwordx4 v[206:207], off
	v_lshl_add_u64 v[224:225], s[56:57], 0, v[136:137]
	s_mov_b32 m0, s55
	v_lshl_add_u64 v[226:227], s[36:37], 0, v[134:135]
	global_load_lds_dwordx4 v[224:225], off
	v_lshl_add_u64 v[224:225], s[56:57], 0, v[132:133]
	s_add_i32 m0, s55, 0x2000
	s_nop 0
	global_load_lds_dwordx4 v[224:225], off
	v_lshl_add_u64 v[224:225], s[36:37], 0, v[138:139]
	s_mov_b32 m0, s40
	s_nop 0
	global_load_lds_dwordx4 v[224:225], off
	s_mov_b32 m0, s41
	s_nop 0
	global_load_lds_dwordx4 v[226:227], off
	s_waitcnt vmcnt(8)
	s_waitcnt lgkmcnt(0)
	s_barrier
	s_nop 0
	s_waitcnt lgkmcnt(0)
	v_mfma_f32_16x16x32_bf16 v[64:67], v[146:149], v[180:183], v[64:67]
	v_mfma_f32_16x16x32_bf16 v[60:63], v[154:157], v[180:183], v[60:63]
	v_mfma_f32_16x16x32_bf16 v[56:59], v[146:149], v[188:191], v[56:59]
	v_mfma_f32_16x16x32_bf16 v[52:55], v[154:157], v[188:191], v[52:55]
	v_mfma_f32_16x16x32_bf16 v[40:43], v[146:149], v[196:199], v[40:43]
	v_mfma_f32_16x16x32_bf16 v[36:39], v[154:157], v[196:199], v[36:39]
	v_mfma_f32_16x16x32_bf16 v[24:27], v[146:149], v[216:219], v[24:27]
	v_mfma_f32_16x16x32_bf16 v[20:23], v[154:157], v[216:219], v[20:23]
	v_mfma_f32_16x16x32_bf16 v[64:67], v[150:153], v[184:187], v[64:67]
	v_mfma_f32_16x16x32_bf16 v[60:63], v[158:161], v[184:187], v[60:63]
	v_mfma_f32_16x16x32_bf16 v[56:59], v[150:153], v[192:195], v[56:59]
	v_mfma_f32_16x16x32_bf16 v[52:55], v[158:161], v[192:195], v[52:55]
	v_mfma_f32_16x16x32_bf16 v[40:43], v[150:153], v[212:215], v[40:43]
	v_mfma_f32_16x16x32_bf16 v[36:39], v[158:161], v[212:215], v[36:39]
	v_mfma_f32_16x16x32_bf16 v[24:27], v[150:153], v[220:223], v[24:27]
	v_mfma_f32_16x16x32_bf16 v[20:23], v[158:161], v[220:223], v[20:23]
	s_nop 0
	s_nop 0
	v_mfma_f32_16x16x32_bf16 v[48:51], v[162:165], v[180:183], v[48:51]
	v_mfma_f32_16x16x32_bf16 v[44:47], v[172:175], v[180:183], v[44:47]
	v_mfma_f32_16x16x32_bf16 v[32:35], v[162:165], v[188:191], v[32:35]
	v_mfma_f32_16x16x32_bf16 v[28:31], v[172:175], v[188:191], v[28:31]
	v_mfma_f32_16x16x32_bf16 v[16:19], v[162:165], v[196:199], v[16:19]
	v_mfma_f32_16x16x32_bf16 v[12:15], v[172:175], v[196:199], v[12:15]
	v_mfma_f32_16x16x32_bf16 v[8:11], v[162:165], v[216:219], v[8:11]
	v_mfma_f32_16x16x32_bf16 v[4:7], v[172:175], v[216:219], v[4:7]
	v_mfma_f32_16x16x32_bf16 v[48:51], v[168:171], v[184:187], v[48:51]
	v_mfma_f32_16x16x32_bf16 v[44:47], v[176:179], v[184:187], v[44:47]
	v_mfma_f32_16x16x32_bf16 v[32:35], v[168:171], v[192:195], v[32:35]
	v_mfma_f32_16x16x32_bf16 v[28:31], v[176:179], v[192:195], v[28:31]
	v_mfma_f32_16x16x32_bf16 v[16:19], v[168:171], v[212:215], v[16:19]
	v_mfma_f32_16x16x32_bf16 v[12:15], v[176:179], v[212:215], v[12:15]
	v_mfma_f32_16x16x32_bf16 v[8:11], v[168:171], v[220:223], v[8:11]
	v_mfma_f32_16x16x32_bf16 v[4:7], v[176:179], v[220:223], v[4:7]
	s_nop 0
	s_barrier
	s_add_i32 s55, 0, 0x18000
	v_add_u32_e32 v2, s55, v144
	s_add_i32 s56, 0, 0x1c000
	ds_read_b128 v[146:149], v2
	ds_read_b128 v[150:153], v2 offset:1024
	ds_read_b128 v[154:157], v2 offset:2048
	ds_read_b128 v[158:161], v2 offset:3072
	v_add_u32_e32 v2, s56, v144
	ds_read_b128 v[162:165], v2
	ds_read_b128 v[168:171], v2 offset:1024
	ds_read_b128 v[172:175], v2 offset:2048
	ds_read_b128 v[176:179], v2 offset:3072
	s_add_u32 s36, s36, 0x80000
	s_addc_u32 s37, s37, 0
	s_mov_b32 m0, s42
	v_lshl_add_u64 v[228:229], s[36:37], 0, v[138:139]
	ds_read_b128 v[180:183], v145 offset:32768
	ds_read_b128 v[184:187], v145 offset:33792
	ds_read_b128 v[188:191], v145 offset:34816
	ds_read_b128 v[192:195], v145 offset:35840
	ds_read_b128 v[196:199], v145 offset:36864
	ds_read_b128 v[212:215], v145 offset:37888
	ds_read_b128 v[216:219], v145 offset:38912
	ds_read_b128 v[220:223], v145 offset:39936
	global_load_lds_dwordx4 v[228:229], off
	v_lshl_add_u64 v[228:229], s[36:37], 0, v[134:135]
	s_mov_b32 m0, s43
	s_nop 0
	global_load_lds_dwordx4 v[228:229], off
	s_waitcnt vmcnt(8)
	s_waitcnt lgkmcnt(0)
	s_barrier
	s_nop 0
	s_waitcnt lgkmcnt(0)
	v_mfma_f32_16x16x32_bf16 v[128:131], v[146:149], v[180:183], v[128:131]
	v_mfma_f32_16x16x32_bf16 v[124:127], v[154:157], v[180:183], v[124:127]
	v_mfma_f32_16x16x32_bf16 v[120:123], v[146:149], v[188:191], v[120:123]
	v_mfma_f32_16x16x32_bf16 v[116:119], v[154:157], v[188:191], v[116:119]
	v_mfma_f32_16x16x32_bf16 v[104:107], v[146:149], v[196:199], v[104:107]
	v_mfma_f32_16x16x32_bf16 v[100:103], v[154:157], v[196:199], v[100:103]
	v_mfma_f32_16x16x32_bf16 v[88:91], v[146:149], v[216:219], v[88:91]
	v_mfma_f32_16x16x32_bf16 v[84:87], v[154:157], v[216:219], v[84:87]
	v_mfma_f32_16x16x32_bf16 v[128:131], v[150:153], v[184:187], v[128:131]
	v_mfma_f32_16x16x32_bf16 v[124:127], v[158:161], v[184:187], v[124:127]
	v_mfma_f32_16x16x32_bf16 v[120:123], v[150:153], v[192:195], v[120:123]
	v_mfma_f32_16x16x32_bf16 v[116:119], v[158:161], v[192:195], v[116:119]
	v_mfma_f32_16x16x32_bf16 v[104:107], v[150:153], v[212:215], v[104:107]
	v_mfma_f32_16x16x32_bf16 v[100:103], v[158:161], v[212:215], v[100:103]
	v_mfma_f32_16x16x32_bf16 v[88:91], v[150:153], v[220:223], v[88:91]
	v_mfma_f32_16x16x32_bf16 v[84:87], v[158:161], v[220:223], v[84:87]
	s_nop 0
	s_nop 0
	v_mfma_f32_16x16x32_bf16 v[112:115], v[162:165], v[180:183], v[112:115]
	v_mfma_f32_16x16x32_bf16 v[108:111], v[172:175], v[180:183], v[108:111]
	v_mfma_f32_16x16x32_bf16 v[96:99], v[162:165], v[188:191], v[96:99]
	v_mfma_f32_16x16x32_bf16 v[92:95], v[172:175], v[188:191], v[92:95]
	v_mfma_f32_16x16x32_bf16 v[80:83], v[162:165], v[196:199], v[80:83]
	v_mfma_f32_16x16x32_bf16 v[76:79], v[172:175], v[196:199], v[76:79]
	v_mfma_f32_16x16x32_bf16 v[72:75], v[162:165], v[216:219], v[72:75]
	v_mfma_f32_16x16x32_bf16 v[68:71], v[172:175], v[216:219], v[68:71]
	v_mfma_f32_16x16x32_bf16 v[112:115], v[168:171], v[184:187], v[112:115]
	v_mfma_f32_16x16x32_bf16 v[108:111], v[176:179], v[184:187], v[108:111]
	v_mfma_f32_16x16x32_bf16 v[96:99], v[168:171], v[192:195], v[96:99]
	v_mfma_f32_16x16x32_bf16 v[92:95], v[176:179], v[192:195], v[92:95]
	v_mfma_f32_16x16x32_bf16 v[80:83], v[168:171], v[212:215], v[80:83]
	v_mfma_f32_16x16x32_bf16 v[76:79], v[176:179], v[212:215], v[76:79]
	v_mfma_f32_16x16x32_bf16 v[72:75], v[168:171], v[220:223], v[72:75]
	v_mfma_f32_16x16x32_bf16 v[68:71], v[176:179], v[220:223], v[68:71]
	s_nop 0
	s_barrier
	s_add_i32 s36, s55, s38
	v_lshl_add_u64 v[204:205], v[204:205], 0, s[94:95]
	s_mov_b32 m0, s36
	ds_read_b128 v[180:183], v145 offset:49152
	ds_read_b128 v[184:187], v145 offset:50176
	ds_read_b128 v[188:191], v145 offset:51200
	ds_read_b128 v[192:195], v145 offset:52224
	ds_read_b128 v[196:199], v145 offset:53248
	ds_read_b128 v[212:215], v145 offset:54272
	ds_read_b128 v[216:219], v145 offset:55296
	ds_read_b128 v[220:223], v145 offset:56320
	global_load_lds_dwordx4 v[204:205], off
	s_add_i32 m0, s36, 0x2000
	s_add_u32 s34, s34, 0x80080
	v_lshl_add_u64 v[204:205], v[206:207], 0, s[94:95]
	s_addc_u32 s35, s35, 0
	s_add_i32 s36, s56, s38
	global_load_lds_dwordx4 v[204:205], off
	v_lshl_add_u64 v[204:205], s[34:35], 0, v[136:137]
	s_mov_b32 m0, s36
	s_nop 0
	global_load_lds_dwordx4 v[204:205], off
	v_lshl_add_u64 v[204:205], s[34:35], 0, v[132:133]
	s_add_i32 m0, s36, 0x2000
	s_nop 0
	global_load_lds_dwordx4 v[204:205], off
	v_lshl_add_u64 v[204:205], v[224:225], 0, s[94:95]
	s_mov_b32 m0, s44
	s_nop 0
	global_load_lds_dwordx4 v[204:205], off
	v_lshl_add_u64 v[204:205], v[226:227], 0, s[94:95]
	s_mov_b32 m0, s45
	s_nop 0
	global_load_lds_dwordx4 v[204:205], off
	s_waitcnt vmcnt(8)
	s_waitcnt lgkmcnt(0)
	s_barrier
	s_nop 0
	s_waitcnt lgkmcnt(0)
	v_mfma_f32_16x16x32_bf16 v[64:67], v[146:149], v[180:183], v[64:67]
	v_mfma_f32_16x16x32_bf16 v[60:63], v[154:157], v[180:183], v[60:63]
	v_mfma_f32_16x16x32_bf16 v[56:59], v[146:149], v[188:191], v[56:59]
	v_mfma_f32_16x16x32_bf16 v[52:55], v[154:157], v[188:191], v[52:55]
	v_mfma_f32_16x16x32_bf16 v[40:43], v[146:149], v[196:199], v[40:43]
	v_mfma_f32_16x16x32_bf16 v[36:39], v[154:157], v[196:199], v[36:39]
	v_mfma_f32_16x16x32_bf16 v[24:27], v[146:149], v[216:219], v[24:27]
	v_mfma_f32_16x16x32_bf16 v[20:23], v[154:157], v[216:219], v[20:23]
	v_mfma_f32_16x16x32_bf16 v[64:67], v[150:153], v[184:187], v[64:67]
	v_mfma_f32_16x16x32_bf16 v[60:63], v[158:161], v[184:187], v[60:63]
	v_mfma_f32_16x16x32_bf16 v[56:59], v[150:153], v[192:195], v[56:59]
	v_mfma_f32_16x16x32_bf16 v[52:55], v[158:161], v[192:195], v[52:55]
	v_mfma_f32_16x16x32_bf16 v[40:43], v[150:153], v[212:215], v[40:43]
	v_mfma_f32_16x16x32_bf16 v[36:39], v[158:161], v[212:215], v[36:39]
	v_mfma_f32_16x16x32_bf16 v[24:27], v[150:153], v[220:223], v[24:27]
	v_mfma_f32_16x16x32_bf16 v[20:23], v[158:161], v[220:223], v[20:23]
	s_nop 0
	s_nop 0
	v_mfma_f32_16x16x32_bf16 v[48:51], v[162:165], v[180:183], v[48:51]
	v_mfma_f32_16x16x32_bf16 v[44:47], v[172:175], v[180:183], v[44:47]
	v_mfma_f32_16x16x32_bf16 v[32:35], v[162:165], v[188:191], v[32:35]
	v_mfma_f32_16x16x32_bf16 v[28:31], v[172:175], v[188:191], v[28:31]
	v_mfma_f32_16x16x32_bf16 v[16:19], v[162:165], v[196:199], v[16:19]
	v_mfma_f32_16x16x32_bf16 v[12:15], v[172:175], v[196:199], v[12:15]
	v_mfma_f32_16x16x32_bf16 v[8:11], v[162:165], v[216:219], v[8:11]
	v_mfma_f32_16x16x32_bf16 v[4:7], v[172:175], v[216:219], v[4:7]
	v_mfma_f32_16x16x32_bf16 v[48:51], v[168:171], v[184:187], v[48:51]
	v_mfma_f32_16x16x32_bf16 v[44:47], v[176:179], v[184:187], v[44:47]
	v_mfma_f32_16x16x32_bf16 v[32:35], v[168:171], v[192:195], v[32:35]
	v_mfma_f32_16x16x32_bf16 v[28:31], v[176:179], v[192:195], v[28:31]
	v_mfma_f32_16x16x32_bf16 v[16:19], v[168:171], v[212:215], v[16:19]
	v_mfma_f32_16x16x32_bf16 v[12:15], v[176:179], v[212:215], v[12:15]
	v_mfma_f32_16x16x32_bf16 v[8:11], v[168:171], v[220:223], v[8:11]
	v_mfma_f32_16x16x32_bf16 v[4:7], v[176:179], v[220:223], v[4:7]
	s_nop 0
	s_barrier
	s_add_i32 s54, s54, 2
	s_add_u32 s30, s30, 0x100
	s_addc_u32 s31, s31, 0
	s_add_u32 s52, s52, 0x100
	s_addc_u32 s53, s53, 0
	s_cmp_gt_u32 s54, 29
	s_cbranch_scc0 .LBB0_316
	s_and_b64 vcc, exec, s[18:19]
	s_cbranch_vccz .LBB0_319
	s_barrier

.LBB0_342:
	s_add_u32 s38, s36, 0xfffe0080
	s_addc_u32 s39, s37, -1
	s_add_i32 s56, 0, 0x10000
	s_cmp_eq_u32 s55, 4
	s_cselect_b32 s45, s23, s39
	s_cselect_b32 s44, s25, s38
	v_add_u32_e32 v2, s56, v150
	s_cselect_b32 s39, s27, s54
	s_cselect_b32 s38, s29, s53
	s_add_i32 s58, 0, 0x14000
	ds_read_b128 v[144:147], v2
	ds_read_b128 v[152:155], v2 offset:1024
	ds_read_b128 v[156:159], v2 offset:2048
	ds_read_b128 v[160:163], v2 offset:3072
	v_add_u32_e32 v2, s58, v150
	ds_read_b128 v[168:171], v2
	ds_read_b128 v[172:175], v2 offset:1024
	ds_read_b128 v[176:179], v2 offset:2048
	ds_read_b128 v[180:183], v2 offset:3072
	v_lshl_add_u64 v[148:149], s[36:37], 0, v[140:141]
	s_add_i32 m0, s11, 0xc000
	ds_read_b128 v[184:187], v151
	ds_read_b128 v[188:191], v151 offset:1024
	ds_read_b128 v[192:195], v151 offset:2048
	ds_read_b128 v[196:199], v151 offset:3072
	ds_read_b128 v[212:215], v151 offset:4096
	ds_read_b128 v[216:219], v151 offset:5120
	ds_read_b128 v[220:223], v151 offset:6144
	ds_read_b128 v[224:227], v151 offset:7168
	global_load_lds_dwordx4 v[148:149], off
	v_lshl_add_u64 v[148:149], s[36:37], 0, v[142:143]
	s_add_i32 m0, s11, 0xe000
	s_nop 0
	global_load_lds_dwordx4 v[148:149], off
	s_waitcnt vmcnt(8)
	s_waitcnt lgkmcnt(0)
	s_barrier
	s_nop 0
	s_waitcnt lgkmcnt(0)
	v_mfma_f32_16x16x32_bf16 v[128:131], v[144:147], v[184:187], v[128:131]
	v_mfma_f32_16x16x32_bf16 v[124:127], v[156:159], v[184:187], v[124:127]
	v_mfma_f32_16x16x32_bf16 v[116:119], v[144:147], v[192:195], v[116:119]
	v_mfma_f32_16x16x32_bf16 v[108:111], v[156:159], v[192:195], v[108:111]
	v_mfma_f32_16x16x32_bf16 v[100:103], v[144:147], v[212:215], v[100:103]
	v_mfma_f32_16x16x32_bf16 v[92:95], v[156:159], v[212:215], v[92:95]
	v_mfma_f32_16x16x32_bf16 v[84:87], v[144:147], v[220:223], v[84:87]
	v_mfma_f32_16x16x32_bf16 v[76:79], v[156:159], v[220:223], v[76:79]
	v_mfma_f32_16x16x32_bf16 v[128:131], v[152:155], v[188:191], v[128:131]
	v_mfma_f32_16x16x32_bf16 v[124:127], v[160:163], v[188:191], v[124:127]
	v_mfma_f32_16x16x32_bf16 v[116:119], v[152:155], v[196:199], v[116:119]
	v_mfma_f32_16x16x32_bf16 v[108:111], v[160:163], v[196:199], v[108:111]
	v_mfma_f32_16x16x32_bf16 v[100:103], v[152:155], v[216:219], v[100:103]
	v_mfma_f32_16x16x32_bf16 v[92:95], v[160:163], v[216:219], v[92:95]
	v_mfma_f32_16x16x32_bf16 v[84:87], v[152:155], v[224:227], v[84:87]
	v_mfma_f32_16x16x32_bf16 v[76:79], v[160:163], v[224:227], v[76:79]
	s_nop 0
	s_nop 0
	v_mfma_f32_16x16x32_bf16 v[120:123], v[168:171], v[184:187], v[120:123]
	v_mfma_f32_16x16x32_bf16 v[112:115], v[176:179], v[184:187], v[112:115]
	v_mfma_f32_16x16x32_bf16 v[104:107], v[168:171], v[192:195], v[104:107]
	v_mfma_f32_16x16x32_bf16 v[96:99], v[176:179], v[192:195], v[96:99]
	v_mfma_f32_16x16x32_bf16 v[88:91], v[168:171], v[212:215], v[88:91]
	v_mfma_f32_16x16x32_bf16 v[80:83], v[176:179], v[212:215], v[80:83]
	v_mfma_f32_16x16x32_bf16 v[72:75], v[168:171], v[220:223], v[72:75]
	v_mfma_f32_16x16x32_bf16 v[68:71], v[176:179], v[220:223], v[68:71]
	v_mfma_f32_16x16x32_bf16 v[120:123], v[172:175], v[188:191], v[120:123]
	v_mfma_f32_16x16x32_bf16 v[112:115], v[180:183], v[188:191], v[112:115]
	v_mfma_f32_16x16x32_bf16 v[104:107], v[172:175], v[196:199], v[104:107]
	v_mfma_f32_16x16x32_bf16 v[96:99], v[180:183], v[196:199], v[96:99]
	v_mfma_f32_16x16x32_bf16 v[88:91], v[172:175], v[216:219], v[88:91]
	v_mfma_f32_16x16x32_bf16 v[80:83], v[180:183], v[216:219], v[80:83]
	v_mfma_f32_16x16x32_bf16 v[72:75], v[172:175], v[224:227], v[72:75]
	v_mfma_f32_16x16x32_bf16 v[68:71], v[180:183], v[224:227], v[68:71]
	s_nop 0
	s_barrier
	s_add_i32 s56, s56, s10
	v_lshl_add_u64 v[148:149], s[38:39], 0, v[134:135]
	s_mov_b32 m0, s56
	ds_read_b128 v[184:187], v151 offset:16384
	ds_read_b128 v[188:191], v151 offset:17408
	ds_read_b128 v[192:195], v151 offset:18432
	ds_read_b128 v[196:199], v151 offset:19456
	ds_read_b128 v[212:215], v151 offset:20480
	ds_read_b128 v[216:219], v151 offset:21504
	ds_read_b128 v[220:223], v151 offset:22528
	ds_read_b128 v[224:227], v151 offset:23552
	global_load_lds_dwordx4 v[148:149], off
	s_add_i32 m0, s56, 0x2000
	s_add_u32 s56, s38, 0x20000
	v_lshl_add_u64 v[164:165], s[38:39], 0, v[138:139]
	s_addc_u32 s57, s39, 0
	s_add_i32 s58, s58, s10
	global_load_lds_dwordx4 v[164:165], off
	v_lshl_add_u64 v[204:205], s[56:57], 0, v[134:135]
	s_mov_b32 m0, s58
	v_lshl_add_u64 v[206:207], s[44:45], 0, v[136:137]
	global_load_lds_dwordx4 v[204:205], off
	v_lshl_add_u64 v[204:205], s[56:57], 0, v[138:139]
	s_add_i32 m0, s58, 0x2000
	s_nop 0
	global_load_lds_dwordx4 v[204:205], off
	v_lshl_add_u64 v[204:205], s[44:45], 0, v[132:133]
	s_mov_b32 m0, s11
	s_nop 0
	global_load_lds_dwordx4 v[204:205], off
	s_mov_b32 m0, s33
	s_nop 0
	global_load_lds_dwordx4 v[206:207], off
	s_waitcnt vmcnt(8)
	s_waitcnt lgkmcnt(0)
	s_barrier
	s_nop 0
	s_waitcnt lgkmcnt(0)
	v_mfma_f32_16x16x32_bf16 v[64:67], v[144:147], v[184:187], v[64:67]
	v_mfma_f32_16x16x32_bf16 v[60:63], v[156:159], v[184:187], v[60:63]
	v_mfma_f32_16x16x32_bf16 v[52:55], v[144:147], v[192:195], v[52:55]
	v_mfma_f32_16x16x32_bf16 v[44:47], v[156:159], v[192:195], v[44:47]
	v_mfma_f32_16x16x32_bf16 v[36:39], v[144:147], v[212:215], v[36:39]
	v_mfma_f32_16x16x32_bf16 v[28:31], v[156:159], v[212:215], v[28:31]
	v_mfma_f32_16x16x32_bf16 v[20:23], v[144:147], v[220:223], v[20:23]
	v_mfma_f32_16x16x32_bf16 v[12:15], v[156:159], v[220:223], v[12:15]
	v_mfma_f32_16x16x32_bf16 v[64:67], v[152:155], v[188:191], v[64:67]
	v_mfma_f32_16x16x32_bf16 v[60:63], v[160:163], v[188:191], v[60:63]
	v_mfma_f32_16x16x32_bf16 v[52:55], v[152:155], v[196:199], v[52:55]
	v_mfma_f32_16x16x32_bf16 v[44:47], v[160:163], v[196:199], v[44:47]
	v_mfma_f32_16x16x32_bf16 v[36:39], v[152:155], v[216:219], v[36:39]
	v_mfma_f32_16x16x32_bf16 v[28:31], v[160:163], v[216:219], v[28:31]
	v_mfma_f32_16x16x32_bf16 v[20:23], v[152:155], v[224:227], v[20:23]
	v_mfma_f32_16x16x32_bf16 v[12:15], v[160:163], v[224:227], v[12:15]
	s_nop 0
	s_nop 0
	v_mfma_f32_16x16x32_bf16 v[56:59], v[168:171], v[184:187], v[56:59]
	v_mfma_f32_16x16x32_bf16 v[48:51], v[176:179], v[184:187], v[48:51]
	v_mfma_f32_16x16x32_bf16 v[40:43], v[168:171], v[192:195], v[40:43]
	v_mfma_f32_16x16x32_bf16 v[32:35], v[176:179], v[192:195], v[32:35]
	v_mfma_f32_16x16x32_bf16 v[24:27], v[168:171], v[212:215], v[24:27]
	v_mfma_f32_16x16x32_bf16 v[16:19], v[176:179], v[212:215], v[16:19]
	v_mfma_f32_16x16x32_bf16 v[8:11], v[168:171], v[220:223], v[8:11]
	v_mfma_f32_16x16x32_bf16 v[4:7], v[176:179], v[220:223], v[4:7]
	v_mfma_f32_16x16x32_bf16 v[56:59], v[172:175], v[188:191], v[56:59]
	v_mfma_f32_16x16x32_bf16 v[48:51], v[180:183], v[188:191], v[48:51]
	v_mfma_f32_16x16x32_bf16 v[40:43], v[172:175], v[196:199], v[40:43]
	v_mfma_f32_16x16x32_bf16 v[32:35], v[180:183], v[196:199], v[32:35]
	v_mfma_f32_16x16x32_bf16 v[24:27], v[172:175], v[216:219], v[24:27]
	v_mfma_f32_16x16x32_bf16 v[16:19], v[180:183], v[216:219], v[16:19]
	v_mfma_f32_16x16x32_bf16 v[8:11], v[172:175], v[224:227], v[8:11]
	v_mfma_f32_16x16x32_bf16 v[4:7], v[180:183], v[224:227], v[4:7]
	s_nop 0
	s_barrier
	s_add_i32 s56, 0, 0x18000
	v_add_u32_e32 v2, s56, v150
	s_add_i32 s57, 0, 0x1c000
	ds_read_b128 v[144:147], v2
	ds_read_b128 v[152:155], v2 offset:1024
	ds_read_b128 v[156:159], v2 offset:2048
	ds_read_b128 v[160:163], v2 offset:3072
	v_add_u32_e32 v2, s57, v150
	ds_read_b128 v[168:171], v2
	ds_read_b128 v[172:175], v2 offset:1024
	ds_read_b128 v[176:179], v2 offset:2048
	ds_read_b128 v[180:183], v2 offset:3072
	s_add_u32 s44, s44, 0x20000
	s_addc_u32 s45, s45, 0
	s_mov_b32 m0, s40
	v_lshl_add_u64 v[228:229], s[44:45], 0, v[132:133]
	ds_read_b128 v[184:187], v151 offset:32768
	ds_read_b128 v[188:191], v151 offset:33792
	ds_read_b128 v[192:195], v151 offset:34816
	ds_read_b128 v[196:199], v151 offset:35840
	ds_read_b128 v[212:215], v151 offset:36864
	ds_read_b128 v[216:219], v151 offset:37888
	ds_read_b128 v[220:223], v151 offset:38912
	ds_read_b128 v[224:227], v151 offset:39936
	global_load_lds_dwordx4 v[228:229], off
	v_lshl_add_u64 v[228:229], s[44:45], 0, v[136:137]
	s_mov_b32 m0, s41
	s_nop 0
	global_load_lds_dwordx4 v[228:229], off
	s_waitcnt vmcnt(8)
	s_waitcnt lgkmcnt(0)
	s_barrier
	s_nop 0
	s_waitcnt lgkmcnt(0)
	v_mfma_f32_16x16x32_bf16 v[128:131], v[144:147], v[184:187], v[128:131]
	v_mfma_f32_16x16x32_bf16 v[124:127], v[156:159], v[184:187], v[124:127]
	v_mfma_f32_16x16x32_bf16 v[116:119], v[144:147], v[192:195], v[116:119]
	v_mfma_f32_16x16x32_bf16 v[108:111], v[156:159], v[192:195], v[108:111]
	v_mfma_f32_16x16x32_bf16 v[100:103], v[144:147], v[212:215], v[100:103]
	v_mfma_f32_16x16x32_bf16 v[92:95], v[156:159], v[212:215], v[92:95]
	v_mfma_f32_16x16x32_bf16 v[84:87], v[144:147], v[220:223], v[84:87]
	v_mfma_f32_16x16x32_bf16 v[76:79], v[156:159], v[220:223], v[76:79]
	v_mfma_f32_16x16x32_bf16 v[128:131], v[152:155], v[188:191], v[128:131]
	v_mfma_f32_16x16x32_bf16 v[124:127], v[160:163], v[188:191], v[124:127]
	v_mfma_f32_16x16x32_bf16 v[116:119], v[152:155], v[196:199], v[116:119]
	v_mfma_f32_16x16x32_bf16 v[108:111], v[160:163], v[196:199], v[108:111]
	v_mfma_f32_16x16x32_bf16 v[100:103], v[152:155], v[216:219], v[100:103]
	v_mfma_f32_16x16x32_bf16 v[92:95], v[160:163], v[216:219], v[92:95]
	v_mfma_f32_16x16x32_bf16 v[84:87], v[152:155], v[224:227], v[84:87]
	v_mfma_f32_16x16x32_bf16 v[76:79], v[160:163], v[224:227], v[76:79]
	s_nop 0
	s_nop 0
	v_mfma_f32_16x16x32_bf16 v[120:123], v[168:171], v[184:187], v[120:123]
	v_mfma_f32_16x16x32_bf16 v[112:115], v[176:179], v[184:187], v[112:115]
	v_mfma_f32_16x16x32_bf16 v[104:107], v[168:171], v[192:195], v[104:107]
	v_mfma_f32_16x16x32_bf16 v[96:99], v[176:179], v[192:195], v[96:99]
	v_mfma_f32_16x16x32_bf16 v[88:91], v[168:171], v[212:215], v[88:91]
	v_mfma_f32_16x16x32_bf16 v[80:83], v[176:179], v[212:215], v[80:83]
	v_mfma_f32_16x16x32_bf16 v[72:75], v[168:171], v[220:223], v[72:75]
	v_mfma_f32_16x16x32_bf16 v[68:71], v[176:179], v[220:223], v[68:71]
	v_mfma_f32_16x16x32_bf16 v[120:123], v[172:175], v[188:191], v[120:123]
	v_mfma_f32_16x16x32_bf16 v[112:115], v[180:183], v[188:191], v[112:115]
	v_mfma_f32_16x16x32_bf16 v[104:107], v[172:175], v[196:199], v[104:107]
	v_mfma_f32_16x16x32_bf16 v[96:99], v[180:183], v[196:199], v[96:99]
	v_mfma_f32_16x16x32_bf16 v[88:91], v[172:175], v[216:219], v[88:91]
	v_mfma_f32_16x16x32_bf16 v[80:83], v[180:183], v[216:219], v[80:83]
	v_mfma_f32_16x16x32_bf16 v[72:75], v[172:175], v[224:227], v[72:75]
	v_mfma_f32_16x16x32_bf16 v[68:71], v[180:183], v[224:227], v[68:71]
	s_nop 0
	s_barrier
	s_add_i32 s44, s56, s10
	v_lshl_add_u64 v[148:149], v[148:149], 0, s[94:95]
	s_mov_b32 m0, s44
	ds_read_b128 v[184:187], v151 offset:49152
	ds_read_b128 v[188:191], v151 offset:50176
	ds_read_b128 v[192:195], v151 offset:51200
	ds_read_b128 v[196:199], v151 offset:52224
	ds_read_b128 v[212:215], v151 offset:53248
	ds_read_b128 v[216:219], v151 offset:54272
	ds_read_b128 v[220:223], v151 offset:55296
	ds_read_b128 v[224:227], v151 offset:56320
	global_load_lds_dwordx4 v[148:149], off
	s_add_i32 m0, s44, 0x2000
	s_add_u32 s38, s38, 0x20080
	v_lshl_add_u64 v[148:149], v[164:165], 0, s[94:95]
	s_addc_u32 s39, s39, 0
	s_add_i32 s44, s57, s10
	global_load_lds_dwordx4 v[148:149], off
	v_lshl_add_u64 v[148:149], s[38:39], 0, v[134:135]
	s_mov_b32 m0, s44
	s_nop 0
	global_load_lds_dwordx4 v[148:149], off
	v_lshl_add_u64 v[148:149], s[38:39], 0, v[138:139]
	s_add_i32 m0, s44, 0x2000
	s_nop 0
	global_load_lds_dwordx4 v[148:149], off
	v_lshl_add_u64 v[148:149], v[204:205], 0, s[94:95]
	s_mov_b32 m0, s46
	s_nop 0
	global_load_lds_dwordx4 v[148:149], off
	v_lshl_add_u64 v[148:149], v[206:207], 0, s[94:95]
	s_mov_b32 m0, s47
	s_nop 0
	global_load_lds_dwordx4 v[148:149], off
	s_waitcnt vmcnt(8)
	s_waitcnt lgkmcnt(0)
	s_barrier
	s_nop 0
	s_waitcnt lgkmcnt(0)
	v_mfma_f32_16x16x32_bf16 v[64:67], v[144:147], v[184:187], v[64:67]
	v_mfma_f32_16x16x32_bf16 v[60:63], v[156:159], v[184:187], v[60:63]
	v_mfma_f32_16x16x32_bf16 v[52:55], v[144:147], v[192:195], v[52:55]
	v_mfma_f32_16x16x32_bf16 v[44:47], v[156:159], v[192:195], v[44:47]
	v_mfma_f32_16x16x32_bf16 v[36:39], v[144:147], v[212:215], v[36:39]
	v_mfma_f32_16x16x32_bf16 v[28:31], v[156:159], v[212:215], v[28:31]
	v_mfma_f32_16x16x32_bf16 v[20:23], v[144:147], v[220:223], v[20:23]
	v_mfma_f32_16x16x32_bf16 v[12:15], v[156:159], v[220:223], v[12:15]
	v_mfma_f32_16x16x32_bf16 v[64:67], v[152:155], v[188:191], v[64:67]
	v_mfma_f32_16x16x32_bf16 v[60:63], v[160:163], v[188:191], v[60:63]
	v_mfma_f32_16x16x32_bf16 v[52:55], v[152:155], v[196:199], v[52:55]
	v_mfma_f32_16x16x32_bf16 v[44:47], v[160:163], v[196:199], v[44:47]
	v_mfma_f32_16x16x32_bf16 v[36:39], v[152:155], v[216:219], v[36:39]
	v_mfma_f32_16x16x32_bf16 v[28:31], v[160:163], v[216:219], v[28:31]
	v_mfma_f32_16x16x32_bf16 v[20:23], v[152:155], v[224:227], v[20:23]
	v_mfma_f32_16x16x32_bf16 v[12:15], v[160:163], v[224:227], v[12:15]
	s_nop 0
	s_nop 0
	v_mfma_f32_16x16x32_bf16 v[56:59], v[168:171], v[184:187], v[56:59]
	v_mfma_f32_16x16x32_bf16 v[48:51], v[176:179], v[184:187], v[48:51]
	v_mfma_f32_16x16x32_bf16 v[40:43], v[168:171], v[192:195], v[40:43]
	v_mfma_f32_16x16x32_bf16 v[32:35], v[176:179], v[192:195], v[32:35]
	v_mfma_f32_16x16x32_bf16 v[24:27], v[168:171], v[212:215], v[24:27]
	v_mfma_f32_16x16x32_bf16 v[16:19], v[176:179], v[212:215], v[16:19]
	v_mfma_f32_16x16x32_bf16 v[8:11], v[168:171], v[220:223], v[8:11]
	v_mfma_f32_16x16x32_bf16 v[4:7], v[176:179], v[220:223], v[4:7]
	v_mfma_f32_16x16x32_bf16 v[56:59], v[172:175], v[188:191], v[56:59]
	v_mfma_f32_16x16x32_bf16 v[48:51], v[180:183], v[188:191], v[48:51]
	v_mfma_f32_16x16x32_bf16 v[40:43], v[172:175], v[196:199], v[40:43]
	v_mfma_f32_16x16x32_bf16 v[32:35], v[180:183], v[196:199], v[32:35]
	v_mfma_f32_16x16x32_bf16 v[24:27], v[172:175], v[216:219], v[24:27]
	v_mfma_f32_16x16x32_bf16 v[16:19], v[180:183], v[216:219], v[16:19]
	v_mfma_f32_16x16x32_bf16 v[8:11], v[172:175], v[224:227], v[8:11]
	v_mfma_f32_16x16x32_bf16 v[4:7], v[180:183], v[224:227], v[4:7]
	s_nop 0
	s_barrier
	s_add_i32 s55, s55, 2
	s_add_u32 s36, s36, 0x100
	s_addc_u32 s37, s37, 0
	s_add_u32 s53, s53, 0x100
	s_addc_u32 s54, s54, 0
	s_cmp_gt_u32 s55, 5
	s_cbranch_scc0 .LBB0_342
	s_and_b64 vcc, exec, s[18:19]
	s_cbranch_vccz .LBB0_345
	s_barrier

.LBB0_655:
	s_add_u32 s36, s34, 0xfffe0080
	s_addc_u32 s37, s35, -1
	s_add_i32 s55, 0, 0x10000
	s_cmp_eq_u32 s54, 4
	s_cselect_b32 s39, s27, s37
	s_cselect_b32 s38, s50, s36
	v_add_u32_e32 v2, s55, v144
	s_cselect_b32 s37, s23, s53
	s_cselect_b32 s36, s51, s52
	s_add_i32 s58, 0, 0x14000
	ds_read_b128 v[146:149], v2
	ds_read_b128 v[150:153], v2 offset:1024
	ds_read_b128 v[154:157], v2 offset:2048
	ds_read_b128 v[158:161], v2 offset:3072
	v_add_u32_e32 v2, s58, v144
	ds_read_b128 v[162:165], v2
	ds_read_b128 v[166:169], v2 offset:1024
	ds_read_b128 v[170:173], v2 offset:2048
	ds_read_b128 v[174:177], v2 offset:3072
	v_lshl_add_u64 v[198:199], s[34:35], 0, v[140:141]
	s_add_i32 m0, s40, 0xc000
	ds_read_b128 v[178:181], v145
	ds_read_b128 v[182:185], v145 offset:1024
	ds_read_b128 v[186:189], v145 offset:2048
	ds_read_b128 v[190:193], v145 offset:3072
	ds_read_b128 v[194:197], v145 offset:4096
	ds_read_b128 v[212:215], v145 offset:5120
	ds_read_b128 v[216:219], v145 offset:6144
	ds_read_b128 v[220:223], v145 offset:7168
	global_load_lds_dwordx4 v[198:199], off
	v_lshl_add_u64 v[198:199], s[34:35], 0, v[142:143]
	s_add_i32 m0, s40, 0xe000
	s_nop 0
	global_load_lds_dwordx4 v[198:199], off
	s_waitcnt vmcnt(8)
	s_waitcnt lgkmcnt(0)
	s_barrier
	s_nop 0
	s_waitcnt lgkmcnt(0)
	v_mfma_f32_16x16x32_bf16 v[128:131], v[146:149], v[178:181], v[128:131]
	v_mfma_f32_16x16x32_bf16 v[124:127], v[154:157], v[178:181], v[124:127]
	v_mfma_f32_16x16x32_bf16 v[120:123], v[146:149], v[186:189], v[120:123]
	v_mfma_f32_16x16x32_bf16 v[116:119], v[154:157], v[186:189], v[116:119]
	v_mfma_f32_16x16x32_bf16 v[104:107], v[146:149], v[194:197], v[104:107]
	v_mfma_f32_16x16x32_bf16 v[100:103], v[154:157], v[194:197], v[100:103]
	v_mfma_f32_16x16x32_bf16 v[88:91], v[146:149], v[216:219], v[88:91]
	v_mfma_f32_16x16x32_bf16 v[84:87], v[154:157], v[216:219], v[84:87]
	v_mfma_f32_16x16x32_bf16 v[128:131], v[150:153], v[182:185], v[128:131]
	v_mfma_f32_16x16x32_bf16 v[124:127], v[158:161], v[182:185], v[124:127]
	v_mfma_f32_16x16x32_bf16 v[120:123], v[150:153], v[190:193], v[120:123]
	v_mfma_f32_16x16x32_bf16 v[116:119], v[158:161], v[190:193], v[116:119]
	v_mfma_f32_16x16x32_bf16 v[104:107], v[150:153], v[212:215], v[104:107]
	v_mfma_f32_16x16x32_bf16 v[100:103], v[158:161], v[212:215], v[100:103]
	v_mfma_f32_16x16x32_bf16 v[88:91], v[150:153], v[220:223], v[88:91]
	v_mfma_f32_16x16x32_bf16 v[84:87], v[158:161], v[220:223], v[84:87]
	s_nop 0
	s_nop 0
	v_mfma_f32_16x16x32_bf16 v[112:115], v[162:165], v[178:181], v[112:115]
	v_mfma_f32_16x16x32_bf16 v[108:111], v[170:173], v[178:181], v[108:111]
	v_mfma_f32_16x16x32_bf16 v[96:99], v[162:165], v[186:189], v[96:99]
	v_mfma_f32_16x16x32_bf16 v[92:95], v[170:173], v[186:189], v[92:95]
	v_mfma_f32_16x16x32_bf16 v[80:83], v[162:165], v[194:197], v[80:83]
	v_mfma_f32_16x16x32_bf16 v[76:79], v[170:173], v[194:197], v[76:79]
	v_mfma_f32_16x16x32_bf16 v[72:75], v[162:165], v[216:219], v[72:75]
	v_mfma_f32_16x16x32_bf16 v[68:71], v[170:173], v[216:219], v[68:71]
	v_mfma_f32_16x16x32_bf16 v[112:115], v[166:169], v[182:185], v[112:115]
	v_mfma_f32_16x16x32_bf16 v[108:111], v[174:177], v[182:185], v[108:111]
	v_mfma_f32_16x16x32_bf16 v[96:99], v[166:169], v[190:193], v[96:99]
	v_mfma_f32_16x16x32_bf16 v[92:95], v[174:177], v[190:193], v[92:95]
	v_mfma_f32_16x16x32_bf16 v[80:83], v[166:169], v[212:215], v[80:83]
	v_mfma_f32_16x16x32_bf16 v[76:79], v[174:177], v[212:215], v[76:79]
	v_mfma_f32_16x16x32_bf16 v[72:75], v[166:169], v[220:223], v[72:75]
	v_mfma_f32_16x16x32_bf16 v[68:71], v[174:177], v[220:223], v[68:71]
	s_nop 0
	s_barrier
	s_add_i32 s55, s55, s15
	v_lshl_add_u64 v[198:199], s[36:37], 0, v[136:137]
	s_mov_b32 m0, s55
	ds_read_b128 v[178:181], v145 offset:16384
	ds_read_b128 v[182:185], v145 offset:17408
	ds_read_b128 v[186:189], v145 offset:18432
	ds_read_b128 v[190:193], v145 offset:19456
	ds_read_b128 v[194:197], v145 offset:20480
	ds_read_b128 v[212:215], v145 offset:21504
	ds_read_b128 v[216:219], v145 offset:22528
	ds_read_b128 v[220:223], v145 offset:23552
	global_load_lds_dwordx4 v[198:199], off
	s_add_i32 m0, s55, 0x2000
	s_add_u32 s56, s36, 0x20000
	v_lshl_add_u64 v[204:205], s[36:37], 0, v[132:133]
	s_addc_u32 s57, s37, 0
	s_add_i32 s55, s58, s15
	global_load_lds_dwordx4 v[204:205], off
	v_lshl_add_u64 v[206:207], s[56:57], 0, v[136:137]
	s_mov_b32 m0, s55
	v_lshl_add_u64 v[224:225], s[38:39], 0, v[134:135]
	global_load_lds_dwordx4 v[206:207], off
	v_lshl_add_u64 v[206:207], s[56:57], 0, v[132:133]
	s_add_i32 m0, s55, 0x2000
	s_nop 0
	global_load_lds_dwordx4 v[206:207], off
	v_lshl_add_u64 v[206:207], s[38:39], 0, v[138:139]
	s_mov_b32 m0, s40
	s_nop 0
	global_load_lds_dwordx4 v[206:207], off
	s_mov_b32 m0, s41
	s_nop 0
	global_load_lds_dwordx4 v[224:225], off
	s_waitcnt vmcnt(8)
	s_waitcnt lgkmcnt(0)
	s_barrier
	s_nop 0
	s_waitcnt lgkmcnt(0)
	v_mfma_f32_16x16x32_bf16 v[64:67], v[146:149], v[178:181], v[64:67]
	v_mfma_f32_16x16x32_bf16 v[60:63], v[154:157], v[178:181], v[60:63]
	v_mfma_f32_16x16x32_bf16 v[56:59], v[146:149], v[186:189], v[56:59]
	v_mfma_f32_16x16x32_bf16 v[52:55], v[154:157], v[186:189], v[52:55]
	v_mfma_f32_16x16x32_bf16 v[40:43], v[146:149], v[194:197], v[40:43]
	v_mfma_f32_16x16x32_bf16 v[36:39], v[154:157], v[194:197], v[36:39]
	v_mfma_f32_16x16x32_bf16 v[24:27], v[146:149], v[216:219], v[24:27]
	v_mfma_f32_16x16x32_bf16 v[20:23], v[154:157], v[216:219], v[20:23]
	v_mfma_f32_16x16x32_bf16 v[64:67], v[150:153], v[182:185], v[64:67]
	v_mfma_f32_16x16x32_bf16 v[60:63], v[158:161], v[182:185], v[60:63]
	v_mfma_f32_16x16x32_bf16 v[56:59], v[150:153], v[190:193], v[56:59]
	v_mfma_f32_16x16x32_bf16 v[52:55], v[158:161], v[190:193], v[52:55]
	v_mfma_f32_16x16x32_bf16 v[40:43], v[150:153], v[212:215], v[40:43]
	v_mfma_f32_16x16x32_bf16 v[36:39], v[158:161], v[212:215], v[36:39]
	v_mfma_f32_16x16x32_bf16 v[24:27], v[150:153], v[220:223], v[24:27]
	v_mfma_f32_16x16x32_bf16 v[20:23], v[158:161], v[220:223], v[20:23]
	s_nop 0
	s_nop 0
	v_mfma_f32_16x16x32_bf16 v[48:51], v[162:165], v[178:181], v[48:51]
	v_mfma_f32_16x16x32_bf16 v[44:47], v[170:173], v[178:181], v[44:47]
	v_mfma_f32_16x16x32_bf16 v[32:35], v[162:165], v[186:189], v[32:35]
	v_mfma_f32_16x16x32_bf16 v[28:31], v[170:173], v[186:189], v[28:31]
	v_mfma_f32_16x16x32_bf16 v[16:19], v[162:165], v[194:197], v[16:19]
	v_mfma_f32_16x16x32_bf16 v[12:15], v[170:173], v[194:197], v[12:15]
	v_mfma_f32_16x16x32_bf16 v[8:11], v[162:165], v[216:219], v[8:11]
	v_mfma_f32_16x16x32_bf16 v[4:7], v[170:173], v[216:219], v[4:7]
	v_mfma_f32_16x16x32_bf16 v[48:51], v[166:169], v[182:185], v[48:51]
	v_mfma_f32_16x16x32_bf16 v[44:47], v[174:177], v[182:185], v[44:47]
	v_mfma_f32_16x16x32_bf16 v[32:35], v[166:169], v[190:193], v[32:35]
	v_mfma_f32_16x16x32_bf16 v[28:31], v[174:177], v[190:193], v[28:31]
	v_mfma_f32_16x16x32_bf16 v[16:19], v[166:169], v[212:215], v[16:19]
	v_mfma_f32_16x16x32_bf16 v[12:15], v[174:177], v[212:215], v[12:15]
	v_mfma_f32_16x16x32_bf16 v[8:11], v[166:169], v[220:223], v[8:11]
	v_mfma_f32_16x16x32_bf16 v[4:7], v[174:177], v[220:223], v[4:7]
	s_nop 0
	s_barrier
	s_add_i32 s55, 0, 0x18000
	v_add_u32_e32 v2, s55, v144
	s_add_i32 s56, 0, 0x1c000
	ds_read_b128 v[146:149], v2
	ds_read_b128 v[150:153], v2 offset:1024
	ds_read_b128 v[154:157], v2 offset:2048
	ds_read_b128 v[158:161], v2 offset:3072
	v_add_u32_e32 v2, s56, v144
	ds_read_b128 v[162:165], v2
	ds_read_b128 v[166:169], v2 offset:1024
	ds_read_b128 v[170:173], v2 offset:2048
	ds_read_b128 v[174:177], v2 offset:3072
	s_add_u32 s38, s38, 0x20000
	s_addc_u32 s39, s39, 0
	s_mov_b32 m0, s44
	v_lshl_add_u64 v[226:227], s[38:39], 0, v[138:139]
	ds_read_b128 v[178:181], v145 offset:32768
	ds_read_b128 v[182:185], v145 offset:33792
	ds_read_b128 v[186:189], v145 offset:34816
	ds_read_b128 v[190:193], v145 offset:35840
	ds_read_b128 v[194:197], v145 offset:36864
	ds_read_b128 v[212:215], v145 offset:37888
	ds_read_b128 v[216:219], v145 offset:38912
	ds_read_b128 v[220:223], v145 offset:39936
	global_load_lds_dwordx4 v[226:227], off
	v_lshl_add_u64 v[226:227], s[38:39], 0, v[134:135]
	s_mov_b32 m0, s45
	s_nop 0
	global_load_lds_dwordx4 v[226:227], off
	s_waitcnt vmcnt(8)
	s_waitcnt lgkmcnt(0)
	s_barrier
	s_nop 0
	s_waitcnt lgkmcnt(0)
	v_mfma_f32_16x16x32_bf16 v[128:131], v[146:149], v[178:181], v[128:131]
	v_mfma_f32_16x16x32_bf16 v[124:127], v[154:157], v[178:181], v[124:127]
	v_mfma_f32_16x16x32_bf16 v[120:123], v[146:149], v[186:189], v[120:123]
	v_mfma_f32_16x16x32_bf16 v[116:119], v[154:157], v[186:189], v[116:119]
	v_mfma_f32_16x16x32_bf16 v[104:107], v[146:149], v[194:197], v[104:107]
	v_mfma_f32_16x16x32_bf16 v[100:103], v[154:157], v[194:197], v[100:103]
	v_mfma_f32_16x16x32_bf16 v[88:91], v[146:149], v[216:219], v[88:91]
	v_mfma_f32_16x16x32_bf16 v[84:87], v[154:157], v[216:219], v[84:87]
	v_mfma_f32_16x16x32_bf16 v[128:131], v[150:153], v[182:185], v[128:131]
	v_mfma_f32_16x16x32_bf16 v[124:127], v[158:161], v[182:185], v[124:127]
	v_mfma_f32_16x16x32_bf16 v[120:123], v[150:153], v[190:193], v[120:123]
	v_mfma_f32_16x16x32_bf16 v[116:119], v[158:161], v[190:193], v[116:119]
	v_mfma_f32_16x16x32_bf16 v[104:107], v[150:153], v[212:215], v[104:107]
	v_mfma_f32_16x16x32_bf16 v[100:103], v[158:161], v[212:215], v[100:103]
	v_mfma_f32_16x16x32_bf16 v[88:91], v[150:153], v[220:223], v[88:91]
	v_mfma_f32_16x16x32_bf16 v[84:87], v[158:161], v[220:223], v[84:87]
	s_nop 0
	s_nop 0
	v_mfma_f32_16x16x32_bf16 v[112:115], v[162:165], v[178:181], v[112:115]
	v_mfma_f32_16x16x32_bf16 v[108:111], v[170:173], v[178:181], v[108:111]
	v_mfma_f32_16x16x32_bf16 v[96:99], v[162:165], v[186:189], v[96:99]
	v_mfma_f32_16x16x32_bf16 v[92:95], v[170:173], v[186:189], v[92:95]
	v_mfma_f32_16x16x32_bf16 v[80:83], v[162:165], v[194:197], v[80:83]
	v_mfma_f32_16x16x32_bf16 v[76:79], v[170:173], v[194:197], v[76:79]
	v_mfma_f32_16x16x32_bf16 v[72:75], v[162:165], v[216:219], v[72:75]
	v_mfma_f32_16x16x32_bf16 v[68:71], v[170:173], v[216:219], v[68:71]
	v_mfma_f32_16x16x32_bf16 v[112:115], v[166:169], v[182:185], v[112:115]
	v_mfma_f32_16x16x32_bf16 v[108:111], v[174:177], v[182:185], v[108:111]
	v_mfma_f32_16x16x32_bf16 v[96:99], v[166:169], v[190:193], v[96:99]
	v_mfma_f32_16x16x32_bf16 v[92:95], v[174:177], v[190:193], v[92:95]
	v_mfma_f32_16x16x32_bf16 v[80:83], v[166:169], v[212:215], v[80:83]
	v_mfma_f32_16x16x32_bf16 v[76:79], v[174:177], v[212:215], v[76:79]
	v_mfma_f32_16x16x32_bf16 v[72:75], v[166:169], v[220:223], v[72:75]
	v_mfma_f32_16x16x32_bf16 v[68:71], v[174:177], v[220:223], v[68:71]
	s_nop 0
	s_barrier
	s_add_i32 s38, s55, s15
	v_lshl_add_u64 v[198:199], v[198:199], 0, s[94:95]
	s_mov_b32 m0, s38
	ds_read_b128 v[178:181], v145 offset:49152
	ds_read_b128 v[182:185], v145 offset:50176
	ds_read_b128 v[186:189], v145 offset:51200
	ds_read_b128 v[190:193], v145 offset:52224
	ds_read_b128 v[194:197], v145 offset:53248
	ds_read_b128 v[212:215], v145 offset:54272
	ds_read_b128 v[216:219], v145 offset:55296
	ds_read_b128 v[220:223], v145 offset:56320
	global_load_lds_dwordx4 v[198:199], off
	s_add_i32 m0, s38, 0x2000
	s_add_u32 s36, s36, 0x20080
	v_lshl_add_u64 v[198:199], v[204:205], 0, s[94:95]
	s_addc_u32 s37, s37, 0
	s_add_i32 s38, s56, s15
	global_load_lds_dwordx4 v[198:199], off
	v_lshl_add_u64 v[198:199], s[36:37], 0, v[136:137]
	s_mov_b32 m0, s38
	s_nop 0
	global_load_lds_dwordx4 v[198:199], off
	v_lshl_add_u64 v[198:199], s[36:37], 0, v[132:133]
	s_add_i32 m0, s38, 0x2000
	s_nop 0
	global_load_lds_dwordx4 v[198:199], off
	v_lshl_add_u64 v[198:199], v[206:207], 0, s[94:95]
	s_mov_b32 m0, s46
	s_nop 0
	global_load_lds_dwordx4 v[198:199], off
	v_lshl_add_u64 v[198:199], v[224:225], 0, s[94:95]
	s_mov_b32 m0, s47
	s_nop 0
	global_load_lds_dwordx4 v[198:199], off
	s_waitcnt vmcnt(8)
	s_waitcnt lgkmcnt(0)
	s_barrier
	s_nop 0
	s_waitcnt lgkmcnt(0)
	v_mfma_f32_16x16x32_bf16 v[64:67], v[146:149], v[178:181], v[64:67]
	v_mfma_f32_16x16x32_bf16 v[60:63], v[154:157], v[178:181], v[60:63]
	v_mfma_f32_16x16x32_bf16 v[56:59], v[146:149], v[186:189], v[56:59]
	v_mfma_f32_16x16x32_bf16 v[52:55], v[154:157], v[186:189], v[52:55]
	v_mfma_f32_16x16x32_bf16 v[40:43], v[146:149], v[194:197], v[40:43]
	v_mfma_f32_16x16x32_bf16 v[36:39], v[154:157], v[194:197], v[36:39]
	v_mfma_f32_16x16x32_bf16 v[24:27], v[146:149], v[216:219], v[24:27]
	v_mfma_f32_16x16x32_bf16 v[20:23], v[154:157], v[216:219], v[20:23]
	v_mfma_f32_16x16x32_bf16 v[64:67], v[150:153], v[182:185], v[64:67]
	v_mfma_f32_16x16x32_bf16 v[60:63], v[158:161], v[182:185], v[60:63]
	v_mfma_f32_16x16x32_bf16 v[56:59], v[150:153], v[190:193], v[56:59]
	v_mfma_f32_16x16x32_bf16 v[52:55], v[158:161], v[190:193], v[52:55]
	v_mfma_f32_16x16x32_bf16 v[40:43], v[150:153], v[212:215], v[40:43]
	v_mfma_f32_16x16x32_bf16 v[36:39], v[158:161], v[212:215], v[36:39]
	v_mfma_f32_16x16x32_bf16 v[24:27], v[150:153], v[220:223], v[24:27]
	v_mfma_f32_16x16x32_bf16 v[20:23], v[158:161], v[220:223], v[20:23]
	s_nop 0
	s_nop 0
	v_mfma_f32_16x16x32_bf16 v[48:51], v[162:165], v[178:181], v[48:51]
	v_mfma_f32_16x16x32_bf16 v[44:47], v[170:173], v[178:181], v[44:47]
	v_mfma_f32_16x16x32_bf16 v[32:35], v[162:165], v[186:189], v[32:35]
	v_mfma_f32_16x16x32_bf16 v[28:31], v[170:173], v[186:189], v[28:31]
	v_mfma_f32_16x16x32_bf16 v[16:19], v[162:165], v[194:197], v[16:19]
	v_mfma_f32_16x16x32_bf16 v[12:15], v[170:173], v[194:197], v[12:15]
	v_mfma_f32_16x16x32_bf16 v[8:11], v[162:165], v[216:219], v[8:11]
	v_mfma_f32_16x16x32_bf16 v[4:7], v[170:173], v[216:219], v[4:7]
	v_mfma_f32_16x16x32_bf16 v[48:51], v[166:169], v[182:185], v[48:51]
	v_mfma_f32_16x16x32_bf16 v[44:47], v[174:177], v[182:185], v[44:47]
	v_mfma_f32_16x16x32_bf16 v[32:35], v[166:169], v[190:193], v[32:35]
	v_mfma_f32_16x16x32_bf16 v[28:31], v[174:177], v[190:193], v[28:31]
	v_mfma_f32_16x16x32_bf16 v[16:19], v[166:169], v[212:215], v[16:19]
	v_mfma_f32_16x16x32_bf16 v[12:15], v[174:177], v[212:215], v[12:15]
	v_mfma_f32_16x16x32_bf16 v[8:11], v[166:169], v[220:223], v[8:11]
	v_mfma_f32_16x16x32_bf16 v[4:7], v[174:177], v[220:223], v[4:7]
	s_nop 0
	s_barrier
	s_add_i32 s54, s54, 2
	s_add_u32 s34, s34, 0x100
	s_addc_u32 s35, s35, 0
	s_add_u32 s52, s52, 0x100
	s_addc_u32 s53, s53, 0
	s_cmp_gt_u32 s54, 5
	s_cbranch_scc0 .LBB0_655
	s_and_b64 vcc, exec, s[20:21]
	s_cbranch_vccz .LBB0_658
	s_barrier

.LBB0_673:
	s_add_u32 s46, s44, 0xfffe0080
	s_addc_u32 s47, s45, -1
	s_add_i32 s59, 0, 0x10000
	s_cmp_eq_u32 s58, 4
	s_cselect_b32 s49, s29, s47
	s_cselect_b32 s48, s37, s46
	v_add_u32_e32 v2, s59, v148
	s_cselect_b32 s47, s27, s57
	s_cselect_b32 s46, s39, s56
	s_add_i32 s61, 0, 0x14000
	ds_read_b128 v[144:147], v2
	ds_read_b128 v[150:153], v2 offset:1024
	ds_read_b128 v[154:157], v2 offset:2048
	ds_read_b128 v[158:161], v2 offset:3072
	v_add_u32_e32 v2, s61, v148
	ds_read_b128 v[162:165], v2
	ds_read_b128 v[166:169], v2 offset:1024
	ds_read_b128 v[170:173], v2 offset:2048
	ds_read_b128 v[174:177], v2 offset:3072
	v_lshl_add_u64 v[198:199], s[44:45], 0, v[140:141]
	s_add_i32 m0, s33, 0xc000
	ds_read_b128 v[178:181], v149
	ds_read_b128 v[182:185], v149 offset:1024
	ds_read_b128 v[186:189], v149 offset:2048
	ds_read_b128 v[190:193], v149 offset:3072
	ds_read_b128 v[194:197], v149 offset:4096
	ds_read_b128 v[212:215], v149 offset:5120
	ds_read_b128 v[216:219], v149 offset:6144
	ds_read_b128 v[220:223], v149 offset:7168
	global_load_lds_dwordx4 v[198:199], off
	v_lshl_add_u64 v[198:199], s[44:45], 0, v[142:143]
	s_add_i32 m0, s33, 0xe000
	s_nop 0
	global_load_lds_dwordx4 v[198:199], off
	s_waitcnt vmcnt(8)
	s_waitcnt lgkmcnt(0)
	s_barrier
	s_nop 0
	s_waitcnt lgkmcnt(0)
	v_mfma_f32_16x16x32_bf16 v[128:131], v[144:147], v[178:181], v[128:131]
	v_mfma_f32_16x16x32_bf16 v[124:127], v[154:157], v[178:181], v[124:127]
	v_mfma_f32_16x16x32_bf16 v[112:115], v[144:147], v[186:189], v[112:115]
	v_mfma_f32_16x16x32_bf16 v[108:111], v[154:157], v[186:189], v[108:111]
	v_mfma_f32_16x16x32_bf16 v[96:99], v[144:147], v[194:197], v[96:99]
	v_mfma_f32_16x16x32_bf16 v[92:95], v[154:157], v[194:197], v[92:95]
	v_mfma_f32_16x16x32_bf16 v[80:83], v[144:147], v[216:219], v[80:83]
	v_mfma_f32_16x16x32_bf16 v[76:79], v[154:157], v[216:219], v[76:79]
	v_mfma_f32_16x16x32_bf16 v[128:131], v[150:153], v[182:185], v[128:131]
	v_mfma_f32_16x16x32_bf16 v[124:127], v[158:161], v[182:185], v[124:127]
	v_mfma_f32_16x16x32_bf16 v[112:115], v[150:153], v[190:193], v[112:115]
	v_mfma_f32_16x16x32_bf16 v[108:111], v[158:161], v[190:193], v[108:111]
	v_mfma_f32_16x16x32_bf16 v[96:99], v[150:153], v[212:215], v[96:99]
	v_mfma_f32_16x16x32_bf16 v[92:95], v[158:161], v[212:215], v[92:95]
	v_mfma_f32_16x16x32_bf16 v[80:83], v[150:153], v[220:223], v[80:83]
	v_mfma_f32_16x16x32_bf16 v[76:79], v[158:161], v[220:223], v[76:79]
	s_nop 0
	s_nop 0
	v_mfma_f32_16x16x32_bf16 v[120:123], v[162:165], v[178:181], v[120:123]
	v_mfma_f32_16x16x32_bf16 v[116:119], v[170:173], v[178:181], v[116:119]
	v_mfma_f32_16x16x32_bf16 v[104:107], v[162:165], v[186:189], v[104:107]
	v_mfma_f32_16x16x32_bf16 v[100:103], v[170:173], v[186:189], v[100:103]
	v_mfma_f32_16x16x32_bf16 v[88:91], v[162:165], v[194:197], v[88:91]
	v_mfma_f32_16x16x32_bf16 v[84:87], v[170:173], v[194:197], v[84:87]
	v_mfma_f32_16x16x32_bf16 v[72:75], v[162:165], v[216:219], v[72:75]
	v_mfma_f32_16x16x32_bf16 v[68:71], v[170:173], v[216:219], v[68:71]
	v_mfma_f32_16x16x32_bf16 v[120:123], v[166:169], v[182:185], v[120:123]
	v_mfma_f32_16x16x32_bf16 v[116:119], v[174:177], v[182:185], v[116:119]
	v_mfma_f32_16x16x32_bf16 v[104:107], v[166:169], v[190:193], v[104:107]
	v_mfma_f32_16x16x32_bf16 v[100:103], v[174:177], v[190:193], v[100:103]
	v_mfma_f32_16x16x32_bf16 v[88:91], v[166:169], v[212:215], v[88:91]
	v_mfma_f32_16x16x32_bf16 v[84:87], v[174:177], v[212:215], v[84:87]
	v_mfma_f32_16x16x32_bf16 v[72:75], v[166:169], v[220:223], v[72:75]
	v_mfma_f32_16x16x32_bf16 v[68:71], v[174:177], v[220:223], v[68:71]
	s_nop 0
	s_barrier
	s_add_i32 s59, s59, s15
	v_lshl_add_u64 v[198:199], s[46:47], 0, v[134:135]
	s_mov_b32 m0, s59
	ds_read_b128 v[178:181], v149 offset:16384
	ds_read_b128 v[182:185], v149 offset:17408
	ds_read_b128 v[186:189], v149 offset:18432
	ds_read_b128 v[190:193], v149 offset:19456
	ds_read_b128 v[194:197], v149 offset:20480
	ds_read_b128 v[212:215], v149 offset:21504
	ds_read_b128 v[216:219], v149 offset:22528
	ds_read_b128 v[220:223], v149 offset:23552
	global_load_lds_dwordx4 v[198:199], off
	s_add_i32 m0, s59, 0x2000
	s_add_u32 s62, s46, 0x20000
	v_lshl_add_u64 v[204:205], s[46:47], 0, v[138:139]
	s_addc_u32 s63, s47, 0
	s_add_i32 s59, s61, s15
	global_load_lds_dwordx4 v[204:205], off
	v_lshl_add_u64 v[206:207], s[62:63], 0, v[134:135]
	s_mov_b32 m0, s59
	v_lshl_add_u64 v[224:225], s[48:49], 0, v[136:137]
	global_load_lds_dwordx4 v[206:207], off
	v_lshl_add_u64 v[206:207], s[62:63], 0, v[138:139]
	s_add_i32 m0, s59, 0x2000
	s_nop 0
	global_load_lds_dwordx4 v[206:207], off
	v_lshl_add_u64 v[206:207], s[48:49], 0, v[132:133]
	s_mov_b32 m0, s33
	s_nop 0
	global_load_lds_dwordx4 v[206:207], off
	s_mov_b32 m0, s40
	s_nop 0
	global_load_lds_dwordx4 v[224:225], off
	s_waitcnt vmcnt(8)
	s_waitcnt lgkmcnt(0)
	s_barrier
	s_nop 0
	s_waitcnt lgkmcnt(0)
	v_mfma_f32_16x16x32_bf16 v[64:67], v[144:147], v[178:181], v[64:67]
	v_mfma_f32_16x16x32_bf16 v[60:63], v[154:157], v[178:181], v[60:63]
	v_mfma_f32_16x16x32_bf16 v[48:51], v[144:147], v[186:189], v[48:51]
	v_mfma_f32_16x16x32_bf16 v[44:47], v[154:157], v[186:189], v[44:47]
	v_mfma_f32_16x16x32_bf16 v[32:35], v[144:147], v[194:197], v[32:35]
	v_mfma_f32_16x16x32_bf16 v[28:31], v[154:157], v[194:197], v[28:31]
	v_mfma_f32_16x16x32_bf16 v[16:19], v[144:147], v[216:219], v[16:19]
	v_mfma_f32_16x16x32_bf16 v[12:15], v[154:157], v[216:219], v[12:15]
	v_mfma_f32_16x16x32_bf16 v[64:67], v[150:153], v[182:185], v[64:67]
	v_mfma_f32_16x16x32_bf16 v[60:63], v[158:161], v[182:185], v[60:63]
	v_mfma_f32_16x16x32_bf16 v[48:51], v[150:153], v[190:193], v[48:51]
	v_mfma_f32_16x16x32_bf16 v[44:47], v[158:161], v[190:193], v[44:47]
	v_mfma_f32_16x16x32_bf16 v[32:35], v[150:153], v[212:215], v[32:35]
	v_mfma_f32_16x16x32_bf16 v[28:31], v[158:161], v[212:215], v[28:31]
	v_mfma_f32_16x16x32_bf16 v[16:19], v[150:153], v[220:223], v[16:19]
	v_mfma_f32_16x16x32_bf16 v[12:15], v[158:161], v[220:223], v[12:15]
	s_nop 0
	s_nop 0
	v_mfma_f32_16x16x32_bf16 v[56:59], v[162:165], v[178:181], v[56:59]
	v_mfma_f32_16x16x32_bf16 v[52:55], v[170:173], v[178:181], v[52:55]
	v_mfma_f32_16x16x32_bf16 v[40:43], v[162:165], v[186:189], v[40:43]
	v_mfma_f32_16x16x32_bf16 v[36:39], v[170:173], v[186:189], v[36:39]
	v_mfma_f32_16x16x32_bf16 v[24:27], v[162:165], v[194:197], v[24:27]
	v_mfma_f32_16x16x32_bf16 v[20:23], v[170:173], v[194:197], v[20:23]
	v_mfma_f32_16x16x32_bf16 v[8:11], v[162:165], v[216:219], v[8:11]
	v_mfma_f32_16x16x32_bf16 v[4:7], v[170:173], v[216:219], v[4:7]
	v_mfma_f32_16x16x32_bf16 v[56:59], v[166:169], v[182:185], v[56:59]
	v_mfma_f32_16x16x32_bf16 v[52:55], v[174:177], v[182:185], v[52:55]
	v_mfma_f32_16x16x32_bf16 v[40:43], v[166:169], v[190:193], v[40:43]
	v_mfma_f32_16x16x32_bf16 v[36:39], v[174:177], v[190:193], v[36:39]
	v_mfma_f32_16x16x32_bf16 v[24:27], v[166:169], v[212:215], v[24:27]
	v_mfma_f32_16x16x32_bf16 v[20:23], v[174:177], v[212:215], v[20:23]
	v_mfma_f32_16x16x32_bf16 v[8:11], v[166:169], v[220:223], v[8:11]
	v_mfma_f32_16x16x32_bf16 v[4:7], v[174:177], v[220:223], v[4:7]
	s_nop 0
	s_barrier
	s_add_i32 s59, 0, 0x18000
	v_add_u32_e32 v2, s59, v148
	s_add_i32 s61, 0, 0x1c000
	ds_read_b128 v[144:147], v2
	ds_read_b128 v[150:153], v2 offset:1024
	ds_read_b128 v[154:157], v2 offset:2048
	ds_read_b128 v[158:161], v2 offset:3072
	v_add_u32_e32 v2, s61, v148
	ds_read_b128 v[162:165], v2
	ds_read_b128 v[166:169], v2 offset:1024
	ds_read_b128 v[170:173], v2 offset:2048
	ds_read_b128 v[174:177], v2 offset:3072
	s_add_u32 s48, s48, 0x20000
	s_addc_u32 s49, s49, 0
	s_mov_b32 m0, s41
	v_lshl_add_u64 v[226:227], s[48:49], 0, v[132:133]
	ds_read_b128 v[178:181], v149 offset:32768
	ds_read_b128 v[182:185], v149 offset:33792
	ds_read_b128 v[186:189], v149 offset:34816
	ds_read_b128 v[190:193], v149 offset:35840
	ds_read_b128 v[194:197], v149 offset:36864
	ds_read_b128 v[212:215], v149 offset:37888
	ds_read_b128 v[216:219], v149 offset:38912
	ds_read_b128 v[220:223], v149 offset:39936
	global_load_lds_dwordx4 v[226:227], off
	v_lshl_add_u64 v[226:227], s[48:49], 0, v[136:137]
	s_mov_b32 m0, s50
	s_nop 0
	global_load_lds_dwordx4 v[226:227], off
	s_waitcnt vmcnt(8)
	s_waitcnt lgkmcnt(0)
	s_barrier
	s_nop 0
	s_waitcnt lgkmcnt(0)
	v_mfma_f32_16x16x32_bf16 v[128:131], v[144:147], v[178:181], v[128:131]
	v_mfma_f32_16x16x32_bf16 v[124:127], v[154:157], v[178:181], v[124:127]
	v_mfma_f32_16x16x32_bf16 v[112:115], v[144:147], v[186:189], v[112:115]
	v_mfma_f32_16x16x32_bf16 v[108:111], v[154:157], v[186:189], v[108:111]
	v_mfma_f32_16x16x32_bf16 v[96:99], v[144:147], v[194:197], v[96:99]
	v_mfma_f32_16x16x32_bf16 v[92:95], v[154:157], v[194:197], v[92:95]
	v_mfma_f32_16x16x32_bf16 v[80:83], v[144:147], v[216:219], v[80:83]
	v_mfma_f32_16x16x32_bf16 v[76:79], v[154:157], v[216:219], v[76:79]
	v_mfma_f32_16x16x32_bf16 v[128:131], v[150:153], v[182:185], v[128:131]
	v_mfma_f32_16x16x32_bf16 v[124:127], v[158:161], v[182:185], v[124:127]
	v_mfma_f32_16x16x32_bf16 v[112:115], v[150:153], v[190:193], v[112:115]
	v_mfma_f32_16x16x32_bf16 v[108:111], v[158:161], v[190:193], v[108:111]
	v_mfma_f32_16x16x32_bf16 v[96:99], v[150:153], v[212:215], v[96:99]
	v_mfma_f32_16x16x32_bf16 v[92:95], v[158:161], v[212:215], v[92:95]
	v_mfma_f32_16x16x32_bf16 v[80:83], v[150:153], v[220:223], v[80:83]
	v_mfma_f32_16x16x32_bf16 v[76:79], v[158:161], v[220:223], v[76:79]
	s_nop 0
	s_nop 0
	v_mfma_f32_16x16x32_bf16 v[120:123], v[162:165], v[178:181], v[120:123]
	v_mfma_f32_16x16x32_bf16 v[116:119], v[170:173], v[178:181], v[116:119]
	v_mfma_f32_16x16x32_bf16 v[104:107], v[162:165], v[186:189], v[104:107]
	v_mfma_f32_16x16x32_bf16 v[100:103], v[170:173], v[186:189], v[100:103]
	v_mfma_f32_16x16x32_bf16 v[88:91], v[162:165], v[194:197], v[88:91]
	v_mfma_f32_16x16x32_bf16 v[84:87], v[170:173], v[194:197], v[84:87]
	v_mfma_f32_16x16x32_bf16 v[72:75], v[162:165], v[216:219], v[72:75]
	v_mfma_f32_16x16x32_bf16 v[68:71], v[170:173], v[216:219], v[68:71]
	v_mfma_f32_16x16x32_bf16 v[120:123], v[166:169], v[182:185], v[120:123]
	v_mfma_f32_16x16x32_bf16 v[116:119], v[174:177], v[182:185], v[116:119]
	v_mfma_f32_16x16x32_bf16 v[104:107], v[166:169], v[190:193], v[104:107]
	v_mfma_f32_16x16x32_bf16 v[100:103], v[174:177], v[190:193], v[100:103]
	v_mfma_f32_16x16x32_bf16 v[88:91], v[166:169], v[212:215], v[88:91]
	v_mfma_f32_16x16x32_bf16 v[84:87], v[174:177], v[212:215], v[84:87]
	v_mfma_f32_16x16x32_bf16 v[72:75], v[166:169], v[220:223], v[72:75]
	v_mfma_f32_16x16x32_bf16 v[68:71], v[174:177], v[220:223], v[68:71]
	s_nop 0
	s_barrier
	s_add_i32 s48, s59, s15
	v_lshl_add_u64 v[198:199], v[198:199], 0, s[94:95]
	s_mov_b32 m0, s48
	ds_read_b128 v[178:181], v149 offset:49152
	ds_read_b128 v[182:185], v149 offset:50176
	ds_read_b128 v[186:189], v149 offset:51200
	ds_read_b128 v[190:193], v149 offset:52224
	ds_read_b128 v[194:197], v149 offset:53248
	ds_read_b128 v[212:215], v149 offset:54272
	ds_read_b128 v[216:219], v149 offset:55296
	ds_read_b128 v[220:223], v149 offset:56320
	global_load_lds_dwordx4 v[198:199], off
	s_add_i32 m0, s48, 0x2000
	s_add_u32 s46, s46, 0x20080
	v_lshl_add_u64 v[198:199], v[204:205], 0, s[94:95]
	s_addc_u32 s47, s47, 0
	s_add_i32 s48, s61, s15
	global_load_lds_dwordx4 v[198:199], off
	v_lshl_add_u64 v[198:199], s[46:47], 0, v[134:135]
	s_mov_b32 m0, s48
	s_nop 0
	global_load_lds_dwordx4 v[198:199], off
	v_lshl_add_u64 v[198:199], s[46:47], 0, v[138:139]
	s_add_i32 m0, s48, 0x2000
	s_nop 0
	global_load_lds_dwordx4 v[198:199], off
	v_lshl_add_u64 v[198:199], v[206:207], 0, s[94:95]
	s_mov_b32 m0, s51
	s_nop 0
	global_load_lds_dwordx4 v[198:199], off
	v_lshl_add_u64 v[198:199], v[224:225], 0, s[94:95]
	s_mov_b32 m0, s52
	s_nop 0
	global_load_lds_dwordx4 v[198:199], off
	s_waitcnt vmcnt(8)
	s_waitcnt lgkmcnt(0)
	s_barrier
	s_nop 0
	s_waitcnt lgkmcnt(0)
	v_mfma_f32_16x16x32_bf16 v[64:67], v[144:147], v[178:181], v[64:67]
	v_mfma_f32_16x16x32_bf16 v[60:63], v[154:157], v[178:181], v[60:63]
	v_mfma_f32_16x16x32_bf16 v[48:51], v[144:147], v[186:189], v[48:51]
	v_mfma_f32_16x16x32_bf16 v[44:47], v[154:157], v[186:189], v[44:47]
	v_mfma_f32_16x16x32_bf16 v[32:35], v[144:147], v[194:197], v[32:35]
	v_mfma_f32_16x16x32_bf16 v[28:31], v[154:157], v[194:197], v[28:31]
	v_mfma_f32_16x16x32_bf16 v[16:19], v[144:147], v[216:219], v[16:19]
	v_mfma_f32_16x16x32_bf16 v[12:15], v[154:157], v[216:219], v[12:15]
	v_mfma_f32_16x16x32_bf16 v[64:67], v[150:153], v[182:185], v[64:67]
	v_mfma_f32_16x16x32_bf16 v[60:63], v[158:161], v[182:185], v[60:63]
	v_mfma_f32_16x16x32_bf16 v[48:51], v[150:153], v[190:193], v[48:51]
	v_mfma_f32_16x16x32_bf16 v[44:47], v[158:161], v[190:193], v[44:47]
	v_mfma_f32_16x16x32_bf16 v[32:35], v[150:153], v[212:215], v[32:35]
	v_mfma_f32_16x16x32_bf16 v[28:31], v[158:161], v[212:215], v[28:31]
	v_mfma_f32_16x16x32_bf16 v[16:19], v[150:153], v[220:223], v[16:19]
	v_mfma_f32_16x16x32_bf16 v[12:15], v[158:161], v[220:223], v[12:15]
	s_nop 0
	s_nop 0
	v_mfma_f32_16x16x32_bf16 v[56:59], v[162:165], v[178:181], v[56:59]
	v_mfma_f32_16x16x32_bf16 v[52:55], v[170:173], v[178:181], v[52:55]
	v_mfma_f32_16x16x32_bf16 v[40:43], v[162:165], v[186:189], v[40:43]
	v_mfma_f32_16x16x32_bf16 v[36:39], v[170:173], v[186:189], v[36:39]
	v_mfma_f32_16x16x32_bf16 v[24:27], v[162:165], v[194:197], v[24:27]
	v_mfma_f32_16x16x32_bf16 v[20:23], v[170:173], v[194:197], v[20:23]
	v_mfma_f32_16x16x32_bf16 v[8:11], v[162:165], v[216:219], v[8:11]
	v_mfma_f32_16x16x32_bf16 v[4:7], v[170:173], v[216:219], v[4:7]
	v_mfma_f32_16x16x32_bf16 v[56:59], v[166:169], v[182:185], v[56:59]
	v_mfma_f32_16x16x32_bf16 v[52:55], v[174:177], v[182:185], v[52:55]
	v_mfma_f32_16x16x32_bf16 v[40:43], v[166:169], v[190:193], v[40:43]
	v_mfma_f32_16x16x32_bf16 v[36:39], v[174:177], v[190:193], v[36:39]
	v_mfma_f32_16x16x32_bf16 v[24:27], v[166:169], v[212:215], v[24:27]
	v_mfma_f32_16x16x32_bf16 v[20:23], v[174:177], v[212:215], v[20:23]
	v_mfma_f32_16x16x32_bf16 v[8:11], v[166:169], v[220:223], v[8:11]
	v_mfma_f32_16x16x32_bf16 v[4:7], v[174:177], v[220:223], v[4:7]
	s_nop 0
	s_barrier
	s_add_i32 s58, s58, 2
	s_add_u32 s44, s44, 0x100
	s_addc_u32 s45, s45, 0
	s_add_u32 s56, s56, 0x100
	s_addc_u32 s57, s57, 0
	s_cmp_gt_u32 s58, 5
	s_cbranch_scc0 .LBB0_673
	s_and_b64 vcc, exec, s[24:25]
	s_cbranch_vccz .LBB0_676
	s_barrier

.LBB0_705:
	s_add_u32 s30, s28, 0xfffc0080
	s_addc_u32 s31, s29, -1
	s_add_i32 s52, 0, 0x10000
	s_cmp_eq_u32 s51, 12
	s_cselect_b32 s35, s21, s31
	s_cselect_b32 s34, s47, s30
	v_add_u32_e32 v2, s52, v198
	s_cselect_b32 s31, s19, s50
	s_cselect_b32 s30, s48, s49
	s_add_i32 s54, 0, 0x14000
	ds_read_b128 v[124:127], v2
	ds_read_b128 v[128:131], v2 offset:1024
	ds_read_b128 v[132:135], v2 offset:2048
	ds_read_b128 v[136:139], v2 offset:3072
	v_add_u32_e32 v2, s54, v198
	ds_read_b128 v[148:151], v2
	ds_read_b128 v[152:155], v2 offset:1024
	ds_read_b128 v[156:159], v2 offset:2048
	ds_read_b128 v[160:163], v2 offset:3072
	v_lshl_add_u64 v[196:197], s[28:29], 0, v[184:185]
	s_add_i32 m0, s11, 0xc000
	ds_read_b128 v[164:167], v199
	ds_read_b128 v[168:171], v199 offset:1024
	ds_read_b128 v[172:175], v199 offset:2048
	ds_read_b128 v[188:191], v199 offset:3072
	ds_read_b128 v[192:195], v199 offset:4096
	ds_read_b128 v[212:215], v199 offset:5120
	ds_read_b128 v[216:219], v199 offset:6144
	ds_read_b128 v[220:223], v199 offset:7168
	global_load_lds_dwordx4 v[196:197], off
	v_lshl_add_u64 v[196:197], s[28:29], 0, v[186:187]
	s_add_i32 m0, s11, 0xe000
	s_nop 0
	global_load_lds_dwordx4 v[196:197], off
	s_waitcnt vmcnt(8)
	s_waitcnt lgkmcnt(0)
	s_barrier
	s_nop 0
	s_waitcnt lgkmcnt(0)
	v_mfma_f32_16x16x32_bf16 v[144:147], v[124:127], v[164:167], v[144:147]
	v_mfma_f32_16x16x32_bf16 v[140:143], v[132:135], v[164:167], v[140:143]
	v_mfma_f32_16x16x32_bf16 v[112:115], v[124:127], v[172:175], v[112:115]
	v_mfma_f32_16x16x32_bf16 v[108:111], v[132:135], v[172:175], v[108:111]
	v_mfma_f32_16x16x32_bf16 v[100:103], v[124:127], v[192:195], v[100:103]
	v_mfma_f32_16x16x32_bf16 v[92:95], v[132:135], v[192:195], v[92:95]
	v_mfma_f32_16x16x32_bf16 v[84:87], v[124:127], v[216:219], v[84:87]
	v_mfma_f32_16x16x32_bf16 v[76:79], v[132:135], v[216:219], v[76:79]
	v_mfma_f32_16x16x32_bf16 v[144:147], v[128:131], v[168:171], v[144:147]
	v_mfma_f32_16x16x32_bf16 v[140:143], v[136:139], v[168:171], v[140:143]
	v_mfma_f32_16x16x32_bf16 v[112:115], v[128:131], v[188:191], v[112:115]
	v_mfma_f32_16x16x32_bf16 v[108:111], v[136:139], v[188:191], v[108:111]
	v_mfma_f32_16x16x32_bf16 v[100:103], v[128:131], v[212:215], v[100:103]
	v_mfma_f32_16x16x32_bf16 v[92:95], v[136:139], v[212:215], v[92:95]
	v_mfma_f32_16x16x32_bf16 v[84:87], v[128:131], v[220:223], v[84:87]
	v_mfma_f32_16x16x32_bf16 v[76:79], v[136:139], v[220:223], v[76:79]
	s_nop 0
	s_nop 0
	v_mfma_f32_16x16x32_bf16 v[120:123], v[148:151], v[164:167], v[120:123]
	v_mfma_f32_16x16x32_bf16 v[116:119], v[156:159], v[164:167], v[116:119]
	v_mfma_f32_16x16x32_bf16 v[104:107], v[148:151], v[172:175], v[104:107]
	v_mfma_f32_16x16x32_bf16 v[96:99], v[156:159], v[172:175], v[96:99]
	v_mfma_f32_16x16x32_bf16 v[88:91], v[148:151], v[192:195], v[88:91]
	v_mfma_f32_16x16x32_bf16 v[80:83], v[156:159], v[192:195], v[80:83]
	v_mfma_f32_16x16x32_bf16 v[72:75], v[148:151], v[216:219], v[72:75]
	v_mfma_f32_16x16x32_bf16 v[68:71], v[156:159], v[216:219], v[68:71]
	v_mfma_f32_16x16x32_bf16 v[120:123], v[152:155], v[168:171], v[120:123]
	v_mfma_f32_16x16x32_bf16 v[116:119], v[160:163], v[168:171], v[116:119]
	v_mfma_f32_16x16x32_bf16 v[104:107], v[152:155], v[188:191], v[104:107]
	v_mfma_f32_16x16x32_bf16 v[96:99], v[160:163], v[188:191], v[96:99]
	v_mfma_f32_16x16x32_bf16 v[88:91], v[152:155], v[212:215], v[88:91]
	v_mfma_f32_16x16x32_bf16 v[80:83], v[160:163], v[212:215], v[80:83]
	v_mfma_f32_16x16x32_bf16 v[72:75], v[152:155], v[220:223], v[72:75]
	v_mfma_f32_16x16x32_bf16 v[68:71], v[160:163], v[220:223], v[68:71]
	s_nop 0
	s_barrier
	s_add_i32 s52, s52, s9
	v_lshl_add_u64 v[196:197], s[30:31], 0, v[180:181]
	s_mov_b32 m0, s52
	ds_read_b128 v[164:167], v199 offset:16384
	ds_read_b128 v[168:171], v199 offset:17408
	ds_read_b128 v[172:175], v199 offset:18432
	ds_read_b128 v[188:191], v199 offset:19456
	ds_read_b128 v[192:195], v199 offset:20480
	ds_read_b128 v[212:215], v199 offset:21504
	ds_read_b128 v[216:219], v199 offset:22528
	ds_read_b128 v[220:223], v199 offset:23552
	global_load_lds_dwordx4 v[196:197], off
	s_add_i32 m0, s52, 0x2000
	s_add_u32 s52, s30, 0x40000
	v_lshl_add_u64 v[204:205], s[30:31], 0, v[176:177]
	s_addc_u32 s53, s31, 0
	s_add_i32 s54, s54, s9
	global_load_lds_dwordx4 v[204:205], off
	v_lshl_add_u64 v[206:207], s[52:53], 0, v[180:181]
	s_mov_b32 m0, s54
	v_lshl_add_u64 v[224:225], s[34:35], 0, v[178:179]
	global_load_lds_dwordx4 v[206:207], off
	v_lshl_add_u64 v[206:207], s[52:53], 0, v[176:177]
	s_add_i32 m0, s54, 0x2000
	s_nop 0
	global_load_lds_dwordx4 v[206:207], off
	v_lshl_add_u64 v[206:207], s[34:35], 0, v[182:183]
	s_mov_b32 m0, s11
	s_nop 0
	global_load_lds_dwordx4 v[206:207], off
	s_mov_b32 m0, s15
	s_nop 0
	global_load_lds_dwordx4 v[224:225], off
	s_waitcnt vmcnt(8)
	s_waitcnt lgkmcnt(0)
	s_barrier
	s_nop 0
	s_waitcnt lgkmcnt(0)
	v_mfma_f32_16x16x32_bf16 v[64:67], v[124:127], v[164:167], v[64:67]
	v_mfma_f32_16x16x32_bf16 v[60:63], v[132:135], v[164:167], v[60:63]
	v_mfma_f32_16x16x32_bf16 v[52:55], v[124:127], v[172:175], v[52:55]
	v_mfma_f32_16x16x32_bf16 v[44:47], v[132:135], v[172:175], v[44:47]
	v_mfma_f32_16x16x32_bf16 v[36:39], v[124:127], v[192:195], v[36:39]
	v_mfma_f32_16x16x32_bf16 v[28:31], v[132:135], v[192:195], v[28:31]
	v_mfma_f32_16x16x32_bf16 v[20:23], v[124:127], v[216:219], v[20:23]
	v_mfma_f32_16x16x32_bf16 v[12:15], v[132:135], v[216:219], v[12:15]
	v_mfma_f32_16x16x32_bf16 v[64:67], v[128:131], v[168:171], v[64:67]
	v_mfma_f32_16x16x32_bf16 v[60:63], v[136:139], v[168:171], v[60:63]
	v_mfma_f32_16x16x32_bf16 v[52:55], v[128:131], v[188:191], v[52:55]
	v_mfma_f32_16x16x32_bf16 v[44:47], v[136:139], v[188:191], v[44:47]
	v_mfma_f32_16x16x32_bf16 v[36:39], v[128:131], v[212:215], v[36:39]
	v_mfma_f32_16x16x32_bf16 v[28:31], v[136:139], v[212:215], v[28:31]
	v_mfma_f32_16x16x32_bf16 v[20:23], v[128:131], v[220:223], v[20:23]
	v_mfma_f32_16x16x32_bf16 v[12:15], v[136:139], v[220:223], v[12:15]
	s_nop 0
	s_nop 0
	v_mfma_f32_16x16x32_bf16 v[56:59], v[148:151], v[164:167], v[56:59]
	v_mfma_f32_16x16x32_bf16 v[48:51], v[156:159], v[164:167], v[48:51]
	v_mfma_f32_16x16x32_bf16 v[40:43], v[148:151], v[172:175], v[40:43]
	v_mfma_f32_16x16x32_bf16 v[32:35], v[156:159], v[172:175], v[32:35]
	v_mfma_f32_16x16x32_bf16 v[24:27], v[148:151], v[192:195], v[24:27]
	v_mfma_f32_16x16x32_bf16 v[16:19], v[156:159], v[192:195], v[16:19]
	v_mfma_f32_16x16x32_bf16 v[8:11], v[148:151], v[216:219], v[8:11]
	v_mfma_f32_16x16x32_bf16 v[4:7], v[156:159], v[216:219], v[4:7]
	v_mfma_f32_16x16x32_bf16 v[56:59], v[152:155], v[168:171], v[56:59]
	v_mfma_f32_16x16x32_bf16 v[48:51], v[160:163], v[168:171], v[48:51]
	v_mfma_f32_16x16x32_bf16 v[40:43], v[152:155], v[188:191], v[40:43]
	v_mfma_f32_16x16x32_bf16 v[32:35], v[160:163], v[188:191], v[32:35]
	v_mfma_f32_16x16x32_bf16 v[24:27], v[152:155], v[212:215], v[24:27]
	v_mfma_f32_16x16x32_bf16 v[16:19], v[160:163], v[212:215], v[16:19]
	v_mfma_f32_16x16x32_bf16 v[8:11], v[152:155], v[220:223], v[8:11]
	v_mfma_f32_16x16x32_bf16 v[4:7], v[160:163], v[220:223], v[4:7]
	s_nop 0
	s_barrier
	s_add_i32 s52, 0, 0x18000
	v_add_u32_e32 v2, s52, v198
	s_add_i32 s53, 0, 0x1c000
	ds_read_b128 v[124:127], v2
	ds_read_b128 v[128:131], v2 offset:1024
	ds_read_b128 v[132:135], v2 offset:2048
	ds_read_b128 v[136:139], v2 offset:3072
	v_add_u32_e32 v2, s53, v198
	ds_read_b128 v[148:151], v2
	ds_read_b128 v[152:155], v2 offset:1024
	ds_read_b128 v[156:159], v2 offset:2048
	ds_read_b128 v[160:163], v2 offset:3072
	s_add_u32 s34, s34, 0x40000
	s_addc_u32 s35, s35, 0
	s_mov_b32 m0, s33
	v_lshl_add_u64 v[226:227], s[34:35], 0, v[182:183]
	ds_read_b128 v[164:167], v199 offset:32768
	ds_read_b128 v[168:171], v199 offset:33792
	ds_read_b128 v[172:175], v199 offset:34816
	ds_read_b128 v[188:191], v199 offset:35840
	ds_read_b128 v[192:195], v199 offset:36864
	ds_read_b128 v[212:215], v199 offset:37888
	ds_read_b128 v[216:219], v199 offset:38912
	ds_read_b128 v[220:223], v199 offset:39936
	global_load_lds_dwordx4 v[226:227], off
	v_lshl_add_u64 v[226:227], s[34:35], 0, v[178:179]
	s_mov_b32 m0, s36
	s_nop 0
	global_load_lds_dwordx4 v[226:227], off
	s_waitcnt vmcnt(8)
	s_waitcnt lgkmcnt(0)
	s_barrier
	s_nop 0
	s_waitcnt lgkmcnt(0)
	v_mfma_f32_16x16x32_bf16 v[144:147], v[124:127], v[164:167], v[144:147]
	v_mfma_f32_16x16x32_bf16 v[140:143], v[132:135], v[164:167], v[140:143]
	v_mfma_f32_16x16x32_bf16 v[112:115], v[124:127], v[172:175], v[112:115]
	v_mfma_f32_16x16x32_bf16 v[108:111], v[132:135], v[172:175], v[108:111]
	v_mfma_f32_16x16x32_bf16 v[100:103], v[124:127], v[192:195], v[100:103]
	v_mfma_f32_16x16x32_bf16 v[92:95], v[132:135], v[192:195], v[92:95]
	v_mfma_f32_16x16x32_bf16 v[84:87], v[124:127], v[216:219], v[84:87]
	v_mfma_f32_16x16x32_bf16 v[76:79], v[132:135], v[216:219], v[76:79]
	v_mfma_f32_16x16x32_bf16 v[144:147], v[128:131], v[168:171], v[144:147]
	v_mfma_f32_16x16x32_bf16 v[140:143], v[136:139], v[168:171], v[140:143]
	v_mfma_f32_16x16x32_bf16 v[112:115], v[128:131], v[188:191], v[112:115]
	v_mfma_f32_16x16x32_bf16 v[108:111], v[136:139], v[188:191], v[108:111]
	v_mfma_f32_16x16x32_bf16 v[100:103], v[128:131], v[212:215], v[100:103]
	v_mfma_f32_16x16x32_bf16 v[92:95], v[136:139], v[212:215], v[92:95]
	v_mfma_f32_16x16x32_bf16 v[84:87], v[128:131], v[220:223], v[84:87]
	v_mfma_f32_16x16x32_bf16 v[76:79], v[136:139], v[220:223], v[76:79]
	s_nop 0
	s_nop 0
	v_mfma_f32_16x16x32_bf16 v[120:123], v[148:151], v[164:167], v[120:123]
	v_mfma_f32_16x16x32_bf16 v[116:119], v[156:159], v[164:167], v[116:119]
	v_mfma_f32_16x16x32_bf16 v[104:107], v[148:151], v[172:175], v[104:107]
	v_mfma_f32_16x16x32_bf16 v[96:99], v[156:159], v[172:175], v[96:99]
	v_mfma_f32_16x16x32_bf16 v[88:91], v[148:151], v[192:195], v[88:91]
	v_mfma_f32_16x16x32_bf16 v[80:83], v[156:159], v[192:195], v[80:83]
	v_mfma_f32_16x16x32_bf16 v[72:75], v[148:151], v[216:219], v[72:75]
	v_mfma_f32_16x16x32_bf16 v[68:71], v[156:159], v[216:219], v[68:71]
	v_mfma_f32_16x16x32_bf16 v[120:123], v[152:155], v[168:171], v[120:123]
	v_mfma_f32_16x16x32_bf16 v[116:119], v[160:163], v[168:171], v[116:119]
	v_mfma_f32_16x16x32_bf16 v[104:107], v[152:155], v[188:191], v[104:107]
	v_mfma_f32_16x16x32_bf16 v[96:99], v[160:163], v[188:191], v[96:99]
	v_mfma_f32_16x16x32_bf16 v[88:91], v[152:155], v[212:215], v[88:91]
	v_mfma_f32_16x16x32_bf16 v[80:83], v[160:163], v[212:215], v[80:83]
	v_mfma_f32_16x16x32_bf16 v[72:75], v[152:155], v[220:223], v[72:75]
	v_mfma_f32_16x16x32_bf16 v[68:71], v[160:163], v[220:223], v[68:71]
	s_nop 0
	s_barrier
	s_add_i32 s34, s52, s9
	v_lshl_add_u64 v[196:197], v[196:197], 0, s[94:95]
	s_mov_b32 m0, s34
	ds_read_b128 v[164:167], v199 offset:49152
	ds_read_b128 v[168:171], v199 offset:50176
	ds_read_b128 v[172:175], v199 offset:51200
	ds_read_b128 v[188:191], v199 offset:52224
	ds_read_b128 v[192:195], v199 offset:53248
	ds_read_b128 v[212:215], v199 offset:54272
	ds_read_b128 v[216:219], v199 offset:55296
	ds_read_b128 v[220:223], v199 offset:56320
	global_load_lds_dwordx4 v[196:197], off
	s_add_i32 m0, s34, 0x2000
	s_add_u32 s30, s30, 0x40080
	v_lshl_add_u64 v[196:197], v[204:205], 0, s[94:95]
	s_addc_u32 s31, s31, 0
	s_add_i32 s34, s53, s9
	global_load_lds_dwordx4 v[196:197], off
	v_lshl_add_u64 v[196:197], s[30:31], 0, v[180:181]
	s_mov_b32 m0, s34
	s_nop 0
	global_load_lds_dwordx4 v[196:197], off
	v_lshl_add_u64 v[196:197], s[30:31], 0, v[176:177]
	s_add_i32 m0, s34, 0x2000
	s_nop 0
	global_load_lds_dwordx4 v[196:197], off
	v_lshl_add_u64 v[196:197], v[206:207], 0, s[94:95]
	s_mov_b32 m0, s41
	s_nop 0
	global_load_lds_dwordx4 v[196:197], off
	v_lshl_add_u64 v[196:197], v[224:225], 0, s[94:95]
	s_mov_b32 m0, s44
	s_nop 0
	global_load_lds_dwordx4 v[196:197], off
	s_waitcnt vmcnt(8)
	s_waitcnt lgkmcnt(0)
	s_barrier
	s_nop 0
	s_waitcnt lgkmcnt(0)
	v_mfma_f32_16x16x32_bf16 v[64:67], v[124:127], v[164:167], v[64:67]
	v_mfma_f32_16x16x32_bf16 v[60:63], v[132:135], v[164:167], v[60:63]
	v_mfma_f32_16x16x32_bf16 v[52:55], v[124:127], v[172:175], v[52:55]
	v_mfma_f32_16x16x32_bf16 v[44:47], v[132:135], v[172:175], v[44:47]
	v_mfma_f32_16x16x32_bf16 v[36:39], v[124:127], v[192:195], v[36:39]
	v_mfma_f32_16x16x32_bf16 v[28:31], v[132:135], v[192:195], v[28:31]
	v_mfma_f32_16x16x32_bf16 v[20:23], v[124:127], v[216:219], v[20:23]
	v_mfma_f32_16x16x32_bf16 v[12:15], v[132:135], v[216:219], v[12:15]
	v_mfma_f32_16x16x32_bf16 v[64:67], v[128:131], v[168:171], v[64:67]
	v_mfma_f32_16x16x32_bf16 v[60:63], v[136:139], v[168:171], v[60:63]
	v_mfma_f32_16x16x32_bf16 v[52:55], v[128:131], v[188:191], v[52:55]
	v_mfma_f32_16x16x32_bf16 v[44:47], v[136:139], v[188:191], v[44:47]
	v_mfma_f32_16x16x32_bf16 v[36:39], v[128:131], v[212:215], v[36:39]
	v_mfma_f32_16x16x32_bf16 v[28:31], v[136:139], v[212:215], v[28:31]
	v_mfma_f32_16x16x32_bf16 v[20:23], v[128:131], v[220:223], v[20:23]
	v_mfma_f32_16x16x32_bf16 v[12:15], v[136:139], v[220:223], v[12:15]
	s_nop 0
	s_nop 0
	v_mfma_f32_16x16x32_bf16 v[56:59], v[148:151], v[164:167], v[56:59]
	v_mfma_f32_16x16x32_bf16 v[48:51], v[156:159], v[164:167], v[48:51]
	v_mfma_f32_16x16x32_bf16 v[40:43], v[148:151], v[172:175], v[40:43]
	v_mfma_f32_16x16x32_bf16 v[32:35], v[156:159], v[172:175], v[32:35]
	v_mfma_f32_16x16x32_bf16 v[24:27], v[148:151], v[192:195], v[24:27]
	v_mfma_f32_16x16x32_bf16 v[16:19], v[156:159], v[192:195], v[16:19]
	v_mfma_f32_16x16x32_bf16 v[8:11], v[148:151], v[216:219], v[8:11]
	v_mfma_f32_16x16x32_bf16 v[4:7], v[156:159], v[216:219], v[4:7]
	v_mfma_f32_16x16x32_bf16 v[56:59], v[152:155], v[168:171], v[56:59]
	v_mfma_f32_16x16x32_bf16 v[48:51], v[160:163], v[168:171], v[48:51]
	v_mfma_f32_16x16x32_bf16 v[40:43], v[152:155], v[188:191], v[40:43]
	v_mfma_f32_16x16x32_bf16 v[32:35], v[160:163], v[188:191], v[32:35]
	v_mfma_f32_16x16x32_bf16 v[24:27], v[152:155], v[212:215], v[24:27]
	v_mfma_f32_16x16x32_bf16 v[16:19], v[160:163], v[212:215], v[16:19]
	v_mfma_f32_16x16x32_bf16 v[8:11], v[152:155], v[220:223], v[8:11]
	v_mfma_f32_16x16x32_bf16 v[4:7], v[160:163], v[220:223], v[4:7]
	s_nop 0
	s_barrier
	s_add_i32 s51, s51, 2
	s_add_u32 s28, s28, 0x100
	s_addc_u32 s29, s29, 0
	s_add_u32 s49, s49, 0x100
	s_addc_u32 s50, s50, 0
	s_cmp_gt_u32 s51, 13
	s_cbranch_scc0 .LBB0_705
	s_and_b64 vcc, exec, s[0:1]
	s_cbranch_vccz .LBB0_708
	s_barrier

.LBB0_1242:
	s_add_u32 s36, s34, 0xfff80080
	s_addc_u32 s37, s35, -1
	s_add_i32 s49, 0, 0x10000
	s_cmp_eq_u32 s29, 28
	s_cselect_b32 s39, s25, s37
	s_cselect_b32 s38, s24, s36
	v_add_u32_e32 v1, s49, v178
	s_cselect_b32 s37, s27, s23
	s_cselect_b32 s36, s26, s21
	s_add_i32 s52, 0, 0x14000
	ds_read_b128 v[132:135], v1
	ds_read_b128 v[136:139], v1 offset:1024
	ds_read_b128 v[140:143], v1 offset:2048
	ds_read_b128 v[144:147], v1 offset:3072
	v_add_u32_e32 v1, s52, v178
	ds_read_b128 v[148:151], v1
	ds_read_b128 v[152:155], v1 offset:1024
	ds_read_b128 v[168:171], v1 offset:2048
	ds_read_b128 v[172:175], v1 offset:3072
	v_lshl_add_u64 v[176:177], s[34:35], 0, v[164:165]
	s_add_i32 m0, s31, 0xc000
	ds_read_b128 v[180:183], v179
	ds_read_b128 v[184:187], v179 offset:1024
	ds_read_b128 v[188:191], v179 offset:2048
	ds_read_b128 v[192:195], v179 offset:3072
	ds_read_b128 v[196:199], v179 offset:4096
	ds_read_b128 v[204:207], v179 offset:5120
	ds_read_b128 v[212:215], v179 offset:6144
	ds_read_b128 v[216:219], v179 offset:7168
	global_load_lds_dwordx4 v[176:177], off
	v_lshl_add_u64 v[176:177], s[34:35], 0, v[166:167]
	s_add_i32 m0, s31, 0xe000
	s_nop 0
	global_load_lds_dwordx4 v[176:177], off
	s_waitcnt vmcnt(8)
	s_waitcnt lgkmcnt(0)
	s_barrier
	s_nop 0
	s_waitcnt lgkmcnt(0)
	v_mfma_f32_16x16x32_bf16 v[128:131], v[132:135], v[180:183], v[128:131]
	v_mfma_f32_16x16x32_bf16 v[124:127], v[140:143], v[180:183], v[124:127]
	v_mfma_f32_16x16x32_bf16 v[112:115], v[132:135], v[188:191], v[112:115]
	v_mfma_f32_16x16x32_bf16 v[108:111], v[140:143], v[188:191], v[108:111]
	v_mfma_f32_16x16x32_bf16 v[100:103], v[132:135], v[196:199], v[100:103]
	v_mfma_f32_16x16x32_bf16 v[92:95], v[140:143], v[196:199], v[92:95]
	v_mfma_f32_16x16x32_bf16 v[84:87], v[132:135], v[212:215], v[84:87]
	v_mfma_f32_16x16x32_bf16 v[76:79], v[140:143], v[212:215], v[76:79]
	v_mfma_f32_16x16x32_bf16 v[128:131], v[136:139], v[184:187], v[128:131]
	v_mfma_f32_16x16x32_bf16 v[124:127], v[144:147], v[184:187], v[124:127]
	v_mfma_f32_16x16x32_bf16 v[112:115], v[136:139], v[192:195], v[112:115]
	v_mfma_f32_16x16x32_bf16 v[108:111], v[144:147], v[192:195], v[108:111]
	v_mfma_f32_16x16x32_bf16 v[100:103], v[136:139], v[204:207], v[100:103]
	v_mfma_f32_16x16x32_bf16 v[92:95], v[144:147], v[204:207], v[92:95]
	v_mfma_f32_16x16x32_bf16 v[84:87], v[136:139], v[216:219], v[84:87]
	v_mfma_f32_16x16x32_bf16 v[76:79], v[144:147], v[216:219], v[76:79]
	s_nop 0
	s_nop 0
	v_mfma_f32_16x16x32_bf16 v[120:123], v[148:151], v[180:183], v[120:123]
	v_mfma_f32_16x16x32_bf16 v[116:119], v[168:171], v[180:183], v[116:119]
	v_mfma_f32_16x16x32_bf16 v[104:107], v[148:151], v[188:191], v[104:107]
	v_mfma_f32_16x16x32_bf16 v[96:99], v[168:171], v[188:191], v[96:99]
	v_mfma_f32_16x16x32_bf16 v[88:91], v[148:151], v[196:199], v[88:91]
	v_mfma_f32_16x16x32_bf16 v[80:83], v[168:171], v[196:199], v[80:83]
	v_mfma_f32_16x16x32_bf16 v[72:75], v[148:151], v[212:215], v[72:75]
	v_mfma_f32_16x16x32_bf16 v[68:71], v[168:171], v[212:215], v[68:71]
	v_mfma_f32_16x16x32_bf16 v[120:123], v[152:155], v[184:187], v[120:123]
	v_mfma_f32_16x16x32_bf16 v[116:119], v[172:175], v[184:187], v[116:119]
	v_mfma_f32_16x16x32_bf16 v[104:107], v[152:155], v[192:195], v[104:107]
	v_mfma_f32_16x16x32_bf16 v[96:99], v[172:175], v[192:195], v[96:99]
	v_mfma_f32_16x16x32_bf16 v[88:91], v[152:155], v[204:207], v[88:91]
	v_mfma_f32_16x16x32_bf16 v[80:83], v[172:175], v[204:207], v[80:83]
	v_mfma_f32_16x16x32_bf16 v[72:75], v[152:155], v[216:219], v[72:75]
	v_mfma_f32_16x16x32_bf16 v[68:71], v[172:175], v[216:219], v[68:71]
	s_nop 0
	s_barrier
	s_add_i32 s49, s49, s7
	v_lshl_add_u64 v[176:177], s[36:37], 0, v[160:161]
	s_mov_b32 m0, s49
	ds_read_b128 v[180:183], v179 offset:16384
	ds_read_b128 v[184:187], v179 offset:17408
	ds_read_b128 v[188:191], v179 offset:18432
	ds_read_b128 v[192:195], v179 offset:19456
	ds_read_b128 v[196:199], v179 offset:20480
	ds_read_b128 v[204:207], v179 offset:21504
	ds_read_b128 v[212:215], v179 offset:22528
	ds_read_b128 v[216:219], v179 offset:23552
	global_load_lds_dwordx4 v[176:177], off
	s_add_i32 m0, s49, 0x2000
	s_add_u32 s50, s36, 0x80000
	v_lshl_add_u64 v[220:221], s[36:37], 0, v[156:157]
	s_addc_u32 s51, s37, 0
	s_add_i32 s49, s52, s7
	global_load_lds_dwordx4 v[220:221], off
	v_lshl_add_u64 v[222:223], s[50:51], 0, v[160:161]
	s_mov_b32 m0, s49
	v_lshl_add_u64 v[224:225], s[38:39], 0, v[158:159]
	global_load_lds_dwordx4 v[222:223], off
	v_lshl_add_u64 v[222:223], s[50:51], 0, v[156:157]
	s_add_i32 m0, s49, 0x2000
	s_nop 0
	global_load_lds_dwordx4 v[222:223], off
	v_lshl_add_u64 v[222:223], s[38:39], 0, v[162:163]
	s_mov_b32 m0, s31
	s_nop 0
	global_load_lds_dwordx4 v[222:223], off
	s_mov_b32 m0, s33
	s_nop 0
	global_load_lds_dwordx4 v[224:225], off
	s_waitcnt vmcnt(8)
	s_waitcnt lgkmcnt(0)
	s_barrier
	s_nop 0
	s_waitcnt lgkmcnt(0)
	v_mfma_f32_16x16x32_bf16 v[64:67], v[132:135], v[180:183], v[64:67]
	v_mfma_f32_16x16x32_bf16 v[60:63], v[140:143], v[180:183], v[60:63]
	v_mfma_f32_16x16x32_bf16 v[52:55], v[132:135], v[188:191], v[52:55]
	v_mfma_f32_16x16x32_bf16 v[44:47], v[140:143], v[188:191], v[44:47]
	v_mfma_f32_16x16x32_bf16 v[36:39], v[132:135], v[196:199], v[36:39]
	v_mfma_f32_16x16x32_bf16 v[28:31], v[140:143], v[196:199], v[28:31]
	v_mfma_f32_16x16x32_bf16 v[20:23], v[132:135], v[212:215], v[20:23]
	v_mfma_f32_16x16x32_bf16 v[12:15], v[140:143], v[212:215], v[12:15]
	v_mfma_f32_16x16x32_bf16 v[64:67], v[136:139], v[184:187], v[64:67]
	v_mfma_f32_16x16x32_bf16 v[60:63], v[144:147], v[184:187], v[60:63]
	v_mfma_f32_16x16x32_bf16 v[52:55], v[136:139], v[192:195], v[52:55]
	v_mfma_f32_16x16x32_bf16 v[44:47], v[144:147], v[192:195], v[44:47]
	v_mfma_f32_16x16x32_bf16 v[36:39], v[136:139], v[204:207], v[36:39]
	v_mfma_f32_16x16x32_bf16 v[28:31], v[144:147], v[204:207], v[28:31]
	v_mfma_f32_16x16x32_bf16 v[20:23], v[136:139], v[216:219], v[20:23]
	v_mfma_f32_16x16x32_bf16 v[12:15], v[144:147], v[216:219], v[12:15]
	s_nop 0
	s_nop 0
	v_mfma_f32_16x16x32_bf16 v[56:59], v[148:151], v[180:183], v[56:59]
	v_mfma_f32_16x16x32_bf16 v[48:51], v[168:171], v[180:183], v[48:51]
	v_mfma_f32_16x16x32_bf16 v[40:43], v[148:151], v[188:191], v[40:43]
	v_mfma_f32_16x16x32_bf16 v[32:35], v[168:171], v[188:191], v[32:35]
	v_mfma_f32_16x16x32_bf16 v[24:27], v[148:151], v[196:199], v[24:27]
	v_mfma_f32_16x16x32_bf16 v[16:19], v[168:171], v[196:199], v[16:19]
	v_mfma_f32_16x16x32_bf16 v[8:11], v[148:151], v[212:215], v[8:11]
	v_mfma_f32_16x16x32_bf16 v[4:7], v[168:171], v[212:215], v[4:7]
	v_mfma_f32_16x16x32_bf16 v[56:59], v[152:155], v[184:187], v[56:59]
	v_mfma_f32_16x16x32_bf16 v[48:51], v[172:175], v[184:187], v[48:51]
	v_mfma_f32_16x16x32_bf16 v[40:43], v[152:155], v[192:195], v[40:43]
	v_mfma_f32_16x16x32_bf16 v[32:35], v[172:175], v[192:195], v[32:35]
	v_mfma_f32_16x16x32_bf16 v[24:27], v[152:155], v[204:207], v[24:27]
	v_mfma_f32_16x16x32_bf16 v[16:19], v[172:175], v[204:207], v[16:19]
	v_mfma_f32_16x16x32_bf16 v[8:11], v[152:155], v[216:219], v[8:11]
	v_mfma_f32_16x16x32_bf16 v[4:7], v[172:175], v[216:219], v[4:7]
	s_nop 0
	s_barrier
	s_add_i32 s49, 0, 0x18000
	v_add_u32_e32 v1, s49, v178
	s_add_i32 s50, 0, 0x1c000
	ds_read_b128 v[132:135], v1
	ds_read_b128 v[136:139], v1 offset:1024
	ds_read_b128 v[140:143], v1 offset:2048
	ds_read_b128 v[144:147], v1 offset:3072
	v_add_u32_e32 v1, s50, v178
	ds_read_b128 v[148:151], v1
	ds_read_b128 v[152:155], v1 offset:1024
	ds_read_b128 v[168:171], v1 offset:2048
	ds_read_b128 v[172:175], v1 offset:3072
	s_add_u32 s38, s38, 0x80000
	s_addc_u32 s39, s39, 0
	s_mov_b32 m0, s40
	v_lshl_add_u64 v[226:227], s[38:39], 0, v[162:163]
	ds_read_b128 v[180:183], v179 offset:32768
	ds_read_b128 v[184:187], v179 offset:33792
	ds_read_b128 v[188:191], v179 offset:34816
	ds_read_b128 v[192:195], v179 offset:35840
	ds_read_b128 v[196:199], v179 offset:36864
	ds_read_b128 v[204:207], v179 offset:37888
	ds_read_b128 v[212:215], v179 offset:38912
	ds_read_b128 v[216:219], v179 offset:39936
	global_load_lds_dwordx4 v[226:227], off
	v_lshl_add_u64 v[226:227], s[38:39], 0, v[158:159]
	s_mov_b32 m0, s41
	s_nop 0
	global_load_lds_dwordx4 v[226:227], off
	s_waitcnt vmcnt(8)
	s_waitcnt lgkmcnt(0)
	s_barrier
	s_nop 0
	s_waitcnt lgkmcnt(0)
	v_mfma_f32_16x16x32_bf16 v[128:131], v[132:135], v[180:183], v[128:131]
	v_mfma_f32_16x16x32_bf16 v[124:127], v[140:143], v[180:183], v[124:127]
	v_mfma_f32_16x16x32_bf16 v[112:115], v[132:135], v[188:191], v[112:115]
	v_mfma_f32_16x16x32_bf16 v[108:111], v[140:143], v[188:191], v[108:111]
	v_mfma_f32_16x16x32_bf16 v[100:103], v[132:135], v[196:199], v[100:103]
	v_mfma_f32_16x16x32_bf16 v[92:95], v[140:143], v[196:199], v[92:95]
	v_mfma_f32_16x16x32_bf16 v[84:87], v[132:135], v[212:215], v[84:87]
	v_mfma_f32_16x16x32_bf16 v[76:79], v[140:143], v[212:215], v[76:79]
	v_mfma_f32_16x16x32_bf16 v[128:131], v[136:139], v[184:187], v[128:131]
	v_mfma_f32_16x16x32_bf16 v[124:127], v[144:147], v[184:187], v[124:127]
	v_mfma_f32_16x16x32_bf16 v[112:115], v[136:139], v[192:195], v[112:115]
	v_mfma_f32_16x16x32_bf16 v[108:111], v[144:147], v[192:195], v[108:111]
	v_mfma_f32_16x16x32_bf16 v[100:103], v[136:139], v[204:207], v[100:103]
	v_mfma_f32_16x16x32_bf16 v[92:95], v[144:147], v[204:207], v[92:95]
	v_mfma_f32_16x16x32_bf16 v[84:87], v[136:139], v[216:219], v[84:87]
	v_mfma_f32_16x16x32_bf16 v[76:79], v[144:147], v[216:219], v[76:79]
	s_nop 0
	s_nop 0
	v_mfma_f32_16x16x32_bf16 v[120:123], v[148:151], v[180:183], v[120:123]
	v_mfma_f32_16x16x32_bf16 v[116:119], v[168:171], v[180:183], v[116:119]
	v_mfma_f32_16x16x32_bf16 v[104:107], v[148:151], v[188:191], v[104:107]
	v_mfma_f32_16x16x32_bf16 v[96:99], v[168:171], v[188:191], v[96:99]
	v_mfma_f32_16x16x32_bf16 v[88:91], v[148:151], v[196:199], v[88:91]
	v_mfma_f32_16x16x32_bf16 v[80:83], v[168:171], v[196:199], v[80:83]
	v_mfma_f32_16x16x32_bf16 v[72:75], v[148:151], v[212:215], v[72:75]
	v_mfma_f32_16x16x32_bf16 v[68:71], v[168:171], v[212:215], v[68:71]
	v_mfma_f32_16x16x32_bf16 v[120:123], v[152:155], v[184:187], v[120:123]
	v_mfma_f32_16x16x32_bf16 v[116:119], v[172:175], v[184:187], v[116:119]
	v_mfma_f32_16x16x32_bf16 v[104:107], v[152:155], v[192:195], v[104:107]
	v_mfma_f32_16x16x32_bf16 v[96:99], v[172:175], v[192:195], v[96:99]
	v_mfma_f32_16x16x32_bf16 v[88:91], v[152:155], v[204:207], v[88:91]
	v_mfma_f32_16x16x32_bf16 v[80:83], v[172:175], v[204:207], v[80:83]
	v_mfma_f32_16x16x32_bf16 v[72:75], v[152:155], v[216:219], v[72:75]
	v_mfma_f32_16x16x32_bf16 v[68:71], v[172:175], v[216:219], v[68:71]
	s_nop 0
	s_barrier
	s_add_i32 s38, s49, s7
	v_lshl_add_u64 v[176:177], v[176:177], 0, s[94:95]
	s_mov_b32 m0, s38
	ds_read_b128 v[180:183], v179 offset:49152
	ds_read_b128 v[184:187], v179 offset:50176
	ds_read_b128 v[188:191], v179 offset:51200
	ds_read_b128 v[192:195], v179 offset:52224
	ds_read_b128 v[196:199], v179 offset:53248
	ds_read_b128 v[204:207], v179 offset:54272
	ds_read_b128 v[212:215], v179 offset:55296
	ds_read_b128 v[216:219], v179 offset:56320
	global_load_lds_dwordx4 v[176:177], off
	s_add_i32 m0, s38, 0x2000
	s_add_u32 s36, s36, 0x80080
	v_lshl_add_u64 v[176:177], v[220:221], 0, s[94:95]
	s_addc_u32 s37, s37, 0
	s_add_i32 s38, s50, s7
	global_load_lds_dwordx4 v[176:177], off
	v_lshl_add_u64 v[176:177], s[36:37], 0, v[160:161]
	s_mov_b32 m0, s38
	s_nop 0
	global_load_lds_dwordx4 v[176:177], off
	v_lshl_add_u64 v[176:177], s[36:37], 0, v[156:157]
	s_add_i32 m0, s38, 0x2000
	s_nop 0
	global_load_lds_dwordx4 v[176:177], off
	v_lshl_add_u64 v[176:177], v[222:223], 0, s[94:95]
	s_mov_b32 m0, s44
	s_nop 0
	global_load_lds_dwordx4 v[176:177], off
	v_lshl_add_u64 v[176:177], v[224:225], 0, s[94:95]
	s_mov_b32 m0, s45
	s_nop 0
	global_load_lds_dwordx4 v[176:177], off
	s_waitcnt vmcnt(8)
	s_waitcnt lgkmcnt(0)
	s_barrier
	s_nop 0
	s_waitcnt lgkmcnt(0)
	v_mfma_f32_16x16x32_bf16 v[64:67], v[132:135], v[180:183], v[64:67]
	v_mfma_f32_16x16x32_bf16 v[60:63], v[140:143], v[180:183], v[60:63]
	v_mfma_f32_16x16x32_bf16 v[52:55], v[132:135], v[188:191], v[52:55]
	v_mfma_f32_16x16x32_bf16 v[44:47], v[140:143], v[188:191], v[44:47]
	v_mfma_f32_16x16x32_bf16 v[36:39], v[132:135], v[196:199], v[36:39]
	v_mfma_f32_16x16x32_bf16 v[28:31], v[140:143], v[196:199], v[28:31]
	v_mfma_f32_16x16x32_bf16 v[20:23], v[132:135], v[212:215], v[20:23]
	v_mfma_f32_16x16x32_bf16 v[12:15], v[140:143], v[212:215], v[12:15]
	v_mfma_f32_16x16x32_bf16 v[64:67], v[136:139], v[184:187], v[64:67]
	v_mfma_f32_16x16x32_bf16 v[60:63], v[144:147], v[184:187], v[60:63]
	v_mfma_f32_16x16x32_bf16 v[52:55], v[136:139], v[192:195], v[52:55]
	v_mfma_f32_16x16x32_bf16 v[44:47], v[144:147], v[192:195], v[44:47]
	v_mfma_f32_16x16x32_bf16 v[36:39], v[136:139], v[204:207], v[36:39]
	v_mfma_f32_16x16x32_bf16 v[28:31], v[144:147], v[204:207], v[28:31]
	v_mfma_f32_16x16x32_bf16 v[20:23], v[136:139], v[216:219], v[20:23]
	v_mfma_f32_16x16x32_bf16 v[12:15], v[144:147], v[216:219], v[12:15]
	s_nop 0
	s_nop 0
	v_mfma_f32_16x16x32_bf16 v[56:59], v[148:151], v[180:183], v[56:59]
	v_mfma_f32_16x16x32_bf16 v[48:51], v[168:171], v[180:183], v[48:51]
	v_mfma_f32_16x16x32_bf16 v[40:43], v[148:151], v[188:191], v[40:43]
	v_mfma_f32_16x16x32_bf16 v[32:35], v[168:171], v[188:191], v[32:35]
	v_mfma_f32_16x16x32_bf16 v[24:27], v[148:151], v[196:199], v[24:27]
	v_mfma_f32_16x16x32_bf16 v[16:19], v[168:171], v[196:199], v[16:19]
	v_mfma_f32_16x16x32_bf16 v[8:11], v[148:151], v[212:215], v[8:11]
	v_mfma_f32_16x16x32_bf16 v[4:7], v[168:171], v[212:215], v[4:7]
	v_mfma_f32_16x16x32_bf16 v[56:59], v[152:155], v[184:187], v[56:59]
	v_mfma_f32_16x16x32_bf16 v[48:51], v[172:175], v[184:187], v[48:51]
	v_mfma_f32_16x16x32_bf16 v[40:43], v[152:155], v[192:195], v[40:43]
	v_mfma_f32_16x16x32_bf16 v[32:35], v[172:175], v[192:195], v[32:35]
	v_mfma_f32_16x16x32_bf16 v[24:27], v[152:155], v[204:207], v[24:27]
	v_mfma_f32_16x16x32_bf16 v[16:19], v[172:175], v[204:207], v[16:19]
	v_mfma_f32_16x16x32_bf16 v[8:11], v[152:155], v[216:219], v[8:11]
	v_mfma_f32_16x16x32_bf16 v[4:7], v[172:175], v[216:219], v[4:7]
	s_nop 0
	s_barrier
	s_add_i32 s29, s29, 2
	s_add_u32 s34, s34, 0x100
	s_addc_u32 s35, s35, 0
	s_add_u32 s21, s21, 0x100
	s_addc_u32 s23, s23, 0
	s_cmp_gt_u32 s29, 29
	s_cbranch_scc0 .LBB0_1242
	s_and_b64 vcc, exec, s[18:19]
	s_cbranch_vccz .LBB0_1245
	s_barrier

.LBB0_1260:
	s_add_u32 s34, s30, 0xfffc0080
	s_addc_u32 s35, s31, -1
	s_add_i32 s49, 0, 0x10000
	s_cmp_eq_u32 s27, 12
	s_cselect_b32 s37, s23, s35
	s_cselect_b32 s36, s22, s34
	v_add_u32_e32 v1, s49, v178
	s_cselect_b32 s35, s25, s21
	s_cselect_b32 s34, s24, s19
	s_add_i32 s52, 0, 0x14000
	ds_read_b128 v[132:135], v1
	ds_read_b128 v[136:139], v1 offset:1024
	ds_read_b128 v[140:143], v1 offset:2048
	ds_read_b128 v[144:147], v1 offset:3072
	v_add_u32_e32 v1, s52, v178
	ds_read_b128 v[148:151], v1
	ds_read_b128 v[152:155], v1 offset:1024
	ds_read_b128 v[168:171], v1 offset:2048
	ds_read_b128 v[172:175], v1 offset:3072
	v_lshl_add_u64 v[176:177], s[30:31], 0, v[164:165]
	s_add_i32 m0, s29, 0xc000
	ds_read_b128 v[180:183], v179
	ds_read_b128 v[184:187], v179 offset:1024
	ds_read_b128 v[188:191], v179 offset:2048
	ds_read_b128 v[192:195], v179 offset:3072
	ds_read_b128 v[196:199], v179 offset:4096
	ds_read_b128 v[204:207], v179 offset:5120
	ds_read_b128 v[212:215], v179 offset:6144
	ds_read_b128 v[216:219], v179 offset:7168
	global_load_lds_dwordx4 v[176:177], off
	v_lshl_add_u64 v[176:177], s[30:31], 0, v[166:167]
	s_add_i32 m0, s29, 0xe000
	s_nop 0
	global_load_lds_dwordx4 v[176:177], off
	s_waitcnt vmcnt(8)
	s_waitcnt lgkmcnt(0)
	s_barrier
	s_nop 0
	s_waitcnt lgkmcnt(0)
	v_mfma_f32_16x16x32_bf16 v[128:131], v[132:135], v[180:183], v[128:131]
	v_mfma_f32_16x16x32_bf16 v[124:127], v[140:143], v[180:183], v[124:127]
	v_mfma_f32_16x16x32_bf16 v[112:115], v[132:135], v[188:191], v[112:115]
	v_mfma_f32_16x16x32_bf16 v[108:111], v[140:143], v[188:191], v[108:111]
	v_mfma_f32_16x16x32_bf16 v[100:103], v[132:135], v[196:199], v[100:103]
	v_mfma_f32_16x16x32_bf16 v[92:95], v[140:143], v[196:199], v[92:95]
	v_mfma_f32_16x16x32_bf16 v[84:87], v[132:135], v[212:215], v[84:87]
	v_mfma_f32_16x16x32_bf16 v[76:79], v[140:143], v[212:215], v[76:79]
	v_mfma_f32_16x16x32_bf16 v[128:131], v[136:139], v[184:187], v[128:131]
	v_mfma_f32_16x16x32_bf16 v[124:127], v[144:147], v[184:187], v[124:127]
	v_mfma_f32_16x16x32_bf16 v[112:115], v[136:139], v[192:195], v[112:115]
	v_mfma_f32_16x16x32_bf16 v[108:111], v[144:147], v[192:195], v[108:111]
	v_mfma_f32_16x16x32_bf16 v[100:103], v[136:139], v[204:207], v[100:103]
	v_mfma_f32_16x16x32_bf16 v[92:95], v[144:147], v[204:207], v[92:95]
	v_mfma_f32_16x16x32_bf16 v[84:87], v[136:139], v[216:219], v[84:87]
	v_mfma_f32_16x16x32_bf16 v[76:79], v[144:147], v[216:219], v[76:79]
	s_nop 0
	s_nop 0
	v_mfma_f32_16x16x32_bf16 v[120:123], v[148:151], v[180:183], v[120:123]
	v_mfma_f32_16x16x32_bf16 v[116:119], v[168:171], v[180:183], v[116:119]
	v_mfma_f32_16x16x32_bf16 v[104:107], v[148:151], v[188:191], v[104:107]
	v_mfma_f32_16x16x32_bf16 v[96:99], v[168:171], v[188:191], v[96:99]
	v_mfma_f32_16x16x32_bf16 v[88:91], v[148:151], v[196:199], v[88:91]
	v_mfma_f32_16x16x32_bf16 v[80:83], v[168:171], v[196:199], v[80:83]
	v_mfma_f32_16x16x32_bf16 v[72:75], v[148:151], v[212:215], v[72:75]
	v_mfma_f32_16x16x32_bf16 v[68:71], v[168:171], v[212:215], v[68:71]
	v_mfma_f32_16x16x32_bf16 v[120:123], v[152:155], v[184:187], v[120:123]
	v_mfma_f32_16x16x32_bf16 v[116:119], v[172:175], v[184:187], v[116:119]
	v_mfma_f32_16x16x32_bf16 v[104:107], v[152:155], v[192:195], v[104:107]
	v_mfma_f32_16x16x32_bf16 v[96:99], v[172:175], v[192:195], v[96:99]
	v_mfma_f32_16x16x32_bf16 v[88:91], v[152:155], v[204:207], v[88:91]
	v_mfma_f32_16x16x32_bf16 v[80:83], v[172:175], v[204:207], v[80:83]
	v_mfma_f32_16x16x32_bf16 v[72:75], v[152:155], v[216:219], v[72:75]
	v_mfma_f32_16x16x32_bf16 v[68:71], v[172:175], v[216:219], v[68:71]
	s_nop 0
	s_barrier
	s_add_i32 s49, s49, s7
	v_lshl_add_u64 v[176:177], s[34:35], 0, v[160:161]
	s_mov_b32 m0, s49
	ds_read_b128 v[180:183], v179 offset:16384
	ds_read_b128 v[184:187], v179 offset:17408
	ds_read_b128 v[188:191], v179 offset:18432
	ds_read_b128 v[192:195], v179 offset:19456
	ds_read_b128 v[196:199], v179 offset:20480
	ds_read_b128 v[204:207], v179 offset:21504
	ds_read_b128 v[212:215], v179 offset:22528
	ds_read_b128 v[216:219], v179 offset:23552
	global_load_lds_dwordx4 v[176:177], off
	s_add_i32 m0, s49, 0x2000
	s_add_u32 s50, s34, 0x40000
	v_lshl_add_u64 v[220:221], s[34:35], 0, v[156:157]
	s_addc_u32 s51, s35, 0
	s_add_i32 s49, s52, s7
	global_load_lds_dwordx4 v[220:221], off
	v_lshl_add_u64 v[222:223], s[50:51], 0, v[160:161]
	s_mov_b32 m0, s49
	v_lshl_add_u64 v[224:225], s[36:37], 0, v[158:159]
	global_load_lds_dwordx4 v[222:223], off
	v_lshl_add_u64 v[222:223], s[50:51], 0, v[156:157]
	s_add_i32 m0, s49, 0x2000
	s_nop 0
	global_load_lds_dwordx4 v[222:223], off
	v_lshl_add_u64 v[222:223], s[36:37], 0, v[162:163]
	s_mov_b32 m0, s29
	s_nop 0
	global_load_lds_dwordx4 v[222:223], off
	s_mov_b32 m0, s33
	s_nop 0
	global_load_lds_dwordx4 v[224:225], off
	s_waitcnt vmcnt(8)
	s_waitcnt lgkmcnt(0)
	s_barrier
	s_nop 0
	s_waitcnt lgkmcnt(0)
	v_mfma_f32_16x16x32_bf16 v[64:67], v[132:135], v[180:183], v[64:67]
	v_mfma_f32_16x16x32_bf16 v[60:63], v[140:143], v[180:183], v[60:63]
	v_mfma_f32_16x16x32_bf16 v[52:55], v[132:135], v[188:191], v[52:55]
	v_mfma_f32_16x16x32_bf16 v[44:47], v[140:143], v[188:191], v[44:47]
	v_mfma_f32_16x16x32_bf16 v[36:39], v[132:135], v[196:199], v[36:39]
	v_mfma_f32_16x16x32_bf16 v[28:31], v[140:143], v[196:199], v[28:31]
	v_mfma_f32_16x16x32_bf16 v[20:23], v[132:135], v[212:215], v[20:23]
	v_mfma_f32_16x16x32_bf16 v[12:15], v[140:143], v[212:215], v[12:15]
	v_mfma_f32_16x16x32_bf16 v[64:67], v[136:139], v[184:187], v[64:67]
	v_mfma_f32_16x16x32_bf16 v[60:63], v[144:147], v[184:187], v[60:63]
	v_mfma_f32_16x16x32_bf16 v[52:55], v[136:139], v[192:195], v[52:55]
	v_mfma_f32_16x16x32_bf16 v[44:47], v[144:147], v[192:195], v[44:47]
	v_mfma_f32_16x16x32_bf16 v[36:39], v[136:139], v[204:207], v[36:39]
	v_mfma_f32_16x16x32_bf16 v[28:31], v[144:147], v[204:207], v[28:31]
	v_mfma_f32_16x16x32_bf16 v[20:23], v[136:139], v[216:219], v[20:23]
	v_mfma_f32_16x16x32_bf16 v[12:15], v[144:147], v[216:219], v[12:15]
	s_nop 0
	s_nop 0
	v_mfma_f32_16x16x32_bf16 v[56:59], v[148:151], v[180:183], v[56:59]
	v_mfma_f32_16x16x32_bf16 v[48:51], v[168:171], v[180:183], v[48:51]
	v_mfma_f32_16x16x32_bf16 v[40:43], v[148:151], v[188:191], v[40:43]
	v_mfma_f32_16x16x32_bf16 v[32:35], v[168:171], v[188:191], v[32:35]
	v_mfma_f32_16x16x32_bf16 v[24:27], v[148:151], v[196:199], v[24:27]
	v_mfma_f32_16x16x32_bf16 v[16:19], v[168:171], v[196:199], v[16:19]
	v_mfma_f32_16x16x32_bf16 v[8:11], v[148:151], v[212:215], v[8:11]
	v_mfma_f32_16x16x32_bf16 v[4:7], v[168:171], v[212:215], v[4:7]
	v_mfma_f32_16x16x32_bf16 v[56:59], v[152:155], v[184:187], v[56:59]
	v_mfma_f32_16x16x32_bf16 v[48:51], v[172:175], v[184:187], v[48:51]
	v_mfma_f32_16x16x32_bf16 v[40:43], v[152:155], v[192:195], v[40:43]
	v_mfma_f32_16x16x32_bf16 v[32:35], v[172:175], v[192:195], v[32:35]
	v_mfma_f32_16x16x32_bf16 v[24:27], v[152:155], v[204:207], v[24:27]
	v_mfma_f32_16x16x32_bf16 v[16:19], v[172:175], v[204:207], v[16:19]
	v_mfma_f32_16x16x32_bf16 v[8:11], v[152:155], v[216:219], v[8:11]
	v_mfma_f32_16x16x32_bf16 v[4:7], v[172:175], v[216:219], v[4:7]
	s_nop 0
	s_barrier
	s_add_i32 s49, 0, 0x18000
	v_add_u32_e32 v1, s49, v178
	s_add_i32 s50, 0, 0x1c000
	ds_read_b128 v[132:135], v1
	ds_read_b128 v[136:139], v1 offset:1024
	ds_read_b128 v[140:143], v1 offset:2048
	ds_read_b128 v[144:147], v1 offset:3072
	v_add_u32_e32 v1, s50, v178
	ds_read_b128 v[148:151], v1
	ds_read_b128 v[152:155], v1 offset:1024
	ds_read_b128 v[168:171], v1 offset:2048
	ds_read_b128 v[172:175], v1 offset:3072
	s_add_u32 s36, s36, 0x40000
	s_addc_u32 s37, s37, 0
	s_mov_b32 m0, s38
	v_lshl_add_u64 v[226:227], s[36:37], 0, v[162:163]
	ds_read_b128 v[180:183], v179 offset:32768
	ds_read_b128 v[184:187], v179 offset:33792
	ds_read_b128 v[188:191], v179 offset:34816
	ds_read_b128 v[192:195], v179 offset:35840
	ds_read_b128 v[196:199], v179 offset:36864
	ds_read_b128 v[204:207], v179 offset:37888
	ds_read_b128 v[212:215], v179 offset:38912
	ds_read_b128 v[216:219], v179 offset:39936
	global_load_lds_dwordx4 v[226:227], off
	v_lshl_add_u64 v[226:227], s[36:37], 0, v[158:159]
	s_mov_b32 m0, s39
	s_nop 0
	global_load_lds_dwordx4 v[226:227], off
	s_waitcnt vmcnt(8)
	s_waitcnt lgkmcnt(0)
	s_barrier
	s_nop 0
	s_waitcnt lgkmcnt(0)
	v_mfma_f32_16x16x32_bf16 v[128:131], v[132:135], v[180:183], v[128:131]
	v_mfma_f32_16x16x32_bf16 v[124:127], v[140:143], v[180:183], v[124:127]
	v_mfma_f32_16x16x32_bf16 v[112:115], v[132:135], v[188:191], v[112:115]
	v_mfma_f32_16x16x32_bf16 v[108:111], v[140:143], v[188:191], v[108:111]
	v_mfma_f32_16x16x32_bf16 v[100:103], v[132:135], v[196:199], v[100:103]
	v_mfma_f32_16x16x32_bf16 v[92:95], v[140:143], v[196:199], v[92:95]
	v_mfma_f32_16x16x32_bf16 v[84:87], v[132:135], v[212:215], v[84:87]
	v_mfma_f32_16x16x32_bf16 v[76:79], v[140:143], v[212:215], v[76:79]
	v_mfma_f32_16x16x32_bf16 v[128:131], v[136:139], v[184:187], v[128:131]
	v_mfma_f32_16x16x32_bf16 v[124:127], v[144:147], v[184:187], v[124:127]
	v_mfma_f32_16x16x32_bf16 v[112:115], v[136:139], v[192:195], v[112:115]
	v_mfma_f32_16x16x32_bf16 v[108:111], v[144:147], v[192:195], v[108:111]
	v_mfma_f32_16x16x32_bf16 v[100:103], v[136:139], v[204:207], v[100:103]
	v_mfma_f32_16x16x32_bf16 v[92:95], v[144:147], v[204:207], v[92:95]
	v_mfma_f32_16x16x32_bf16 v[84:87], v[136:139], v[216:219], v[84:87]
	v_mfma_f32_16x16x32_bf16 v[76:79], v[144:147], v[216:219], v[76:79]
	s_nop 0
	s_nop 0
	v_mfma_f32_16x16x32_bf16 v[120:123], v[148:151], v[180:183], v[120:123]
	v_mfma_f32_16x16x32_bf16 v[116:119], v[168:171], v[180:183], v[116:119]
	v_mfma_f32_16x16x32_bf16 v[104:107], v[148:151], v[188:191], v[104:107]
	v_mfma_f32_16x16x32_bf16 v[96:99], v[168:171], v[188:191], v[96:99]
	v_mfma_f32_16x16x32_bf16 v[88:91], v[148:151], v[196:199], v[88:91]
	v_mfma_f32_16x16x32_bf16 v[80:83], v[168:171], v[196:199], v[80:83]
	v_mfma_f32_16x16x32_bf16 v[72:75], v[148:151], v[212:215], v[72:75]
	v_mfma_f32_16x16x32_bf16 v[68:71], v[168:171], v[212:215], v[68:71]
	v_mfma_f32_16x16x32_bf16 v[120:123], v[152:155], v[184:187], v[120:123]
	v_mfma_f32_16x16x32_bf16 v[116:119], v[172:175], v[184:187], v[116:119]
	v_mfma_f32_16x16x32_bf16 v[104:107], v[152:155], v[192:195], v[104:107]
	v_mfma_f32_16x16x32_bf16 v[96:99], v[172:175], v[192:195], v[96:99]
	v_mfma_f32_16x16x32_bf16 v[88:91], v[152:155], v[204:207], v[88:91]
	v_mfma_f32_16x16x32_bf16 v[80:83], v[172:175], v[204:207], v[80:83]
	v_mfma_f32_16x16x32_bf16 v[72:75], v[152:155], v[216:219], v[72:75]
	v_mfma_f32_16x16x32_bf16 v[68:71], v[172:175], v[216:219], v[68:71]
	s_nop 0
	s_barrier
	s_add_i32 s36, s49, s7
	v_lshl_add_u64 v[176:177], v[176:177], 0, s[94:95]
	s_mov_b32 m0, s36
	ds_read_b128 v[180:183], v179 offset:49152
	ds_read_b128 v[184:187], v179 offset:50176
	ds_read_b128 v[188:191], v179 offset:51200
	ds_read_b128 v[192:195], v179 offset:52224
	ds_read_b128 v[196:199], v179 offset:53248
	ds_read_b128 v[204:207], v179 offset:54272
	ds_read_b128 v[212:215], v179 offset:55296
	ds_read_b128 v[216:219], v179 offset:56320
	global_load_lds_dwordx4 v[176:177], off
	s_add_i32 m0, s36, 0x2000
	s_add_u32 s34, s34, 0x40080
	v_lshl_add_u64 v[176:177], v[220:221], 0, s[94:95]
	s_addc_u32 s35, s35, 0
	s_add_i32 s36, s50, s7
	global_load_lds_dwordx4 v[176:177], off
	v_lshl_add_u64 v[176:177], s[34:35], 0, v[160:161]
	s_mov_b32 m0, s36
	s_nop 0
	global_load_lds_dwordx4 v[176:177], off
	v_lshl_add_u64 v[176:177], s[34:35], 0, v[156:157]
	s_add_i32 m0, s36, 0x2000
	s_nop 0
	global_load_lds_dwordx4 v[176:177], off
	v_lshl_add_u64 v[176:177], v[222:223], 0, s[94:95]
	s_mov_b32 m0, s40
	s_nop 0
	global_load_lds_dwordx4 v[176:177], off
	v_lshl_add_u64 v[176:177], v[224:225], 0, s[94:95]
	s_mov_b32 m0, s41
	s_nop 0
	global_load_lds_dwordx4 v[176:177], off
	s_waitcnt vmcnt(8)
	s_waitcnt lgkmcnt(0)
	s_barrier
	s_nop 0
	s_waitcnt lgkmcnt(0)
	v_mfma_f32_16x16x32_bf16 v[64:67], v[132:135], v[180:183], v[64:67]
	v_mfma_f32_16x16x32_bf16 v[60:63], v[140:143], v[180:183], v[60:63]
	v_mfma_f32_16x16x32_bf16 v[52:55], v[132:135], v[188:191], v[52:55]
	v_mfma_f32_16x16x32_bf16 v[44:47], v[140:143], v[188:191], v[44:47]
	v_mfma_f32_16x16x32_bf16 v[36:39], v[132:135], v[196:199], v[36:39]
	v_mfma_f32_16x16x32_bf16 v[28:31], v[140:143], v[196:199], v[28:31]
	v_mfma_f32_16x16x32_bf16 v[20:23], v[132:135], v[212:215], v[20:23]
	v_mfma_f32_16x16x32_bf16 v[12:15], v[140:143], v[212:215], v[12:15]
	v_mfma_f32_16x16x32_bf16 v[64:67], v[136:139], v[184:187], v[64:67]
	v_mfma_f32_16x16x32_bf16 v[60:63], v[144:147], v[184:187], v[60:63]
	v_mfma_f32_16x16x32_bf16 v[52:55], v[136:139], v[192:195], v[52:55]
	v_mfma_f32_16x16x32_bf16 v[44:47], v[144:147], v[192:195], v[44:47]
	v_mfma_f32_16x16x32_bf16 v[36:39], v[136:139], v[204:207], v[36:39]
	v_mfma_f32_16x16x32_bf16 v[28:31], v[144:147], v[204:207], v[28:31]
	v_mfma_f32_16x16x32_bf16 v[20:23], v[136:139], v[216:219], v[20:23]
	v_mfma_f32_16x16x32_bf16 v[12:15], v[144:147], v[216:219], v[12:15]
	s_nop 0
	s_nop 0
	v_mfma_f32_16x16x32_bf16 v[56:59], v[148:151], v[180:183], v[56:59]
	v_mfma_f32_16x16x32_bf16 v[48:51], v[168:171], v[180:183], v[48:51]
	v_mfma_f32_16x16x32_bf16 v[40:43], v[148:151], v[188:191], v[40:43]
	v_mfma_f32_16x16x32_bf16 v[32:35], v[168:171], v[188:191], v[32:35]
	v_mfma_f32_16x16x32_bf16 v[24:27], v[148:151], v[196:199], v[24:27]
	v_mfma_f32_16x16x32_bf16 v[16:19], v[168:171], v[196:199], v[16:19]
	v_mfma_f32_16x16x32_bf16 v[8:11], v[148:151], v[212:215], v[8:11]
	v_mfma_f32_16x16x32_bf16 v[4:7], v[168:171], v[212:215], v[4:7]
	v_mfma_f32_16x16x32_bf16 v[56:59], v[152:155], v[184:187], v[56:59]
	v_mfma_f32_16x16x32_bf16 v[48:51], v[172:175], v[184:187], v[48:51]
	v_mfma_f32_16x16x32_bf16 v[40:43], v[152:155], v[192:195], v[40:43]
	v_mfma_f32_16x16x32_bf16 v[32:35], v[172:175], v[192:195], v[32:35]
	v_mfma_f32_16x16x32_bf16 v[24:27], v[152:155], v[204:207], v[24:27]
	v_mfma_f32_16x16x32_bf16 v[16:19], v[172:175], v[204:207], v[16:19]
	v_mfma_f32_16x16x32_bf16 v[8:11], v[152:155], v[216:219], v[8:11]
	v_mfma_f32_16x16x32_bf16 v[4:7], v[172:175], v[216:219], v[4:7]
	s_nop 0
	s_barrier
	s_add_i32 s27, s27, 2
	s_add_u32 s30, s30, 0x100
	s_addc_u32 s31, s31, 0
	s_add_u32 s19, s19, 0x100
	s_addc_u32 s21, s21, 0
	s_cmp_gt_u32 s27, 13
	s_cbranch_scc0 .LBB0_1260
	s_and_b64 vcc, exec, s[16:17]
	s_cbranch_vccz .LBB0_1263
	s_barrier

.LBB0_1278:
	s_add_u32 s30, s28, 0xfffc0080
	s_addc_u32 s31, s29, -1
	s_add_i32 s45, 0, 0x10000
	s_cmp_eq_u32 s25, 12
	s_cselect_b32 s35, s21, s31
	s_cselect_b32 s34, s20, s30
	v_add_u32_e32 v1, s45, v178
	s_cselect_b32 s31, s23, s19
	s_cselect_b32 s30, s22, s1
	s_add_i32 s48, 0, 0x14000
	ds_read_b128 v[132:135], v1
	ds_read_b128 v[136:139], v1 offset:1024
	ds_read_b128 v[140:143], v1 offset:2048
	ds_read_b128 v[144:147], v1 offset:3072
	v_add_u32_e32 v1, s48, v178
	ds_read_b128 v[148:151], v1
	ds_read_b128 v[152:155], v1 offset:1024
	ds_read_b128 v[168:171], v1 offset:2048
	ds_read_b128 v[172:175], v1 offset:3072
	v_lshl_add_u64 v[176:177], s[28:29], 0, v[164:165]
	s_add_i32 m0, s27, 0xc000
	ds_read_b128 v[180:183], v179
	ds_read_b128 v[184:187], v179 offset:1024
	ds_read_b128 v[188:191], v179 offset:2048
	ds_read_b128 v[192:195], v179 offset:3072
	ds_read_b128 v[196:199], v179 offset:4096
	ds_read_b128 v[204:207], v179 offset:5120
	ds_read_b128 v[212:215], v179 offset:6144
	ds_read_b128 v[216:219], v179 offset:7168
	global_load_lds_dwordx4 v[176:177], off
	v_lshl_add_u64 v[176:177], s[28:29], 0, v[166:167]
	s_add_i32 m0, s27, 0xe000
	s_nop 0
	global_load_lds_dwordx4 v[176:177], off
	s_waitcnt vmcnt(8)
	s_waitcnt lgkmcnt(0)
	s_barrier
	s_nop 0
	s_waitcnt lgkmcnt(0)
	v_mfma_f32_16x16x32_bf16 v[128:131], v[132:135], v[180:183], v[128:131]
	v_mfma_f32_16x16x32_bf16 v[124:127], v[140:143], v[180:183], v[124:127]
	v_mfma_f32_16x16x32_bf16 v[112:115], v[132:135], v[188:191], v[112:115]
	v_mfma_f32_16x16x32_bf16 v[108:111], v[140:143], v[188:191], v[108:111]
	v_mfma_f32_16x16x32_bf16 v[100:103], v[132:135], v[196:199], v[100:103]
	v_mfma_f32_16x16x32_bf16 v[92:95], v[140:143], v[196:199], v[92:95]
	v_mfma_f32_16x16x32_bf16 v[84:87], v[132:135], v[212:215], v[84:87]
	v_mfma_f32_16x16x32_bf16 v[76:79], v[140:143], v[212:215], v[76:79]
	v_mfma_f32_16x16x32_bf16 v[128:131], v[136:139], v[184:187], v[128:131]
	v_mfma_f32_16x16x32_bf16 v[124:127], v[144:147], v[184:187], v[124:127]
	v_mfma_f32_16x16x32_bf16 v[112:115], v[136:139], v[192:195], v[112:115]
	v_mfma_f32_16x16x32_bf16 v[108:111], v[144:147], v[192:195], v[108:111]
	v_mfma_f32_16x16x32_bf16 v[100:103], v[136:139], v[204:207], v[100:103]
	v_mfma_f32_16x16x32_bf16 v[92:95], v[144:147], v[204:207], v[92:95]
	v_mfma_f32_16x16x32_bf16 v[84:87], v[136:139], v[216:219], v[84:87]
	v_mfma_f32_16x16x32_bf16 v[76:79], v[144:147], v[216:219], v[76:79]
	s_nop 0
	s_nop 0
	v_mfma_f32_16x16x32_bf16 v[120:123], v[148:151], v[180:183], v[120:123]
	v_mfma_f32_16x16x32_bf16 v[116:119], v[168:171], v[180:183], v[116:119]
	v_mfma_f32_16x16x32_bf16 v[104:107], v[148:151], v[188:191], v[104:107]
	v_mfma_f32_16x16x32_bf16 v[96:99], v[168:171], v[188:191], v[96:99]
	v_mfma_f32_16x16x32_bf16 v[88:91], v[148:151], v[196:199], v[88:91]
	v_mfma_f32_16x16x32_bf16 v[80:83], v[168:171], v[196:199], v[80:83]
	v_mfma_f32_16x16x32_bf16 v[72:75], v[148:151], v[212:215], v[72:75]
	v_mfma_f32_16x16x32_bf16 v[68:71], v[168:171], v[212:215], v[68:71]
	v_mfma_f32_16x16x32_bf16 v[120:123], v[152:155], v[184:187], v[120:123]
	v_mfma_f32_16x16x32_bf16 v[116:119], v[172:175], v[184:187], v[116:119]
	v_mfma_f32_16x16x32_bf16 v[104:107], v[152:155], v[192:195], v[104:107]
	v_mfma_f32_16x16x32_bf16 v[96:99], v[172:175], v[192:195], v[96:99]
	v_mfma_f32_16x16x32_bf16 v[88:91], v[152:155], v[204:207], v[88:91]
	v_mfma_f32_16x16x32_bf16 v[80:83], v[172:175], v[204:207], v[80:83]
	v_mfma_f32_16x16x32_bf16 v[72:75], v[152:155], v[216:219], v[72:75]
	v_mfma_f32_16x16x32_bf16 v[68:71], v[172:175], v[216:219], v[68:71]
	s_nop 0
	s_barrier
	s_add_i32 s45, s45, s11
	v_lshl_add_u64 v[176:177], s[30:31], 0, v[160:161]
	s_mov_b32 m0, s45
	ds_read_b128 v[180:183], v179 offset:16384
	ds_read_b128 v[184:187], v179 offset:17408
	ds_read_b128 v[188:191], v179 offset:18432
	ds_read_b128 v[192:195], v179 offset:19456
	ds_read_b128 v[196:199], v179 offset:20480
	ds_read_b128 v[204:207], v179 offset:21504
	ds_read_b128 v[212:215], v179 offset:22528
	ds_read_b128 v[216:219], v179 offset:23552
	global_load_lds_dwordx4 v[176:177], off
	s_add_i32 m0, s45, 0x2000
	s_add_u32 s46, s30, 0x40000
	v_lshl_add_u64 v[220:221], s[30:31], 0, v[156:157]
	s_addc_u32 s47, s31, 0
	s_add_i32 s45, s48, s11
	global_load_lds_dwordx4 v[220:221], off
	v_lshl_add_u64 v[222:223], s[46:47], 0, v[160:161]
	s_mov_b32 m0, s45
	v_lshl_add_u64 v[224:225], s[34:35], 0, v[158:159]
	global_load_lds_dwordx4 v[222:223], off
	v_lshl_add_u64 v[222:223], s[46:47], 0, v[156:157]
	s_add_i32 m0, s45, 0x2000
	s_nop 0
	global_load_lds_dwordx4 v[222:223], off
	v_lshl_add_u64 v[222:223], s[34:35], 0, v[162:163]
	s_mov_b32 m0, s27
	s_nop 0
	global_load_lds_dwordx4 v[222:223], off
	s_mov_b32 m0, s33
	s_nop 0
	global_load_lds_dwordx4 v[224:225], off
	s_waitcnt vmcnt(8)
	s_waitcnt lgkmcnt(0)
	s_barrier
	s_nop 0
	s_waitcnt lgkmcnt(0)
	v_mfma_f32_16x16x32_bf16 v[64:67], v[132:135], v[180:183], v[64:67]
	v_mfma_f32_16x16x32_bf16 v[60:63], v[140:143], v[180:183], v[60:63]
	v_mfma_f32_16x16x32_bf16 v[52:55], v[132:135], v[188:191], v[52:55]
	v_mfma_f32_16x16x32_bf16 v[44:47], v[140:143], v[188:191], v[44:47]
	v_mfma_f32_16x16x32_bf16 v[36:39], v[132:135], v[196:199], v[36:39]
	v_mfma_f32_16x16x32_bf16 v[28:31], v[140:143], v[196:199], v[28:31]
	v_mfma_f32_16x16x32_bf16 v[20:23], v[132:135], v[212:215], v[20:23]
	v_mfma_f32_16x16x32_bf16 v[12:15], v[140:143], v[212:215], v[12:15]
	v_mfma_f32_16x16x32_bf16 v[64:67], v[136:139], v[184:187], v[64:67]
	v_mfma_f32_16x16x32_bf16 v[60:63], v[144:147], v[184:187], v[60:63]
	v_mfma_f32_16x16x32_bf16 v[52:55], v[136:139], v[192:195], v[52:55]
	v_mfma_f32_16x16x32_bf16 v[44:47], v[144:147], v[192:195], v[44:47]
	v_mfma_f32_16x16x32_bf16 v[36:39], v[136:139], v[204:207], v[36:39]
	v_mfma_f32_16x16x32_bf16 v[28:31], v[144:147], v[204:207], v[28:31]
	v_mfma_f32_16x16x32_bf16 v[20:23], v[136:139], v[216:219], v[20:23]
	v_mfma_f32_16x16x32_bf16 v[12:15], v[144:147], v[216:219], v[12:15]
	s_nop 0
	s_nop 0
	v_mfma_f32_16x16x32_bf16 v[56:59], v[148:151], v[180:183], v[56:59]
	v_mfma_f32_16x16x32_bf16 v[48:51], v[168:171], v[180:183], v[48:51]
	v_mfma_f32_16x16x32_bf16 v[40:43], v[148:151], v[188:191], v[40:43]
	v_mfma_f32_16x16x32_bf16 v[32:35], v[168:171], v[188:191], v[32:35]
	v_mfma_f32_16x16x32_bf16 v[24:27], v[148:151], v[196:199], v[24:27]
	v_mfma_f32_16x16x32_bf16 v[16:19], v[168:171], v[196:199], v[16:19]
	v_mfma_f32_16x16x32_bf16 v[8:11], v[148:151], v[212:215], v[8:11]
	v_mfma_f32_16x16x32_bf16 v[4:7], v[168:171], v[212:215], v[4:7]
	v_mfma_f32_16x16x32_bf16 v[56:59], v[152:155], v[184:187], v[56:59]
	v_mfma_f32_16x16x32_bf16 v[48:51], v[172:175], v[184:187], v[48:51]
	v_mfma_f32_16x16x32_bf16 v[40:43], v[152:155], v[192:195], v[40:43]
	v_mfma_f32_16x16x32_bf16 v[32:35], v[172:175], v[192:195], v[32:35]
	v_mfma_f32_16x16x32_bf16 v[24:27], v[152:155], v[204:207], v[24:27]
	v_mfma_f32_16x16x32_bf16 v[16:19], v[172:175], v[204:207], v[16:19]
	v_mfma_f32_16x16x32_bf16 v[8:11], v[152:155], v[216:219], v[8:11]
	v_mfma_f32_16x16x32_bf16 v[4:7], v[172:175], v[216:219], v[4:7]
	s_nop 0
	s_barrier
	s_add_i32 s45, 0, 0x18000
	v_add_u32_e32 v1, s45, v178
	s_add_i32 s46, 0, 0x1c000
	ds_read_b128 v[132:135], v1
	ds_read_b128 v[136:139], v1 offset:1024
	ds_read_b128 v[140:143], v1 offset:2048
	ds_read_b128 v[144:147], v1 offset:3072
	v_add_u32_e32 v1, s46, v178
	ds_read_b128 v[148:151], v1
	ds_read_b128 v[152:155], v1 offset:1024
	ds_read_b128 v[168:171], v1 offset:2048
	ds_read_b128 v[172:175], v1 offset:3072
	s_add_u32 s34, s34, 0x40000
	s_addc_u32 s35, s35, 0
	s_mov_b32 m0, s36
	v_lshl_add_u64 v[226:227], s[34:35], 0, v[162:163]
	ds_read_b128 v[180:183], v179 offset:32768
	ds_read_b128 v[184:187], v179 offset:33792
	ds_read_b128 v[188:191], v179 offset:34816
	ds_read_b128 v[192:195], v179 offset:35840
	ds_read_b128 v[196:199], v179 offset:36864
	ds_read_b128 v[204:207], v179 offset:37888
	ds_read_b128 v[212:215], v179 offset:38912
	ds_read_b128 v[216:219], v179 offset:39936
	global_load_lds_dwordx4 v[226:227], off
	v_lshl_add_u64 v[226:227], s[34:35], 0, v[158:159]
	s_mov_b32 m0, s37
	s_nop 0
	global_load_lds_dwordx4 v[226:227], off
	s_waitcnt vmcnt(8)
	s_waitcnt lgkmcnt(0)
	s_barrier
	s_nop 0
	s_waitcnt lgkmcnt(0)
	v_mfma_f32_16x16x32_bf16 v[128:131], v[132:135], v[180:183], v[128:131]
	v_mfma_f32_16x16x32_bf16 v[124:127], v[140:143], v[180:183], v[124:127]
	v_mfma_f32_16x16x32_bf16 v[112:115], v[132:135], v[188:191], v[112:115]
	v_mfma_f32_16x16x32_bf16 v[108:111], v[140:143], v[188:191], v[108:111]
	v_mfma_f32_16x16x32_bf16 v[100:103], v[132:135], v[196:199], v[100:103]
	v_mfma_f32_16x16x32_bf16 v[92:95], v[140:143], v[196:199], v[92:95]
	v_mfma_f32_16x16x32_bf16 v[84:87], v[132:135], v[212:215], v[84:87]
	v_mfma_f32_16x16x32_bf16 v[76:79], v[140:143], v[212:215], v[76:79]
	v_mfma_f32_16x16x32_bf16 v[128:131], v[136:139], v[184:187], v[128:131]
	v_mfma_f32_16x16x32_bf16 v[124:127], v[144:147], v[184:187], v[124:127]
	v_mfma_f32_16x16x32_bf16 v[112:115], v[136:139], v[192:195], v[112:115]
	v_mfma_f32_16x16x32_bf16 v[108:111], v[144:147], v[192:195], v[108:111]
	v_mfma_f32_16x16x32_bf16 v[100:103], v[136:139], v[204:207], v[100:103]
	v_mfma_f32_16x16x32_bf16 v[92:95], v[144:147], v[204:207], v[92:95]
	v_mfma_f32_16x16x32_bf16 v[84:87], v[136:139], v[216:219], v[84:87]
	v_mfma_f32_16x16x32_bf16 v[76:79], v[144:147], v[216:219], v[76:79]
	s_nop 0
	s_nop 0
	v_mfma_f32_16x16x32_bf16 v[120:123], v[148:151], v[180:183], v[120:123]
	v_mfma_f32_16x16x32_bf16 v[116:119], v[168:171], v[180:183], v[116:119]
	v_mfma_f32_16x16x32_bf16 v[104:107], v[148:151], v[188:191], v[104:107]
	v_mfma_f32_16x16x32_bf16 v[96:99], v[168:171], v[188:191], v[96:99]
	v_mfma_f32_16x16x32_bf16 v[88:91], v[148:151], v[196:199], v[88:91]
	v_mfma_f32_16x16x32_bf16 v[80:83], v[168:171], v[196:199], v[80:83]
	v_mfma_f32_16x16x32_bf16 v[72:75], v[148:151], v[212:215], v[72:75]
	v_mfma_f32_16x16x32_bf16 v[68:71], v[168:171], v[212:215], v[68:71]
	v_mfma_f32_16x16x32_bf16 v[120:123], v[152:155], v[184:187], v[120:123]
	v_mfma_f32_16x16x32_bf16 v[116:119], v[172:175], v[184:187], v[116:119]
	v_mfma_f32_16x16x32_bf16 v[104:107], v[152:155], v[192:195], v[104:107]
	v_mfma_f32_16x16x32_bf16 v[96:99], v[172:175], v[192:195], v[96:99]
	v_mfma_f32_16x16x32_bf16 v[88:91], v[152:155], v[204:207], v[88:91]
	v_mfma_f32_16x16x32_bf16 v[80:83], v[172:175], v[204:207], v[80:83]
	v_mfma_f32_16x16x32_bf16 v[72:75], v[152:155], v[216:219], v[72:75]
	v_mfma_f32_16x16x32_bf16 v[68:71], v[172:175], v[216:219], v[68:71]
	s_nop 0
	s_barrier
	s_add_i32 s34, s45, s11
	v_lshl_add_u64 v[176:177], v[176:177], 0, s[94:95]
	s_mov_b32 m0, s34
	ds_read_b128 v[180:183], v179 offset:49152
	ds_read_b128 v[184:187], v179 offset:50176
	ds_read_b128 v[188:191], v179 offset:51200
	ds_read_b128 v[192:195], v179 offset:52224
	ds_read_b128 v[196:199], v179 offset:53248
	ds_read_b128 v[204:207], v179 offset:54272
	ds_read_b128 v[212:215], v179 offset:55296
	ds_read_b128 v[216:219], v179 offset:56320
	global_load_lds_dwordx4 v[176:177], off
	s_add_i32 m0, s34, 0x2000
	s_add_u32 s30, s30, 0x40080
	v_lshl_add_u64 v[176:177], v[220:221], 0, s[94:95]
	s_addc_u32 s31, s31, 0
	s_add_i32 s34, s46, s11
	global_load_lds_dwordx4 v[176:177], off
	v_lshl_add_u64 v[176:177], s[30:31], 0, v[160:161]
	s_mov_b32 m0, s34
	s_nop 0
	global_load_lds_dwordx4 v[176:177], off
	v_lshl_add_u64 v[176:177], s[30:31], 0, v[156:157]
	s_add_i32 m0, s34, 0x2000
	s_nop 0
	global_load_lds_dwordx4 v[176:177], off
	v_lshl_add_u64 v[176:177], v[222:223], 0, s[94:95]
	s_mov_b32 m0, s38
	s_nop 0
	global_load_lds_dwordx4 v[176:177], off
	v_lshl_add_u64 v[176:177], v[224:225], 0, s[94:95]
	s_mov_b32 m0, s39
	s_nop 0
	global_load_lds_dwordx4 v[176:177], off
	s_waitcnt vmcnt(8)
	s_waitcnt lgkmcnt(0)
	s_barrier
	s_nop 0
	s_waitcnt lgkmcnt(0)
	v_mfma_f32_16x16x32_bf16 v[64:67], v[132:135], v[180:183], v[64:67]
	v_mfma_f32_16x16x32_bf16 v[60:63], v[140:143], v[180:183], v[60:63]
	v_mfma_f32_16x16x32_bf16 v[52:55], v[132:135], v[188:191], v[52:55]
	v_mfma_f32_16x16x32_bf16 v[44:47], v[140:143], v[188:191], v[44:47]
	v_mfma_f32_16x16x32_bf16 v[36:39], v[132:135], v[196:199], v[36:39]
	v_mfma_f32_16x16x32_bf16 v[28:31], v[140:143], v[196:199], v[28:31]
	v_mfma_f32_16x16x32_bf16 v[20:23], v[132:135], v[212:215], v[20:23]
	v_mfma_f32_16x16x32_bf16 v[12:15], v[140:143], v[212:215], v[12:15]
	v_mfma_f32_16x16x32_bf16 v[64:67], v[136:139], v[184:187], v[64:67]
	v_mfma_f32_16x16x32_bf16 v[60:63], v[144:147], v[184:187], v[60:63]
	v_mfma_f32_16x16x32_bf16 v[52:55], v[136:139], v[192:195], v[52:55]
	v_mfma_f32_16x16x32_bf16 v[44:47], v[144:147], v[192:195], v[44:47]
	v_mfma_f32_16x16x32_bf16 v[36:39], v[136:139], v[204:207], v[36:39]
	v_mfma_f32_16x16x32_bf16 v[28:31], v[144:147], v[204:207], v[28:31]
	v_mfma_f32_16x16x32_bf16 v[20:23], v[136:139], v[216:219], v[20:23]
	v_mfma_f32_16x16x32_bf16 v[12:15], v[144:147], v[216:219], v[12:15]
	s_nop 0
	s_nop 0
	v_mfma_f32_16x16x32_bf16 v[56:59], v[148:151], v[180:183], v[56:59]
	v_mfma_f32_16x16x32_bf16 v[48:51], v[168:171], v[180:183], v[48:51]
	v_mfma_f32_16x16x32_bf16 v[40:43], v[148:151], v[188:191], v[40:43]
	v_mfma_f32_16x16x32_bf16 v[32:35], v[168:171], v[188:191], v[32:35]
	v_mfma_f32_16x16x32_bf16 v[24:27], v[148:151], v[196:199], v[24:27]
	v_mfma_f32_16x16x32_bf16 v[16:19], v[168:171], v[196:199], v[16:19]
	v_mfma_f32_16x16x32_bf16 v[8:11], v[148:151], v[212:215], v[8:11]
	v_mfma_f32_16x16x32_bf16 v[4:7], v[168:171], v[212:215], v[4:7]
	v_mfma_f32_16x16x32_bf16 v[56:59], v[152:155], v[184:187], v[56:59]
	v_mfma_f32_16x16x32_bf16 v[48:51], v[172:175], v[184:187], v[48:51]
	v_mfma_f32_16x16x32_bf16 v[40:43], v[152:155], v[192:195], v[40:43]
	v_mfma_f32_16x16x32_bf16 v[32:35], v[172:175], v[192:195], v[32:35]
	v_mfma_f32_16x16x32_bf16 v[24:27], v[152:155], v[204:207], v[24:27]
	v_mfma_f32_16x16x32_bf16 v[16:19], v[172:175], v[204:207], v[16:19]
	v_mfma_f32_16x16x32_bf16 v[8:11], v[152:155], v[216:219], v[8:11]
	v_mfma_f32_16x16x32_bf16 v[4:7], v[172:175], v[216:219], v[4:7]
	s_nop 0
	s_barrier
	s_add_i32 s25, s25, 2
	s_add_u32 s28, s28, 0x100
	s_addc_u32 s29, s29, 0
	s_add_u32 s1, s1, 0x100
	s_addc_u32 s19, s19, 0
	s_cmp_gt_u32 s25, 13
	s_cbranch_scc0 .LBB0_1278
	s_and_b64 vcc, exec, s[16:17]
	s_cbranch_vccz .LBB0_1281
	s_barrier

.LBB0_1403:
	s_add_u32 s30, s28, 0xfff80080
	s_addc_u32 s31, s29, -1
	s_add_i32 s58, 0, 0x10000
	s_cmp_eq_u32 s57, 28
	s_cselect_b32 s35, s21, s31
	s_cselect_b32 s34, s53, s30
	v_add_u32_e32 v1, s58, v151
	s_cselect_b32 s31, s19, s56
	s_cselect_b32 s30, s54, s55
	s_add_i32 s60, 0, 0x14000
	ds_read_b128 v[144:147], v1
	ds_read_b128 v[154:157], v1 offset:1024
	ds_read_b128 v[158:161], v1 offset:2048
	ds_read_b128 v[162:165], v1 offset:3072
	v_add_u32_e32 v1, s60, v151
	ds_read_b128 v[166:169], v1
	ds_read_b128 v[170:173], v1 offset:1024
	ds_read_b128 v[174:177], v1 offset:2048
	ds_read_b128 v[178:181], v1 offset:3072
	v_lshl_add_u64 v[148:149], s[28:29], 0, v[140:141]
	s_add_i32 m0, s37, 0xc000
	ds_read_b128 v[182:185], v152
	ds_read_b128 v[186:189], v152 offset:1024
	ds_read_b128 v[190:193], v152 offset:2048
	ds_read_b128 v[194:197], v152 offset:3072
	ds_read_b128 v[204:207], v152 offset:4096
	ds_read_b128 v[212:215], v152 offset:5120
	ds_read_b128 v[216:219], v152 offset:6144
	ds_read_b128 v[220:223], v152 offset:7168
	global_load_lds_dwordx4 v[148:149], off
	v_lshl_add_u64 v[148:149], s[28:29], 0, v[142:143]
	s_add_i32 m0, s37, 0xe000
	s_nop 0
	global_load_lds_dwordx4 v[148:149], off
	s_waitcnt vmcnt(8)
	s_waitcnt lgkmcnt(0)
	s_barrier
	s_nop 0
	s_waitcnt lgkmcnt(0)
	v_mfma_f32_16x16x32_bf16 v[128:131], v[144:147], v[182:185], v[128:131]
	v_mfma_f32_16x16x32_bf16 v[124:127], v[158:161], v[182:185], v[124:127]
	v_mfma_f32_16x16x32_bf16 v[120:123], v[144:147], v[190:193], v[120:123]
	v_mfma_f32_16x16x32_bf16 v[116:119], v[158:161], v[190:193], v[116:119]
	v_mfma_f32_16x16x32_bf16 v[96:99], v[144:147], v[204:207], v[96:99]
	v_mfma_f32_16x16x32_bf16 v[92:95], v[158:161], v[204:207], v[92:95]
	v_mfma_f32_16x16x32_bf16 v[88:91], v[144:147], v[216:219], v[88:91]
	v_mfma_f32_16x16x32_bf16 v[84:87], v[158:161], v[216:219], v[84:87]
	v_mfma_f32_16x16x32_bf16 v[128:131], v[154:157], v[186:189], v[128:131]
	v_mfma_f32_16x16x32_bf16 v[124:127], v[162:165], v[186:189], v[124:127]
	v_mfma_f32_16x16x32_bf16 v[120:123], v[154:157], v[194:197], v[120:123]
	v_mfma_f32_16x16x32_bf16 v[116:119], v[162:165], v[194:197], v[116:119]
	v_mfma_f32_16x16x32_bf16 v[96:99], v[154:157], v[212:215], v[96:99]
	v_mfma_f32_16x16x32_bf16 v[92:95], v[162:165], v[212:215], v[92:95]
	v_mfma_f32_16x16x32_bf16 v[88:91], v[154:157], v[220:223], v[88:91]
	v_mfma_f32_16x16x32_bf16 v[84:87], v[162:165], v[220:223], v[84:87]
	s_nop 0
	s_nop 0
	v_mfma_f32_16x16x32_bf16 v[112:115], v[166:169], v[182:185], v[112:115]
	v_mfma_f32_16x16x32_bf16 v[108:111], v[174:177], v[182:185], v[108:111]
	v_mfma_f32_16x16x32_bf16 v[104:107], v[166:169], v[190:193], v[104:107]
	v_mfma_f32_16x16x32_bf16 v[100:103], v[174:177], v[190:193], v[100:103]
	v_mfma_f32_16x16x32_bf16 v[80:83], v[166:169], v[204:207], v[80:83]
	v_mfma_f32_16x16x32_bf16 v[76:79], v[174:177], v[204:207], v[76:79]
	v_mfma_f32_16x16x32_bf16 v[72:75], v[166:169], v[216:219], v[72:75]
	v_mfma_f32_16x16x32_bf16 v[68:71], v[174:177], v[216:219], v[68:71]
	v_mfma_f32_16x16x32_bf16 v[112:115], v[170:173], v[186:189], v[112:115]
	v_mfma_f32_16x16x32_bf16 v[108:111], v[178:181], v[186:189], v[108:111]
	v_mfma_f32_16x16x32_bf16 v[104:107], v[170:173], v[194:197], v[104:107]
	v_mfma_f32_16x16x32_bf16 v[100:103], v[178:181], v[194:197], v[100:103]
	v_mfma_f32_16x16x32_bf16 v[80:83], v[170:173], v[212:215], v[80:83]
	v_mfma_f32_16x16x32_bf16 v[76:79], v[178:181], v[212:215], v[76:79]
	v_mfma_f32_16x16x32_bf16 v[72:75], v[170:173], v[220:223], v[72:75]
	v_mfma_f32_16x16x32_bf16 v[68:71], v[178:181], v[220:223], v[68:71]
	s_nop 0
	s_barrier
	s_add_i32 s58, s58, s6
	v_lshl_add_u64 v[148:149], s[30:31], 0, v[136:137]
	s_mov_b32 m0, s58
	ds_read_b128 v[182:185], v152 offset:16384
	ds_read_b128 v[186:189], v152 offset:17408
	ds_read_b128 v[190:193], v152 offset:18432
	ds_read_b128 v[194:197], v152 offset:19456
	ds_read_b128 v[204:207], v152 offset:20480
	ds_read_b128 v[212:215], v152 offset:21504
	ds_read_b128 v[216:219], v152 offset:22528
	ds_read_b128 v[220:223], v152 offset:23552
	global_load_lds_dwordx4 v[148:149], off
	s_add_i32 m0, s58, 0x2000
	s_add_u32 s58, s30, 0x80000
	v_lshl_add_u64 v[198:199], s[30:31], 0, v[132:133]
	s_addc_u32 s59, s31, 0
	s_add_i32 s60, s60, s6
	global_load_lds_dwordx4 v[198:199], off
	v_lshl_add_u64 v[224:225], s[58:59], 0, v[136:137]
	s_mov_b32 m0, s60
	v_lshl_add_u64 v[226:227], s[34:35], 0, v[134:135]
	global_load_lds_dwordx4 v[224:225], off
	v_lshl_add_u64 v[224:225], s[58:59], 0, v[132:133]
	s_add_i32 m0, s60, 0x2000
	s_nop 0
	global_load_lds_dwordx4 v[224:225], off
	v_lshl_add_u64 v[224:225], s[34:35], 0, v[138:139]
	s_mov_b32 m0, s37
	s_nop 0
	global_load_lds_dwordx4 v[224:225], off
	s_mov_b32 m0, s38
	s_nop 0
	global_load_lds_dwordx4 v[226:227], off
	s_waitcnt vmcnt(8)
	s_waitcnt lgkmcnt(0)
	s_barrier
	s_nop 0
	s_waitcnt lgkmcnt(0)
	v_mfma_f32_16x16x32_bf16 v[64:67], v[144:147], v[182:185], v[64:67]
	v_mfma_f32_16x16x32_bf16 v[60:63], v[158:161], v[182:185], v[60:63]
	v_mfma_f32_16x16x32_bf16 v[56:59], v[144:147], v[190:193], v[56:59]
	v_mfma_f32_16x16x32_bf16 v[52:55], v[158:161], v[190:193], v[52:55]
	v_mfma_f32_16x16x32_bf16 v[32:35], v[144:147], v[204:207], v[32:35]
	v_mfma_f32_16x16x32_bf16 v[28:31], v[158:161], v[204:207], v[28:31]
	v_mfma_f32_16x16x32_bf16 v[16:19], v[144:147], v[216:219], v[16:19]
	v_mfma_f32_16x16x32_bf16 v[12:15], v[158:161], v[216:219], v[12:15]
	v_mfma_f32_16x16x32_bf16 v[64:67], v[154:157], v[186:189], v[64:67]
	v_mfma_f32_16x16x32_bf16 v[60:63], v[162:165], v[186:189], v[60:63]
	v_mfma_f32_16x16x32_bf16 v[56:59], v[154:157], v[194:197], v[56:59]
	v_mfma_f32_16x16x32_bf16 v[52:55], v[162:165], v[194:197], v[52:55]
	v_mfma_f32_16x16x32_bf16 v[32:35], v[154:157], v[212:215], v[32:35]
	v_mfma_f32_16x16x32_bf16 v[28:31], v[162:165], v[212:215], v[28:31]
	v_mfma_f32_16x16x32_bf16 v[16:19], v[154:157], v[220:223], v[16:19]
	v_mfma_f32_16x16x32_bf16 v[12:15], v[162:165], v[220:223], v[12:15]
	s_nop 0
	s_nop 0
	v_mfma_f32_16x16x32_bf16 v[48:51], v[166:169], v[182:185], v[48:51]
	v_mfma_f32_16x16x32_bf16 v[44:47], v[174:177], v[182:185], v[44:47]
	v_mfma_f32_16x16x32_bf16 v[40:43], v[166:169], v[190:193], v[40:43]
	v_mfma_f32_16x16x32_bf16 v[36:39], v[174:177], v[190:193], v[36:39]
	v_mfma_f32_16x16x32_bf16 v[24:27], v[166:169], v[204:207], v[24:27]
	v_mfma_f32_16x16x32_bf16 v[20:23], v[174:177], v[204:207], v[20:23]
	v_mfma_f32_16x16x32_bf16 v[8:11], v[166:169], v[216:219], v[8:11]
	v_mfma_f32_16x16x32_bf16 v[4:7], v[174:177], v[216:219], v[4:7]
	v_mfma_f32_16x16x32_bf16 v[48:51], v[170:173], v[186:189], v[48:51]
	v_mfma_f32_16x16x32_bf16 v[44:47], v[178:181], v[186:189], v[44:47]
	v_mfma_f32_16x16x32_bf16 v[40:43], v[170:173], v[194:197], v[40:43]
	v_mfma_f32_16x16x32_bf16 v[36:39], v[178:181], v[194:197], v[36:39]
	v_mfma_f32_16x16x32_bf16 v[24:27], v[170:173], v[212:215], v[24:27]
	v_mfma_f32_16x16x32_bf16 v[20:23], v[178:181], v[212:215], v[20:23]
	v_mfma_f32_16x16x32_bf16 v[8:11], v[170:173], v[220:223], v[8:11]
	v_mfma_f32_16x16x32_bf16 v[4:7], v[178:181], v[220:223], v[4:7]
	s_nop 0
	s_barrier
	s_add_i32 s58, 0, 0x18000
	v_add_u32_e32 v1, s58, v151
	s_add_i32 s59, 0, 0x1c000
	ds_read_b128 v[144:147], v1
	ds_read_b128 v[154:157], v1 offset:1024
	ds_read_b128 v[158:161], v1 offset:2048
	ds_read_b128 v[162:165], v1 offset:3072
	v_add_u32_e32 v1, s59, v151
	ds_read_b128 v[166:169], v1
	ds_read_b128 v[170:173], v1 offset:1024
	ds_read_b128 v[174:177], v1 offset:2048
	ds_read_b128 v[178:181], v1 offset:3072
	s_add_u32 s34, s34, 0x80000
	s_addc_u32 s35, s35, 0
	s_mov_b32 m0, s39
	v_lshl_add_u64 v[228:229], s[34:35], 0, v[138:139]
	ds_read_b128 v[182:185], v152 offset:32768
	ds_read_b128 v[186:189], v152 offset:33792
	ds_read_b128 v[190:193], v152 offset:34816
	ds_read_b128 v[194:197], v152 offset:35840
	ds_read_b128 v[204:207], v152 offset:36864
	ds_read_b128 v[212:215], v152 offset:37888
	ds_read_b128 v[216:219], v152 offset:38912
	ds_read_b128 v[220:223], v152 offset:39936
	global_load_lds_dwordx4 v[228:229], off
	v_lshl_add_u64 v[228:229], s[34:35], 0, v[134:135]
	s_mov_b32 m0, s40
	s_nop 0
	global_load_lds_dwordx4 v[228:229], off
	s_waitcnt vmcnt(8)
	s_waitcnt lgkmcnt(0)
	s_barrier
	s_nop 0
	s_waitcnt lgkmcnt(0)
	v_mfma_f32_16x16x32_bf16 v[128:131], v[144:147], v[182:185], v[128:131]
	v_mfma_f32_16x16x32_bf16 v[124:127], v[158:161], v[182:185], v[124:127]
	v_mfma_f32_16x16x32_bf16 v[120:123], v[144:147], v[190:193], v[120:123]
	v_mfma_f32_16x16x32_bf16 v[116:119], v[158:161], v[190:193], v[116:119]
	v_mfma_f32_16x16x32_bf16 v[96:99], v[144:147], v[204:207], v[96:99]
	v_mfma_f32_16x16x32_bf16 v[92:95], v[158:161], v[204:207], v[92:95]
	v_mfma_f32_16x16x32_bf16 v[88:91], v[144:147], v[216:219], v[88:91]
	v_mfma_f32_16x16x32_bf16 v[84:87], v[158:161], v[216:219], v[84:87]
	v_mfma_f32_16x16x32_bf16 v[128:131], v[154:157], v[186:189], v[128:131]
	v_mfma_f32_16x16x32_bf16 v[124:127], v[162:165], v[186:189], v[124:127]
	v_mfma_f32_16x16x32_bf16 v[120:123], v[154:157], v[194:197], v[120:123]
	v_mfma_f32_16x16x32_bf16 v[116:119], v[162:165], v[194:197], v[116:119]
	v_mfma_f32_16x16x32_bf16 v[96:99], v[154:157], v[212:215], v[96:99]
	v_mfma_f32_16x16x32_bf16 v[92:95], v[162:165], v[212:215], v[92:95]
	v_mfma_f32_16x16x32_bf16 v[88:91], v[154:157], v[220:223], v[88:91]
	v_mfma_f32_16x16x32_bf16 v[84:87], v[162:165], v[220:223], v[84:87]
	s_nop 0
	s_nop 0
	v_mfma_f32_16x16x32_bf16 v[112:115], v[166:169], v[182:185], v[112:115]
	v_mfma_f32_16x16x32_bf16 v[108:111], v[174:177], v[182:185], v[108:111]
	v_mfma_f32_16x16x32_bf16 v[104:107], v[166:169], v[190:193], v[104:107]
	v_mfma_f32_16x16x32_bf16 v[100:103], v[174:177], v[190:193], v[100:103]
	v_mfma_f32_16x16x32_bf16 v[80:83], v[166:169], v[204:207], v[80:83]
	v_mfma_f32_16x16x32_bf16 v[76:79], v[174:177], v[204:207], v[76:79]
	v_mfma_f32_16x16x32_bf16 v[72:75], v[166:169], v[216:219], v[72:75]
	v_mfma_f32_16x16x32_bf16 v[68:71], v[174:177], v[216:219], v[68:71]
	v_mfma_f32_16x16x32_bf16 v[112:115], v[170:173], v[186:189], v[112:115]
	v_mfma_f32_16x16x32_bf16 v[108:111], v[178:181], v[186:189], v[108:111]
	v_mfma_f32_16x16x32_bf16 v[104:107], v[170:173], v[194:197], v[104:107]
	v_mfma_f32_16x16x32_bf16 v[100:103], v[178:181], v[194:197], v[100:103]
	v_mfma_f32_16x16x32_bf16 v[80:83], v[170:173], v[212:215], v[80:83]
	v_mfma_f32_16x16x32_bf16 v[76:79], v[178:181], v[212:215], v[76:79]
	v_mfma_f32_16x16x32_bf16 v[72:75], v[170:173], v[220:223], v[72:75]
	v_mfma_f32_16x16x32_bf16 v[68:71], v[178:181], v[220:223], v[68:71]
	s_nop 0
	s_barrier
	s_add_i32 s34, s58, s6
	v_lshl_add_u64 v[148:149], v[148:149], 0, s[94:95]
	s_mov_b32 m0, s34
	ds_read_b128 v[182:185], v152 offset:49152
	ds_read_b128 v[186:189], v152 offset:50176
	ds_read_b128 v[190:193], v152 offset:51200
	ds_read_b128 v[194:197], v152 offset:52224
	ds_read_b128 v[204:207], v152 offset:53248
	ds_read_b128 v[212:215], v152 offset:54272
	ds_read_b128 v[216:219], v152 offset:55296
	ds_read_b128 v[220:223], v152 offset:56320
	global_load_lds_dwordx4 v[148:149], off
	s_add_i32 m0, s34, 0x2000
	s_add_u32 s30, s30, 0x80080
	v_lshl_add_u64 v[148:149], v[198:199], 0, s[94:95]
	s_addc_u32 s31, s31, 0
	s_add_i32 s34, s59, s6
	global_load_lds_dwordx4 v[148:149], off
	v_lshl_add_u64 v[148:149], s[30:31], 0, v[136:137]
	s_mov_b32 m0, s34
	s_nop 0
	global_load_lds_dwordx4 v[148:149], off
	v_lshl_add_u64 v[148:149], s[30:31], 0, v[132:133]
	s_add_i32 m0, s34, 0x2000
	s_nop 0
	global_load_lds_dwordx4 v[148:149], off
	v_lshl_add_u64 v[148:149], v[224:225], 0, s[94:95]
	s_mov_b32 m0, s49
	s_nop 0
	global_load_lds_dwordx4 v[148:149], off
	v_lshl_add_u64 v[148:149], v[226:227], 0, s[94:95]
	s_mov_b32 m0, s50
	s_nop 0
	global_load_lds_dwordx4 v[148:149], off
	s_waitcnt vmcnt(8)
	s_waitcnt lgkmcnt(0)
	s_barrier
	s_nop 0
	s_waitcnt lgkmcnt(0)
	v_mfma_f32_16x16x32_bf16 v[64:67], v[144:147], v[182:185], v[64:67]
	v_mfma_f32_16x16x32_bf16 v[60:63], v[158:161], v[182:185], v[60:63]
	v_mfma_f32_16x16x32_bf16 v[56:59], v[144:147], v[190:193], v[56:59]
	v_mfma_f32_16x16x32_bf16 v[52:55], v[158:161], v[190:193], v[52:55]
	v_mfma_f32_16x16x32_bf16 v[32:35], v[144:147], v[204:207], v[32:35]
	v_mfma_f32_16x16x32_bf16 v[28:31], v[158:161], v[204:207], v[28:31]
	v_mfma_f32_16x16x32_bf16 v[16:19], v[144:147], v[216:219], v[16:19]
	v_mfma_f32_16x16x32_bf16 v[12:15], v[158:161], v[216:219], v[12:15]
	v_mfma_f32_16x16x32_bf16 v[64:67], v[154:157], v[186:189], v[64:67]
	v_mfma_f32_16x16x32_bf16 v[60:63], v[162:165], v[186:189], v[60:63]
	v_mfma_f32_16x16x32_bf16 v[56:59], v[154:157], v[194:197], v[56:59]
	v_mfma_f32_16x16x32_bf16 v[52:55], v[162:165], v[194:197], v[52:55]
	v_mfma_f32_16x16x32_bf16 v[32:35], v[154:157], v[212:215], v[32:35]
	v_mfma_f32_16x16x32_bf16 v[28:31], v[162:165], v[212:215], v[28:31]
	v_mfma_f32_16x16x32_bf16 v[16:19], v[154:157], v[220:223], v[16:19]
	v_mfma_f32_16x16x32_bf16 v[12:15], v[162:165], v[220:223], v[12:15]
	s_nop 0
	s_nop 0
	v_mfma_f32_16x16x32_bf16 v[48:51], v[166:169], v[182:185], v[48:51]
	v_mfma_f32_16x16x32_bf16 v[44:47], v[174:177], v[182:185], v[44:47]
	v_mfma_f32_16x16x32_bf16 v[40:43], v[166:169], v[190:193], v[40:43]
	v_mfma_f32_16x16x32_bf16 v[36:39], v[174:177], v[190:193], v[36:39]
	v_mfma_f32_16x16x32_bf16 v[24:27], v[166:169], v[204:207], v[24:27]
	v_mfma_f32_16x16x32_bf16 v[20:23], v[174:177], v[204:207], v[20:23]
	v_mfma_f32_16x16x32_bf16 v[8:11], v[166:169], v[216:219], v[8:11]
	v_mfma_f32_16x16x32_bf16 v[4:7], v[174:177], v[216:219], v[4:7]
	v_mfma_f32_16x16x32_bf16 v[48:51], v[170:173], v[186:189], v[48:51]
	v_mfma_f32_16x16x32_bf16 v[44:47], v[178:181], v[186:189], v[44:47]
	v_mfma_f32_16x16x32_bf16 v[40:43], v[170:173], v[194:197], v[40:43]
	v_mfma_f32_16x16x32_bf16 v[36:39], v[178:181], v[194:197], v[36:39]
	v_mfma_f32_16x16x32_bf16 v[24:27], v[170:173], v[212:215], v[24:27]
	v_mfma_f32_16x16x32_bf16 v[20:23], v[178:181], v[212:215], v[20:23]
	v_mfma_f32_16x16x32_bf16 v[8:11], v[170:173], v[220:223], v[8:11]
	v_mfma_f32_16x16x32_bf16 v[4:7], v[178:181], v[220:223], v[4:7]
	s_nop 0
	s_barrier
	s_add_i32 s57, s57, 2
	s_add_u32 s28, s28, 0x100
	s_addc_u32 s29, s29, 0
	s_add_u32 s55, s55, 0x100
	s_addc_u32 s56, s56, 0
	s_cmp_gt_u32 s57, 29
	s_cbranch_scc0 .LBB0_1403
	s_and_b64 vcc, exec, s[8:9]
	s_cbranch_vccz .LBB0_1406
	s_barrier
